# speedup vs baseline: 1.0226x; 1.0039x over previous
; template <int EPI, int PN>
; __device__ void gemm_phase(const Params& p, const u16* __restrict__ A, const u16* __restrict__ Bt, int nNt, char* smem) {
;     ...
;     const int pl = q / (4 * PN), w = q % (4 * PN);
;     const int gp = pl * 8 + xcd;
;     if (gp >= npatch) break;
;     const int mt = (gp / npn) * 4 + (w & 3), nt = (gp % npn) * PN + (w >> 2);
;     const int gch = sch ^ ((srow >> 1) & 7);
;     const u16* Ag0 = A + (size_t)(mt * 256 + srow) * LDK + gch * 8;
;     const u16* Bg0 = Bt + (size_t)(nt * 256 + srow) * LDK + gch * 8;
;     f32x16 acc[4][2];
; #pragma unroll
;     for (int i = 0; i < 4; ++i)
; #pragma unroll
;       for (int j = 0; j < 2; ++j) acc[i][j] = zero16();
;     asm volatile("s_waitcnt vmcnt(0)" ::: "memory");
; #pragma unroll
;     for (int i = 0; i < 4; ++i) {
;       glds16(Ag0 + (size_t)i * 64 * LDK, ring + (srow + 64 * i) * 64 + sch * 8);
;       glds16(Bg0 + (size_t)i * 64 * LDK, ring + 16384 + (srow + 64 * i) * 64 + sch * 8);
;     }
;     for (int kt = 0; kt < 32; ++kt) {
;       asm volatile("s_waitcnt vmcnt(0)" ::: "memory");
;       __builtin_amdgcn_s_barrier();
;       const u16* Ab = ring + (kt & 1) * STG;
;       const u16* Bb = Ab + 16384;
;       u16* st = ring + ((kt + 1) & 1) * STG;
;       const bool pre = (kt + 1 < 32);
;       s16x8 af[2][4], bf[2][2];
;       auto ldfrag = [&](int ks, int slot) {
; #pragma unroll
;         for (int i = 0; i < 4; ++i) {
;           const int row = wr * 128 + i * 32 + lr;
;           af[slot][i] = *(const s16x8*)(Ab + row * 64 + (((ks * 2 + lh) ^ ((row >> 1) & 7)) * 8));
;         }
; #pragma unroll
;         for (int j = 0; j < 2; ++j) {
;           const int rowb = nh * 128 + wc * 64 + j * 32 + lr;
;           bf[slot][j] = *(const s16x8*)(Bb + rowb * 64 + (((ks * 2 + lh) ^ ((rowb >> 1) & 7)) * 8));
;         }
;       };
;       ldfrag(0, 0);
;       ldfrag(1, 1);
.LBB0_128:
	s_mul_hi_i32 s10, s19, 0xb21642c9
	s_add_i32 s10, s10, s19
	s_lshr_b32 s11, s10, 31
	s_ashr_i32 s10, s10, 6
	s_add_i32 s10, s10, s11
	s_mulk_i32 s10, 0x5c
	s_sub_i32 s11, s19, s10
	s_lshl_b32 s10, s12, 2
	s_and_b32 s13, s11, 3
	s_or_b32 s10, s13, s10
	s_ashr_i32 s11, s11, 2
	v_lshl_add_u32 v0, s10, 8, v141
	v_lshl_add_u32 v6, s11, 8, v141
	v_mad_i64_i32 v[0:1], s[20:21], v0, s0, v[130:131]
	v_mad_i64_i32 v[2:3], s[20:21], v6, s0, v[132:133]
	s_waitcnt vmcnt(0)
	v_readfirstlane_b32 s20, v136
	s_mov_b32 s21, m0
	s_mov_b32 m0, s20
	s_nop 0
	global_load_lds_dwordx4 v[0:1], off
	s_mov_b32 m0, s21
	v_readfirstlane_b32 s20, v138
	s_mov_b32 s21, m0
	s_mov_b32 m0, s20
	s_nop 0
	global_load_lds_dwordx4 v[2:3], off
	s_mov_b32 m0, s21
	v_lshl_add_u64 v[4:5], v[0:1], 0, s[2:3]
	v_readfirstlane_b32 s20, v140
	s_mov_b32 s21, m0
	s_mov_b32 m0, s20
	s_nop 0
	global_load_lds_dwordx4 v[4:5], off
	s_mov_b32 m0, s21
	v_lshl_add_u64 v[4:5], v[2:3], 0, s[2:3]
	v_readfirstlane_b32 s20, v142
	s_mov_b32 s21, m0
	s_mov_b32 m0, s20
	s_nop 0
	global_load_lds_dwordx4 v[4:5], off
	s_mov_b32 m0, s21
	v_lshl_add_u64 v[4:5], v[0:1], 0, s[4:5]
	v_readfirstlane_b32 s20, v144
	s_mov_b32 s21, m0
	s_mov_b32 m0, s20
	s_nop 0
	global_load_lds_dwordx4 v[4:5], off
	s_mov_b32 m0, s21
	v_lshl_add_u64 v[4:5], v[2:3], 0, s[4:5]
	v_readfirstlane_b32 s20, v146
	s_mov_b32 s21, m0
	s_mov_b32 m0, s20
	s_nop 0
	global_load_lds_dwordx4 v[4:5], off
	s_mov_b32 m0, s21
	v_lshl_add_u64 v[0:1], v[0:1], 0, s[6:7]
	s_lshl_b32 s12, s12, 10
	s_lshl_b32 s13, s13, 8
	v_readfirstlane_b32 s20, v148
	s_mov_b32 s21, m0
	s_mov_b32 m0, s20
	s_nop 0
	global_load_lds_dwordx4 v[0:1], off
	s_mov_b32 m0, s21
	v_lshl_add_u64 v[0:1], v[2:3], 0, s[6:7]
	s_or_b32 s12, s13, s12
	v_readfirstlane_b32 s20, v150
	s_mov_b32 s21, m0
	s_mov_b32 m0, s20
	s_nop 0
	global_load_lds_dwordx4 v[0:1], off
	s_mov_b32 m0, s21
	v_add_u32_e32 v0, s12, v141
	v_mad_i64_i32 v[158:159], s[12:13], v0, s0, v[152:153]
	v_mad_i64_i32 v[160:161], s[12:13], v6, s0, v[154:155]
	s_mov_b32 s12, 0x8000
	v_mov_b32_e32 v48, 0
	v_mov_b32_e32 v49, v129
	v_mov_b32_e32 v50, v129
	v_mov_b32_e32 v51, v129
	v_mov_b32_e32 v52, v129
	v_mov_b32_e32 v53, v129
	v_mov_b32_e32 v54, v129
	v_mov_b32_e32 v55, v129
	v_mov_b32_e32 v56, v129
	v_mov_b32_e32 v57, v129
	v_mov_b32_e32 v58, v129
	v_mov_b32_e32 v59, v129
	v_mov_b32_e32 v60, v129
	v_mov_b32_e32 v61, v129
	v_mov_b32_e32 v62, v129
	v_mov_b32_e32 v63, v129
	v_mov_b32_e32 v0, 0
	v_mov_b32_e32 v1, v129
	v_mov_b32_e32 v2, v129
	v_mov_b32_e32 v3, v129
	v_mov_b32_e32 v4, v129
	v_mov_b32_e32 v5, v129
	v_mov_b32_e32 v6, v129
	v_mov_b32_e32 v7, v129
	v_mov_b32_e32 v8, v129
	v_mov_b32_e32 v9, v129
	v_mov_b32_e32 v10, v129
	v_mov_b32_e32 v11, v129
	v_mov_b32_e32 v12, v129
	v_mov_b32_e32 v13, v129
	v_mov_b32_e32 v14, v129
	v_mov_b32_e32 v15, v129
	v_mov_b32_e32 v80, 0
	v_mov_b32_e32 v81, v129
	v_mov_b32_e32 v82, v129
	v_mov_b32_e32 v83, v129
	v_mov_b32_e32 v84, v129
	v_mov_b32_e32 v85, v129
	v_mov_b32_e32 v86, v129
	v_mov_b32_e32 v87, v129
	v_mov_b32_e32 v88, v129
	v_mov_b32_e32 v89, v129
	v_mov_b32_e32 v90, v129
	v_mov_b32_e32 v91, v129
	v_mov_b32_e32 v92, v129
	v_mov_b32_e32 v93, v129
	v_mov_b32_e32 v94, v129
	v_mov_b32_e32 v95, v129
	v_mov_b32_e32 v16, 0
	v_mov_b32_e32 v17, v129
	v_mov_b32_e32 v18, v129
	v_mov_b32_e32 v19, v129
	v_mov_b32_e32 v20, v129
	v_mov_b32_e32 v21, v129
	v_mov_b32_e32 v22, v129
	v_mov_b32_e32 v23, v129
	v_mov_b32_e32 v24, v129
	v_mov_b32_e32 v25, v129
	v_mov_b32_e32 v26, v129
	v_mov_b32_e32 v27, v129
	v_mov_b32_e32 v28, v129
	v_mov_b32_e32 v29, v129
	v_mov_b32_e32 v30, v129
	v_mov_b32_e32 v31, v129
	v_mov_b32_e32 v96, 0
	v_mov_b32_e32 v97, v129
	v_mov_b32_e32 v98, v129
	v_mov_b32_e32 v99, v129
	v_mov_b32_e32 v100, v129
	v_mov_b32_e32 v101, v129
	v_mov_b32_e32 v102, v129
	v_mov_b32_e32 v103, v129
	v_mov_b32_e32 v104, v129
	v_mov_b32_e32 v105, v129
	v_mov_b32_e32 v106, v129
	v_mov_b32_e32 v107, v129
	v_mov_b32_e32 v108, v129
	v_mov_b32_e32 v109, v129
	v_mov_b32_e32 v110, v129
	v_mov_b32_e32 v111, v129
	v_mov_b32_e32 v32, 0
	v_mov_b32_e32 v33, v129
	v_mov_b32_e32 v34, v129
	v_mov_b32_e32 v35, v129
	v_mov_b32_e32 v36, v129
	v_mov_b32_e32 v37, v129
	v_mov_b32_e32 v38, v129
	v_mov_b32_e32 v39, v129
	v_mov_b32_e32 v40, v129
	v_mov_b32_e32 v41, v129
	v_mov_b32_e32 v42, v129
	v_mov_b32_e32 v43, v129
	v_mov_b32_e32 v44, v129
	v_mov_b32_e32 v45, v129
	v_mov_b32_e32 v46, v129
	v_mov_b32_e32 v47, v129
	v_mov_b32_e32 v112, 0
	v_mov_b32_e32 v113, v129
	v_mov_b32_e32 v114, v129
	v_mov_b32_e32 v115, v129
	v_mov_b32_e32 v116, v129
	v_mov_b32_e32 v117, v129
	v_mov_b32_e32 v118, v129
	v_mov_b32_e32 v119, v129
	v_mov_b32_e32 v120, v129
	v_mov_b32_e32 v121, v129
	v_mov_b32_e32 v122, v129
	v_mov_b32_e32 v123, v129
	v_mov_b32_e32 v124, v129
	v_mov_b32_e32 v125, v129
	v_mov_b32_e32 v126, v129
	v_mov_b32_e32 v127, v129
	v_mov_b32_e32 v64, 0
	v_mov_b32_e32 v65, v129
	v_mov_b32_e32 v66, v129
	v_mov_b32_e32 v67, v129
	v_mov_b32_e32 v68, v129
	v_mov_b32_e32 v69, v129
	v_mov_b32_e32 v70, v129
	v_mov_b32_e32 v71, v129
	v_mov_b32_e32 v72, v129
	v_mov_b32_e32 v73, v129
	v_mov_b32_e32 v74, v129
	v_mov_b32_e32 v75, v129
	v_mov_b32_e32 v76, v129
	v_mov_b32_e32 v77, v129
	v_mov_b32_e32 v78, v129
	v_mov_b32_e32 v79, v129
	v_readfirstlane_b32 s99, v136
	s_add_i32 s99, s99, 0x10000
	s_mov_b32 s20, m0
	s_mov_b32 m0, s99
	s_nop 0
	global_load_lds_dwordx4 v[158:159], off
	v_lshl_add_u64 v[232:233], v[158:159], 0, s[2:3]
	s_add_i32 m0, s99, 0x2000
	s_nop 0
	global_load_lds_dwordx4 v[232:233], off
	v_lshl_add_u64 v[234:235], v[158:159], 0, s[4:5]
	s_add_i32 m0, s99, 0x4000
	s_nop 0
	global_load_lds_dwordx4 v[234:235], off
	v_lshl_add_u64 v[232:233], v[158:159], 0, s[6:7]
	s_add_i32 m0, s99, 0x6000
	s_nop 0
	global_load_lds_dwordx4 v[232:233], off
	s_mov_b32 m0, s20
	v_lshl_add_u64 v[158:159], v[158:159], 0, s[8:9]
	s_waitcnt vmcnt(0)
	s_barrier
	v_lshlrev_b32_e32 v227, 1, v143
	v_lshlrev_b32_e32 v229, 1, v147
	v_add_u32_e32 v228, v227, v173
	v_add_u32_e32 v230, v229, v173
	ds_read_b128 v[178:181], v228
	ds_read_b128 v[182:185], v228 offset:4096
	ds_read_b128 v[186:189], v228 offset:8192
	ds_read_b128 v[190:193], v228 offset:12288
	ds_read_b128 v[194:197], v230 offset:32768
	ds_read_b128 v[198:201], v230 offset:36864
	v_add_u32_e32 v228, v227, v174
	v_add_u32_e32 v230, v229, v174
	ds_read_b128 v[202:205], v228
	ds_read_b128 v[206:209], v228 offset:4096
	ds_read_b128 v[210:213], v228 offset:8192
	ds_read_b128 v[214:217], v228 offset:12288
	ds_read_b128 v[218:221], v230 offset:32768
	ds_read_b128 v[222:225], v230 offset:36864
; template <int EPI, int PN>
; __device__ void gemm_phase(const Params& p, const u16* __restrict__ A, const u16* __restrict__ Bt, int nNt, char* smem) {
;     ...
;     for (int kt = 0; kt < 32; ++kt) {
;       asm volatile("s_waitcnt vmcnt(0)" ::: "memory");
;       __builtin_amdgcn_s_barrier();
;       const u16* Ab = ring + (kt & 1) * STG;
;       const u16* Bb = Ab + 16384;
;       u16* st = ring + ((kt + 1) & 1) * STG;
;       const bool pre = (kt + 1 < 32);
;       s16x8 af[2][4], bf[2][2];
;       auto ldfrag = [&](int ks, int slot) {
; #pragma unroll
;         for (int i = 0; i < 4; ++i) {
;           const int row = wr * 128 + i * 32 + lr;
;           af[slot][i] = *(const s16x8*)(Ab + row * 64 + (((ks * 2 + lh) ^ ((row >> 1) & 7)) * 8));
;         }
; #pragma unroll
;         for (int j = 0; j < 2; ++j) {
;           const int rowb = nh * 128 + wc * 64 + j * 32 + lr;
;           bf[slot][j] = *(const s16x8*)(Bb + rowb * 64 + (((ks * 2 + lh) ^ ((rowb >> 1) & 7)) * 8));
;         }
;       };
;       ldfrag(0, 0);
;       ldfrag(1, 1);
;       __builtin_amdgcn_sched_barrier(0);
; #pragma unroll
;       for (int ks = 0; ks < 4; ++ks) {
;         const int slot = ks & 1;
; #pragma unroll
;         for (int i = 0; i < 4; ++i) {
;           acc[i][0] = mfma32(af[slot][i], bf[slot][0], acc[i][0]);
;           acc[i][1] = mfma32(af[slot][i], bf[slot][1], acc[i][1]);
;           __builtin_amdgcn_sched_barrier(0);
;           if (pre && (i & 1) == 0) {
;             const int pi = ks * 2 + (i >> 1);
;             if (pi < 4) glds16(Ag0 + (size_t)pi * 64 * LDK + (kt + 1) * 64, st + (srow + 64 * pi) * 64 + sch * 8);
;             else glds16(Bg0 + (size_t)(pi - 4) * 64 * LDK + (kt + 1) * 64, st + 16384 + (srow + 64 * (pi - 4)) * 64 + sch * 8);
;             __builtin_amdgcn_sched_barrier(0);
;           }
;         }
;         if (ks + 2 < 4) { ldfrag(ks + 2, slot); __builtin_amdgcn_sched_barrier(0); }
;       }
.Lrot129_loop:
	s_add_i32 s13, s12, 0xffff8000
	s_and_b32 s13, s13, 0x8000
	s_lshl_b32 s13, s13, 1
	v_lshl_or_b32 v128, v143, 1, s13
	v_lshl_add_u32 v149, v147, 1, s13
	s_and_b32 s98, s12, 0x8000
	s_lshl_b32 s98, s98, 1
	s_waitcnt lgkmcnt(7)
	v_mfma_f32_32x32x16_bf16 v[64:79], v[178:181], v[194:197], v[64:79]
	v_add3_u32 v226, s98, v162, v156
	s_waitcnt lgkmcnt(6)
	v_mfma_f32_32x32x16_bf16 v[112:127], v[178:181], v[198:201], v[112:127]
	v_readfirstlane_b32 s100, v226
	s_mov_b32 s20, m0
	s_add_i32 m0, s100, 0x8000
	s_nop 0
	global_load_lds_dwordx4 v[160:161], off
	v_mfma_f32_32x32x16_bf16 v[32:47], v[182:185], v[194:197], v[32:47]
	v_mfma_f32_32x32x16_bf16 v[96:111], v[182:185], v[198:201], v[96:111]
	v_lshl_add_u64 v[178:179], v[160:161], 0, s[2:3]
	s_add_i32 m0, s100, 0xa000
	s_nop 0
	global_load_lds_dwordx4 v[178:179], off
	v_mfma_f32_32x32x16_bf16 v[16:31], v[186:189], v[194:197], v[16:31]
	v_mfma_f32_32x32x16_bf16 v[80:95], v[186:189], v[198:201], v[80:95]
	v_lshl_add_u64 v[180:181], v[160:161], 0, s[4:5]
	s_add_i32 m0, s100, 0xc000
	s_nop 0
	global_load_lds_dwordx4 v[180:181], off
	v_mfma_f32_32x32x16_bf16 v[0:15], v[190:193], v[194:197], v[0:15]
	v_mfma_f32_32x32x16_bf16 v[48:63], v[190:193], v[198:201], v[48:63]
	v_lshl_add_u64 v[178:179], v[160:161], 0, s[6:7]
	s_add_i32 m0, s100, 0xe000
	s_nop 0
	global_load_lds_dwordx4 v[178:179], off
	s_mov_b32 m0, s20
	v_lshl_add_u64 v[160:161], v[160:161], 0, s[8:9]
	v_add_u32_e32 v177, v128, v175
	ds_read_b128 v[178:181], v177
	ds_read_b128 v[182:185], v177 offset:4096
	ds_read_b128 v[186:189], v177 offset:8192
	ds_read_b128 v[190:193], v177 offset:12288
	v_add_u32_e32 v177, v149, v175
	ds_read_b128 v[194:197], v177 offset:32768
	ds_read_b128 v[198:201], v177 offset:36864
	s_waitcnt lgkmcnt(7)
	v_mfma_f32_32x32x16_bf16 v[64:79], v[202:205], v[218:221], v[64:79]
	s_waitcnt lgkmcnt(6)
	v_mfma_f32_32x32x16_bf16 v[112:127], v[202:205], v[222:225], v[112:127]
	v_mfma_f32_32x32x16_bf16 v[32:47], v[206:209], v[218:221], v[32:47]
	v_mfma_f32_32x32x16_bf16 v[96:111], v[206:209], v[222:225], v[96:111]
	v_mfma_f32_32x32x16_bf16 v[16:31], v[210:213], v[218:221], v[16:31]
	v_mfma_f32_32x32x16_bf16 v[80:95], v[210:213], v[222:225], v[80:95]
	v_mfma_f32_32x32x16_bf16 v[0:15], v[214:217], v[218:221], v[0:15]
	v_mfma_f32_32x32x16_bf16 v[48:63], v[214:217], v[222:225], v[48:63]
	v_add_u32_e32 v128, v128, v176
	ds_read_b128 v[202:205], v128
	ds_read_b128 v[206:209], v128 offset:4096
	ds_read_b128 v[210:213], v128 offset:8192
	ds_read_b128 v[214:217], v128 offset:12288
	v_add_u32_e32 v128, v149, v176
	ds_read_b128 v[218:221], v128 offset:32768
	ds_read_b128 v[222:225], v128 offset:36864
	s_waitcnt lgkmcnt(7)
	v_mfma_f32_32x32x16_bf16 v[64:79], v[178:181], v[194:197], v[64:79]
	s_waitcnt lgkmcnt(6)
	v_mfma_f32_32x32x16_bf16 v[112:127], v[178:181], v[198:201], v[112:127]
	v_mfma_f32_32x32x16_bf16 v[32:47], v[182:185], v[194:197], v[32:47]
	v_mfma_f32_32x32x16_bf16 v[96:111], v[182:185], v[198:201], v[96:111]
	v_mfma_f32_32x32x16_bf16 v[16:31], v[186:189], v[194:197], v[16:31]
	v_mfma_f32_32x32x16_bf16 v[80:95], v[186:189], v[198:201], v[80:95]
	v_mfma_f32_32x32x16_bf16 v[0:15], v[190:193], v[194:197], v[0:15]
	v_mfma_f32_32x32x16_bf16 v[48:63], v[190:193], v[198:201], v[48:63]
	s_waitcnt vmcnt(0) lgkmcnt(0)
	s_barrier
	v_lshl_or_b32 v227, v143, 1, s98
	v_lshl_add_u32 v229, v147, 1, s98
	v_add_u32_e32 v228, v227, v173
	v_add_u32_e32 v230, v229, v173
	ds_read_b128 v[178:181], v228
	ds_read_b128 v[182:185], v228 offset:4096
	ds_read_b128 v[186:189], v228 offset:8192
	ds_read_b128 v[190:193], v228 offset:12288
	ds_read_b128 v[194:197], v230 offset:32768
	ds_read_b128 v[198:201], v230 offset:36864
	v_add3_u32 v226, s13, v162, v156
	v_mfma_f32_32x32x16_bf16 v[64:79], v[202:205], v[218:221], v[64:79]
	v_readfirstlane_b32 s99, v226
	s_mov_b32 s20, m0
	s_mov_b32 m0, s99
	s_nop 0
	global_load_lds_dwordx4 v[158:159], off
	v_mfma_f32_32x32x16_bf16 v[112:127], v[202:205], v[222:225], v[112:127]
	v_mfma_f32_32x32x16_bf16 v[32:47], v[206:209], v[218:221], v[32:47]
	v_lshl_add_u64 v[232:233], v[158:159], 0, s[2:3]
	s_add_i32 m0, s99, 0x2000
	s_nop 0
	global_load_lds_dwordx4 v[232:233], off
	v_mfma_f32_32x32x16_bf16 v[96:111], v[206:209], v[222:225], v[96:111]
	v_mfma_f32_32x32x16_bf16 v[16:31], v[210:213], v[218:221], v[16:31]
	v_lshl_add_u64 v[234:235], v[158:159], 0, s[4:5]
	s_add_i32 m0, s99, 0x4000
	s_nop 0
	global_load_lds_dwordx4 v[234:235], off
	v_mfma_f32_32x32x16_bf16 v[80:95], v[210:213], v[222:225], v[80:95]
	v_mfma_f32_32x32x16_bf16 v[0:15], v[214:217], v[218:221], v[0:15]
	v_lshl_add_u64 v[232:233], v[158:159], 0, s[6:7]
	s_add_i32 m0, s99, 0x6000
	s_nop 0
	global_load_lds_dwordx4 v[232:233], off
	s_mov_b32 m0, s20
	v_mfma_f32_32x32x16_bf16 v[48:63], v[214:217], v[222:225], v[48:63]
	v_add_u32_e32 v228, v227, v174
	v_add_u32_e32 v230, v229, v174
	ds_read_b128 v[202:205], v228
	ds_read_b128 v[206:209], v228 offset:4096
	ds_read_b128 v[210:213], v228 offset:8192
	ds_read_b128 v[214:217], v228 offset:12288
	ds_read_b128 v[218:221], v230 offset:32768
	ds_read_b128 v[222:225], v230 offset:36864
	s_add_i32 s12, s12, 0x8000
	v_lshl_add_u64 v[158:159], v[158:159], 0, s[8:9]
	s_cmp_eq_u32 s12, 0xf8000
	s_cbranch_scc0 .Lrot129_loop
; template <int EPI, int PN>
; __device__ void gemm_phase(const Params& p, const u16* __restrict__ A, const u16* __restrict__ Bt, int nNt, char* smem) {
;     ...
;     for (int kt = 0; kt < 32; ++kt) {
;       asm volatile("s_waitcnt vmcnt(0)" ::: "memory");
;       __builtin_amdgcn_s_barrier();
;       const u16* Ab = ring + (kt & 1) * STG;
;       const u16* Bb = Ab + 16384;
;       u16* st = ring + ((kt + 1) & 1) * STG;
;       const bool pre = (kt + 1 < 32);
;       s16x8 af[2][4], bf[2][2];
;       auto ldfrag = [&](int ks, int slot) {
; #pragma unroll
;         for (int i = 0; i < 4; ++i) {
;           const int row = wr * 128 + i * 32 + lr;
;           af[slot][i] = *(const s16x8*)(Ab + row * 64 + (((ks * 2 + lh) ^ ((row >> 1) & 7)) * 8));
;         }
; #pragma unroll
;         for (int j = 0; j < 2; ++j) {
;           const int rowb = nh * 128 + wc * 64 + j * 32 + lr;
;           bf[slot][j] = *(const s16x8*)(Bb + rowb * 64 + (((ks * 2 + lh) ^ ((rowb >> 1) & 7)) * 8));
;         }
;       };
;       ldfrag(0, 0);
;       ldfrag(1, 1);
;       __builtin_amdgcn_sched_barrier(0);
; #pragma unroll
;       for (int ks = 0; ks < 4; ++ks) {
;         const int slot = ks & 1;
; #pragma unroll
;         for (int i = 0; i < 4; ++i) {
;           acc[i][0] = mfma32(af[slot][i], bf[slot][0], acc[i][0]);
;           acc[i][1] = mfma32(af[slot][i], bf[slot][1], acc[i][1]);
;           __builtin_amdgcn_sched_barrier(0);
;           if (pre && (i & 1) == 0) {
;             const int pi = ks * 2 + (i >> 1);
;             if (pi < 4) glds16(Ag0 + (size_t)pi * 64 * LDK + (kt + 1) * 64, st + (srow + 64 * pi) * 64 + sch * 8);
;             else glds16(Bg0 + (size_t)(pi - 4) * 64 * LDK + (kt + 1) * 64, st + 16384 + (srow + 64 * (pi - 4)) * 64 + sch * 8);
;             __builtin_amdgcn_sched_barrier(0);
;           }
;         }
;         if (ks + 2 < 4) { ldfrag(ks + 2, slot); __builtin_amdgcn_sched_barrier(0); }
;       }
	s_add_i32 s13, s12, 0xffff8000
	s_and_b32 s13, s13, 0x8000
	s_lshl_b32 s13, s13, 1
	v_lshl_or_b32 v128, v143, 1, s13
	v_lshl_add_u32 v149, v147, 1, s13
	s_and_b32 s98, s12, 0x8000
	s_lshl_b32 s98, s98, 1
	s_waitcnt lgkmcnt(7)
	v_mfma_f32_32x32x16_bf16 v[64:79], v[178:181], v[194:197], v[64:79]
	v_add3_u32 v226, s98, v162, v156
	s_waitcnt lgkmcnt(6)
	v_mfma_f32_32x32x16_bf16 v[112:127], v[178:181], v[198:201], v[112:127]
	v_readfirstlane_b32 s100, v226
	s_mov_b32 s20, m0
	s_add_i32 m0, s100, 0x8000
	s_nop 0
	global_load_lds_dwordx4 v[160:161], off
	v_mfma_f32_32x32x16_bf16 v[32:47], v[182:185], v[194:197], v[32:47]
	v_mfma_f32_32x32x16_bf16 v[96:111], v[182:185], v[198:201], v[96:111]
	v_lshl_add_u64 v[178:179], v[160:161], 0, s[2:3]
	s_add_i32 m0, s100, 0xa000
	s_nop 0
	global_load_lds_dwordx4 v[178:179], off
	v_mfma_f32_32x32x16_bf16 v[16:31], v[186:189], v[194:197], v[16:31]
	v_mfma_f32_32x32x16_bf16 v[80:95], v[186:189], v[198:201], v[80:95]
	v_lshl_add_u64 v[180:181], v[160:161], 0, s[4:5]
	s_add_i32 m0, s100, 0xc000
	s_nop 0
	global_load_lds_dwordx4 v[180:181], off
	v_mfma_f32_32x32x16_bf16 v[0:15], v[190:193], v[194:197], v[0:15]
	v_mfma_f32_32x32x16_bf16 v[48:63], v[190:193], v[198:201], v[48:63]
	v_lshl_add_u64 v[178:179], v[160:161], 0, s[6:7]
	s_add_i32 m0, s100, 0xe000
	s_nop 0
	global_load_lds_dwordx4 v[178:179], off
	s_mov_b32 m0, s20
	v_lshl_add_u64 v[160:161], v[160:161], 0, s[8:9]
	v_add_u32_e32 v177, v128, v175
	ds_read_b128 v[178:181], v177
	ds_read_b128 v[182:185], v177 offset:4096
	ds_read_b128 v[186:189], v177 offset:8192
	ds_read_b128 v[190:193], v177 offset:12288
	v_add_u32_e32 v177, v149, v175
	ds_read_b128 v[194:197], v177 offset:32768
	ds_read_b128 v[198:201], v177 offset:36864
	s_waitcnt lgkmcnt(7)
	v_mfma_f32_32x32x16_bf16 v[64:79], v[202:205], v[218:221], v[64:79]
	s_waitcnt lgkmcnt(6)
	v_mfma_f32_32x32x16_bf16 v[112:127], v[202:205], v[222:225], v[112:127]
	v_mfma_f32_32x32x16_bf16 v[32:47], v[206:209], v[218:221], v[32:47]
	v_mfma_f32_32x32x16_bf16 v[96:111], v[206:209], v[222:225], v[96:111]
	v_mfma_f32_32x32x16_bf16 v[16:31], v[210:213], v[218:221], v[16:31]
	v_mfma_f32_32x32x16_bf16 v[80:95], v[210:213], v[222:225], v[80:95]
	v_mfma_f32_32x32x16_bf16 v[0:15], v[214:217], v[218:221], v[0:15]
	v_mfma_f32_32x32x16_bf16 v[48:63], v[214:217], v[222:225], v[48:63]
	v_add_u32_e32 v128, v128, v176
	ds_read_b128 v[202:205], v128
	ds_read_b128 v[206:209], v128 offset:4096
	ds_read_b128 v[210:213], v128 offset:8192
	ds_read_b128 v[214:217], v128 offset:12288
	v_add_u32_e32 v128, v149, v176
	ds_read_b128 v[218:221], v128 offset:32768
	ds_read_b128 v[222:225], v128 offset:36864
	s_waitcnt lgkmcnt(7)
	v_mfma_f32_32x32x16_bf16 v[64:79], v[178:181], v[194:197], v[64:79]
	s_waitcnt lgkmcnt(6)
	v_mfma_f32_32x32x16_bf16 v[112:127], v[178:181], v[198:201], v[112:127]
	v_mfma_f32_32x32x16_bf16 v[32:47], v[182:185], v[194:197], v[32:47]
	v_mfma_f32_32x32x16_bf16 v[96:111], v[182:185], v[198:201], v[96:111]
	v_mfma_f32_32x32x16_bf16 v[16:31], v[186:189], v[194:197], v[16:31]
	v_mfma_f32_32x32x16_bf16 v[80:95], v[186:189], v[198:201], v[80:95]
	v_mfma_f32_32x32x16_bf16 v[0:15], v[190:193], v[194:197], v[0:15]
	v_mfma_f32_32x32x16_bf16 v[48:63], v[190:193], v[198:201], v[48:63]
	s_waitcnt lgkmcnt(1)
	v_mfma_f32_32x32x16_bf16 v[64:79], v[202:205], v[218:221], v[64:79]
	s_waitcnt lgkmcnt(0)
	v_mfma_f32_32x32x16_bf16 v[112:127], v[202:205], v[222:225], v[112:127]
	v_mfma_f32_32x32x16_bf16 v[32:47], v[206:209], v[218:221], v[32:47]
	v_mfma_f32_32x32x16_bf16 v[96:111], v[206:209], v[222:225], v[96:111]
	v_mfma_f32_32x32x16_bf16 v[16:31], v[210:213], v[218:221], v[16:31]
	v_mfma_f32_32x32x16_bf16 v[80:95], v[210:213], v[222:225], v[80:95]
	v_mfma_f32_32x32x16_bf16 v[0:15], v[214:217], v[218:221], v[0:15]
	v_mfma_f32_32x32x16_bf16 v[48:63], v[214:217], v[222:225], v[48:63]
	s_waitcnt vmcnt(0)
	s_barrier
	ds_read_b128 v[158:161], v164
	ds_read_b128 v[178:181], v164 offset:4096
	ds_read_b128 v[182:185], v164 offset:8192
	ds_read_b128 v[186:189], v164 offset:12288
	ds_read_b128 v[190:193], v165
	ds_read_b128 v[194:197], v165 offset:4096
	ds_read_b128 v[198:201], v166
	ds_read_b128 v[202:205], v166 offset:4096
	ds_read_b128 v[206:209], v166 offset:8192
	ds_read_b128 v[210:213], v166 offset:12288
	ds_read_b128 v[214:217], v168
	ds_read_b128 v[218:221], v168 offset:4096
	s_waitcnt lgkmcnt(7)
	v_mfma_f32_32x32x16_bf16 v[64:79], v[158:161], v[190:193], v[64:79]
	s_waitcnt lgkmcnt(6)
	v_mfma_f32_32x32x16_bf16 v[112:127], v[158:161], v[194:197], v[112:127]
	v_mfma_f32_32x32x16_bf16 v[32:47], v[178:181], v[190:193], v[32:47]
	v_mfma_f32_32x32x16_bf16 v[96:111], v[178:181], v[194:197], v[96:111]
	v_mfma_f32_32x32x16_bf16 v[16:31], v[182:185], v[190:193], v[16:31]
	v_mfma_f32_32x32x16_bf16 v[80:95], v[182:185], v[194:197], v[80:95]
	v_mfma_f32_32x32x16_bf16 v[0:15], v[186:189], v[190:193], v[0:15]
	v_mfma_f32_32x32x16_bf16 v[48:63], v[186:189], v[194:197], v[48:63]
	ds_read_b128 v[158:161], v169
	ds_read_b128 v[178:181], v169 offset:4096
	ds_read_b128 v[182:185], v169 offset:8192
	ds_read_b128 v[186:189], v169 offset:12288
	ds_read_b128 v[190:193], v170
	ds_read_b128 v[194:197], v170 offset:4096
	s_waitcnt lgkmcnt(7)
	v_mfma_f32_32x32x16_bf16 v[64:79], v[198:201], v[214:217], v[64:79]
	s_waitcnt lgkmcnt(6)
; __device__ __forceinline__ int accrow(int reg, int lh) { return (reg & 3) + 8 * (reg >> 2) + 4 * lh; }
; template <int EPI, int PN>
; __device__ void gemm_phase(const Params& p, const u16* __restrict__ A, const u16* __restrict__ Bt, int nNt, char* smem) {
;     ...
;         for (int i = 0; i < 4; ++i) {
;           acc[i][0] = mfma32(af[slot][i], bf[slot][0], acc[i][0]);
;           acc[i][1] = mfma32(af[slot][i], bf[slot][1], acc[i][1]);
;     ...
;     } else if (EPI == 0 && col0 >= NPROJ) {
; #pragma unroll
;       for (int i = 0; i < 4; ++i)
; #pragma unroll
;         for (int r = 0; r < 16; ++r) {
;           const size_t row = row0 + i * 32 + accrow(r, lhE);
;           const int col = col0 + lrE;
;           if (col < NIN) p.dtraw[row * 16 + (col - NPROJ)] = acc[i][0][r];
;         }
;     } else {
; #pragma unroll
;       for (int i = 0; i < 4; ++i)
; #pragma unroll
;         for (int j = 0; j < 2; ++j)
; #pragma unroll
;           for (int r = 0; r < 16; ++r) *(u16*)(et + (i * 32 + accrow(r, lhE)) * 144 + (j * 32 + lrE) * 2) = f2bf(acc[i][j][r]);
	v_mfma_f32_32x32x16_bf16 v[112:127], v[198:201], v[218:221], v[112:127]
	v_mfma_f32_32x32x16_bf16 v[32:47], v[202:205], v[214:217], v[32:47]
	v_mfma_f32_32x32x16_bf16 v[96:111], v[202:205], v[218:221], v[96:111]
	v_mfma_f32_32x32x16_bf16 v[16:31], v[206:209], v[214:217], v[16:31]
	v_mfma_f32_32x32x16_bf16 v[80:95], v[206:209], v[218:221], v[80:95]
	v_mfma_f32_32x32x16_bf16 v[0:15], v[210:213], v[214:217], v[0:15]
	v_mfma_f32_32x32x16_bf16 v[48:63], v[210:213], v[218:221], v[48:63]
	ds_read_b128 v[198:201], v171
	ds_read_b128 v[202:205], v171 offset:4096
	ds_read_b128 v[206:209], v171 offset:8192
	ds_read_b128 v[210:213], v171 offset:12288
	ds_read_b128 v[214:217], v172
	ds_read_b128 v[218:221], v172 offset:4096
	s_waitcnt lgkmcnt(7)
	v_mfma_f32_32x32x16_bf16 v[64:79], v[158:161], v[190:193], v[64:79]
	s_waitcnt lgkmcnt(6)
	v_mfma_f32_32x32x16_bf16 v[112:127], v[158:161], v[194:197], v[112:127]
	v_mfma_f32_32x32x16_bf16 v[32:47], v[178:181], v[190:193], v[32:47]
	v_mfma_f32_32x32x16_bf16 v[96:111], v[178:181], v[194:197], v[96:111]
	v_mfma_f32_32x32x16_bf16 v[16:31], v[182:185], v[190:193], v[16:31]
	v_mfma_f32_32x32x16_bf16 v[80:95], v[182:185], v[194:197], v[80:95]
	v_mfma_f32_32x32x16_bf16 v[0:15], v[186:189], v[190:193], v[0:15]
	v_mfma_f32_32x32x16_bf16 v[48:63], v[186:189], v[194:197], v[48:63]
	s_waitcnt lgkmcnt(1)
	v_mfma_f32_32x32x16_bf16 v[64:79], v[198:201], v[214:217], v[64:79]
	s_waitcnt lgkmcnt(0)
	v_mfma_f32_32x32x16_bf16 v[112:127], v[198:201], v[218:221], v[112:127]
	v_mfma_f32_32x32x16_bf16 v[32:47], v[202:205], v[214:217], v[32:47]
	v_mfma_f32_32x32x16_bf16 v[96:111], v[202:205], v[218:221], v[96:111]
	v_mfma_f32_32x32x16_bf16 v[16:31], v[206:209], v[214:217], v[16:31]
	v_mfma_f32_32x32x16_bf16 v[80:95], v[206:209], v[218:221], v[80:95]
	v_mfma_f32_32x32x16_bf16 v[0:15], v[210:213], v[214:217], v[0:15]
	v_mfma_f32_32x32x16_bf16 v[48:63], v[210:213], v[218:221], v[48:63]
	v_mov_b32_e32 v128, v139
	v_mov_b32_e32 v161, v137
	v_mov_b32_e32 v177, v135
	s_barrier
	s_nop 0
	v_lshl_add_u32 v160, s11, 8, v145
	s_ashr_i32 s11, s10, 31
	s_lshl_b64 s[10:11], s[10:11], 8
	v_mov_b32_e32 v159, s11
	v_or_b32_e32 v158, s10, v134
	v_cmp_gt_i32_e32 vcc, s14, v160
	s_and_saveexec_b64 s[10:11], vcc
	s_xor_b64 s[10:11], exec, s[10:11]
	s_cbranch_execz .LBB0_132
	v_lshlrev_b32_e32 v149, 1, v161
	v_mul_lo_u32 v128, v128, s15
	v_add3_u32 v128, v163, v149, v128
	v_cvt_pk_bf16_f32 v0, v0, s0
	v_cvt_pk_bf16_f32 v64, v64, s0
	v_cvt_pk_bf16_f32 v32, v32, s0
	v_cvt_pk_bf16_f32 v16, v16, s0
	ds_write_b16 v128, v0 offset:13824
	v_cvt_pk_bf16_f32 v0, v1, s0
	ds_write_b16 v128, v64
	v_cvt_pk_bf16_f32 v64, v65, s0
	ds_write_b16 v128, v32 offset:4608
	v_cvt_pk_bf16_f32 v32, v33, s0
	ds_write_b16 v128, v16 offset:9216
	v_cvt_pk_bf16_f32 v16, v17, s0
	ds_write_b16 v128, v0 offset:13968
	v_cvt_pk_bf16_f32 v0, v2, s0
	ds_write_b16 v128, v64 offset:144
	v_cvt_pk_bf16_f32 v64, v66, s0
	ds_write_b16 v128, v32 offset:4752
	v_cvt_pk_bf16_f32 v32, v34, s0
	ds_write_b16 v128, v16 offset:9360
	v_cvt_pk_bf16_f32 v16, v18, s0
	ds_write_b16 v128, v0 offset:14112
	v_cvt_pk_bf16_f32 v0, v3, s0
	ds_write_b16 v128, v64 offset:288
	v_cvt_pk_bf16_f32 v64, v67, s0
	ds_write_b16 v128, v32 offset:4896
	v_cvt_pk_bf16_f32 v32, v35, s0
	ds_write_b16 v128, v16 offset:9504
	v_cvt_pk_bf16_f32 v16, v19, s0
	ds_write_b16 v128, v0 offset:14256
	v_cvt_pk_bf16_f32 v0, v4, s0
	ds_write_b16 v128, v64 offset:432
	v_cvt_pk_bf16_f32 v64, v68, s0
	ds_write_b16 v128, v32 offset:5040
	v_cvt_pk_bf16_f32 v32, v36, s0
	ds_write_b16 v128, v16 offset:9648
	v_cvt_pk_bf16_f32 v16, v20, s0
	ds_write_b16 v128, v0 offset:14976
	v_cvt_pk_bf16_f32 v0, v5, s0
	ds_write_b16 v128, v64 offset:1152
	v_cvt_pk_bf16_f32 v64, v69, s0
	ds_write_b16 v128, v32 offset:5760
	v_cvt_pk_bf16_f32 v32, v37, s0
	ds_write_b16 v128, v16 offset:10368
	v_cvt_pk_bf16_f32 v16, v21, s0
	ds_write_b16 v128, v0 offset:15120
	v_cvt_pk_bf16_f32 v0, v6, s0
	ds_write_b16 v128, v64 offset:1296
	v_cvt_pk_bf16_f32 v64, v70, s0
	ds_write_b16 v128, v32 offset:5904
	v_cvt_pk_bf16_f32 v32, v38, s0
	ds_write_b16 v128, v16 offset:10512
	v_cvt_pk_bf16_f32 v16, v22, s0
	ds_write_b16 v128, v0 offset:15264
	v_cvt_pk_bf16_f32 v0, v7, s0
	ds_write_b16 v128, v64 offset:1440
	v_cvt_pk_bf16_f32 v64, v71, s0
	ds_write_b16 v128, v32 offset:6048
	v_cvt_pk_bf16_f32 v32, v39, s0
	ds_write_b16 v128, v16 offset:10656
	v_cvt_pk_bf16_f32 v16, v23, s0
	ds_write_b16 v128, v0 offset:15408
	v_cvt_pk_bf16_f32 v0, v8, s0
	ds_write_b16 v128, v64 offset:1584
	v_cvt_pk_bf16_f32 v64, v72, s0
	ds_write_b16 v128, v32 offset:6192
	v_cvt_pk_bf16_f32 v32, v40, s0
	ds_write_b16 v128, v16 offset:10800
	v_cvt_pk_bf16_f32 v16, v24, s0
	ds_write_b16 v128, v0 offset:16128
	v_cvt_pk_bf16_f32 v0, v9, s0
	ds_write_b16 v128, v64 offset:2304
	v_cvt_pk_bf16_f32 v64, v73, s0
	ds_write_b16 v128, v32 offset:6912
	v_cvt_pk_bf16_f32 v32, v41, s0
	ds_write_b16 v128, v16 offset:11520
	v_cvt_pk_bf16_f32 v16, v25, s0
	ds_write_b16 v128, v0 offset:16272
	v_cvt_pk_bf16_f32 v0, v10, s0
	ds_write_b16 v128, v64 offset:2448
	v_cvt_pk_bf16_f32 v64, v74, s0
	ds_write_b16 v128, v32 offset:7056
	v_cvt_pk_bf16_f32 v32, v42, s0
	ds_write_b16 v128, v16 offset:11664
	v_cvt_pk_bf16_f32 v16, v26, s0
	ds_write_b16 v128, v0 offset:16416
	v_cvt_pk_bf16_f32 v0, v11, s0
	ds_write_b16 v128, v64 offset:2592
	v_cvt_pk_bf16_f32 v64, v75, s0
	ds_write_b16 v128, v32 offset:7200
	v_cvt_pk_bf16_f32 v32, v43, s0
	ds_write_b16 v128, v16 offset:11808
	v_cvt_pk_bf16_f32 v16, v27, s0
	ds_write_b16 v128, v0 offset:16560
	v_cvt_pk_bf16_f32 v0, v12, s0
	ds_write_b16 v128, v64 offset:2736
	v_cvt_pk_bf16_f32 v64, v76, s0
; __device__ __forceinline__ int accrow(int reg, int lh) { return (reg & 3) + 8 * (reg >> 2) + 4 * lh; }
; template <int EPI, int PN>
; __device__ void gemm_phase(const Params& p, const u16* __restrict__ A, const u16* __restrict__ Bt, int nNt, char* smem) {
;     ...
;           for (int r = 0; r < 16; ++r) *(u16*)(et + (i * 32 + accrow(r, lhE)) * 144 + (j * 32 + lrE) * 2) = f2bf(acc[i][j][r]);
; #pragma unroll
;       for (int it = 0; it < 16; ++it) {
;         const int c = it * 64 + laneE, row = c >> 3, seg = c & 7;
;         const uint4 v = *(const uint4*)(et + row * 144 + seg * 16);
;         if (EPI == 0) *(uint4*)(p.proj + (row0 + row) * NPROJ + col0 + seg * 8) = v;
	ds_write_b16 v128, v32 offset:7344
	v_cvt_pk_bf16_f32 v32, v44, s0
	ds_write_b16 v128, v16 offset:11952
	v_cvt_pk_bf16_f32 v16, v28, s0
	ds_write_b16 v128, v0 offset:17280
	v_cvt_pk_bf16_f32 v0, v13, s0
	ds_write_b16 v128, v64 offset:3456
	v_cvt_pk_bf16_f32 v64, v77, s0
	ds_write_b16 v128, v32 offset:8064
	v_cvt_pk_bf16_f32 v32, v45, s0
	ds_write_b16 v128, v16 offset:12672
	v_cvt_pk_bf16_f32 v16, v29, s0
	ds_write_b16 v128, v0 offset:17424
	v_cvt_pk_bf16_f32 v0, v14, s0
	ds_write_b16 v128, v64 offset:3600
	v_cvt_pk_bf16_f32 v64, v78, s0
	ds_write_b16 v128, v32 offset:8208
	v_cvt_pk_bf16_f32 v32, v46, s0
	ds_write_b16 v128, v16 offset:12816
	v_cvt_pk_bf16_f32 v16, v30, s0
	ds_write_b16 v128, v0 offset:17568
	v_cvt_pk_bf16_f32 v0, v15, s0
	ds_write_b16 v128, v64 offset:3744
	v_cvt_pk_bf16_f32 v64, v79, s0
	ds_write_b16 v128, v32 offset:8352
	v_cvt_pk_bf16_f32 v32, v47, s0
	ds_write_b16 v128, v16 offset:12960
	v_cvt_pk_bf16_f32 v16, v31, s0
	ds_write_b16 v128, v0 offset:17712
	v_cvt_pk_bf16_f32 v0, v48, s0
	ds_write_b16 v128, v64 offset:3888
	v_cvt_pk_bf16_f32 v64, v112, s0
	ds_write_b16 v128, v32 offset:8496
	v_cvt_pk_bf16_f32 v32, v96, s0
	ds_write_b16 v128, v16 offset:13104
	v_cvt_pk_bf16_f32 v16, v80, s0
	ds_write_b16 v128, v0 offset:13888
	v_cvt_pk_bf16_f32 v0, v49, s0
	ds_write_b16 v128, v64 offset:64
	v_cvt_pk_bf16_f32 v64, v113, s0
	ds_write_b16 v128, v32 offset:4672
	v_cvt_pk_bf16_f32 v32, v97, s0
	ds_write_b16 v128, v16 offset:9280
	v_cvt_pk_bf16_f32 v16, v81, s0
	ds_write_b16 v128, v0 offset:14032
	v_cvt_pk_bf16_f32 v0, v50, s0
	ds_write_b16 v128, v64 offset:208
	v_cvt_pk_bf16_f32 v64, v114, s0
	ds_write_b16 v128, v32 offset:4816
	v_cvt_pk_bf16_f32 v32, v98, s0
	ds_write_b16 v128, v16 offset:9424
	v_cvt_pk_bf16_f32 v16, v82, s0
	ds_write_b16 v128, v0 offset:14176
	v_cvt_pk_bf16_f32 v0, v51, s0
	ds_write_b16 v128, v64 offset:352
	v_cvt_pk_bf16_f32 v64, v115, s0
	ds_write_b16 v128, v32 offset:4960
	v_cvt_pk_bf16_f32 v32, v99, s0
	ds_write_b16 v128, v16 offset:9568
	v_cvt_pk_bf16_f32 v16, v83, s0
	ds_write_b16 v128, v0 offset:14320
	v_cvt_pk_bf16_f32 v0, v52, s0
	ds_write_b16 v128, v64 offset:496
	v_cvt_pk_bf16_f32 v64, v116, s0
	ds_write_b16 v128, v32 offset:5104
	v_cvt_pk_bf16_f32 v32, v100, s0
	ds_write_b16 v128, v16 offset:9712
	v_cvt_pk_bf16_f32 v16, v84, s0
	ds_write_b16 v128, v0 offset:15040
	v_cvt_pk_bf16_f32 v0, v53, s0
	ds_write_b16 v128, v64 offset:1216
	v_cvt_pk_bf16_f32 v64, v117, s0
	ds_write_b16 v128, v32 offset:5824
	v_cvt_pk_bf16_f32 v32, v101, s0
	ds_write_b16 v128, v16 offset:10432
	v_cvt_pk_bf16_f32 v16, v85, s0
	ds_write_b16 v128, v0 offset:15184
	v_cvt_pk_bf16_f32 v0, v54, s0
	ds_write_b16 v128, v64 offset:1360
	v_cvt_pk_bf16_f32 v64, v118, s0
	ds_write_b16 v128, v32 offset:5968
	v_cvt_pk_bf16_f32 v32, v102, s0
	ds_write_b16 v128, v16 offset:10576
	v_cvt_pk_bf16_f32 v16, v86, s0
	ds_write_b16 v128, v0 offset:15328
	v_cvt_pk_bf16_f32 v0, v55, s0
	ds_write_b16 v128, v64 offset:1504
	v_cvt_pk_bf16_f32 v64, v119, s0
	ds_write_b16 v128, v32 offset:6112
	v_cvt_pk_bf16_f32 v32, v103, s0
	ds_write_b16 v128, v16 offset:10720
	v_cvt_pk_bf16_f32 v16, v87, s0
	ds_write_b16 v128, v0 offset:15472
	v_cvt_pk_bf16_f32 v0, v56, s0
	ds_write_b16 v128, v64 offset:1648
	v_cvt_pk_bf16_f32 v64, v120, s0
	ds_write_b16 v128, v32 offset:6256
	v_cvt_pk_bf16_f32 v32, v104, s0
	ds_write_b16 v128, v16 offset:10864
	v_cvt_pk_bf16_f32 v16, v88, s0
	ds_write_b16 v128, v0 offset:16192
	v_cvt_pk_bf16_f32 v0, v57, s0
	ds_write_b16 v128, v64 offset:2368
	v_cvt_pk_bf16_f32 v64, v121, s0
	ds_write_b16 v128, v32 offset:6976
	v_cvt_pk_bf16_f32 v32, v105, s0
	ds_write_b16 v128, v16 offset:11584
	v_cvt_pk_bf16_f32 v16, v89, s0
	ds_write_b16 v128, v0 offset:16336
	v_cvt_pk_bf16_f32 v0, v58, s0
	ds_write_b16 v128, v64 offset:2512
	v_cvt_pk_bf16_f32 v64, v122, s0
	ds_write_b16 v128, v32 offset:7120
	v_cvt_pk_bf16_f32 v32, v106, s0
	ds_write_b16 v128, v16 offset:11728
	v_cvt_pk_bf16_f32 v16, v90, s0
	ds_write_b16 v128, v0 offset:16480
	v_cvt_pk_bf16_f32 v0, v59, s0
	ds_write_b16 v128, v64 offset:2656
	v_cvt_pk_bf16_f32 v64, v123, s0
	ds_write_b16 v128, v32 offset:7264
	v_cvt_pk_bf16_f32 v32, v107, s0
	ds_write_b16 v128, v16 offset:11872
	v_cvt_pk_bf16_f32 v16, v91, s0
	ds_write_b16 v128, v0 offset:16624
	v_cvt_pk_bf16_f32 v0, v60, s0
	ds_write_b16 v128, v64 offset:2800
	v_cvt_pk_bf16_f32 v64, v124, s0
	ds_write_b16 v128, v32 offset:7408
	v_cvt_pk_bf16_f32 v32, v108, s0
	ds_write_b16 v128, v16 offset:12016
	v_cvt_pk_bf16_f32 v16, v92, s0
	ds_write_b16 v128, v0 offset:17344
	v_cvt_pk_bf16_f32 v0, v61, s0
	ds_write_b16 v128, v64 offset:3520
	v_cvt_pk_bf16_f32 v64, v125, s0
	ds_write_b16 v128, v32 offset:8128
	v_cvt_pk_bf16_f32 v32, v109, s0
	ds_write_b16 v128, v16 offset:12736
	v_cvt_pk_bf16_f32 v16, v93, s0
	ds_write_b16 v128, v0 offset:17488
	v_cvt_pk_bf16_f32 v0, v62, s0
	ds_write_b16 v128, v64 offset:3664
	v_cvt_pk_bf16_f32 v64, v126, s0
	ds_write_b16 v128, v32 offset:8272
	v_cvt_pk_bf16_f32 v32, v110, s0
	ds_write_b16 v128, v16 offset:12880
	v_cvt_pk_bf16_f32 v16, v94, s0
	ds_write_b16 v128, v0 offset:17632
	v_cvt_pk_bf16_f32 v0, v63, s0
	ds_write_b16 v128, v64 offset:3808
	v_cvt_pk_bf16_f32 v64, v127, s0
	ds_write_b16 v128, v32 offset:8416
	v_cvt_pk_bf16_f32 v32, v111, s0
	ds_write_b16 v128, v16 offset:13024
	v_cvt_pk_bf16_f32 v16, v95, s0
	ds_write_b16 v128, v0 offset:17776
	v_lshlrev_b32_e32 v0, 4, v177
	ds_write_b16 v128, v64 offset:3952
	ds_write_b16 v128, v32 offset:8560
	ds_write_b16 v128, v16 offset:13168
	v_and_b32_e32 v128, 0x70, v0
	v_add_u32_e32 v0, v163, v128
	v_ashrrev_i32_e32 v6, 3, v177
	v_readlane_b32 s36, v253, 39
	v_mad_u64_u32 v[2:3], s[12:13], v6, s16, v[0:1]
	v_ashrrev_i32_e32 v7, 31, v6
	v_readlane_b32 s40, v253, 43
	v_readlane_b32 s41, v253, 44
	ds_read_b128 v[2:5], v2
	v_lshl_add_u64 v[6:7], v[158:159], 0, v[6:7]
	v_mov_b64_e32 v[10:11], s[40:41]
	v_ashrrev_i32_e32 v161, 31, v160
	v_mad_u64_u32 v[8:9], s[12:13], v6, s17, v[10:11]
	v_mad_i32_i24 v9, v7, s17, v9
	v_lshlrev_b64 v[12:13], 1, v[160:161]
	v_add_u32_e32 v1, 64, v177
	v_lshl_add_u64 v[6:7], v[8:9], 0, v[12:13]
	v_ashrrev_i32_e32 v16, 3, v1
	v_lshl_add_u64 v[14:15], v[6:7], 0, v[128:129]
	v_mad_u64_u32 v[6:7], s[12:13], v16, s16, v[0:1]
	v_ashrrev_i32_e32 v17, 31, v16
	ds_read_b128 v[6:9], v6
	s_waitcnt lgkmcnt(1)
; template <int EPI, int PN>
; __device__ void gemm_phase(const Params& p, const u16* __restrict__ A, const u16* __restrict__ Bt, int nNt, char* smem) {
;     ...
;       for (int it = 0; it < 16; ++it) {
;         const int c = it * 64 + laneE, row = c >> 3, seg = c & 7;
;         const uint4 v = *(const uint4*)(et + row * 144 + seg * 16);
;         if (EPI == 0) *(uint4*)(p.proj + (row0 + row) * NPROJ + col0 + seg * 8) = v;
	global_store_dwordx4 v[14:15], v[2:5], off
	v_add_u32_e32 v1, 0x80, v177
	v_readlane_b32 s37, v253, 40
	v_lshl_add_u64 v[2:3], v[158:159], 0, v[16:17]
	v_mad_u64_u32 v[4:5], s[12:13], v2, s17, v[10:11]
	v_mad_i32_i24 v5, v3, s17, v5
	v_lshl_add_u64 v[2:3], v[4:5], 0, v[12:13]
	v_lshl_add_u64 v[2:3], v[2:3], 0, v[128:129]
	s_waitcnt lgkmcnt(0)
	global_store_dwordx4 v[2:3], v[6:9], off
	v_readlane_b32 s38, v253, 41
	v_readlane_b32 s39, v253, 42
	v_ashrrev_i32_e32 v6, 3, v1
	v_mad_u64_u32 v[2:3], s[12:13], v6, s16, v[0:1]
	v_ashrrev_i32_e32 v7, 31, v6
	ds_read_b128 v[2:5], v2
	v_lshl_add_u64 v[6:7], v[158:159], 0, v[6:7]
	v_mad_u64_u32 v[8:9], s[12:13], v6, s17, v[10:11]
	v_mad_i32_i24 v9, v7, s17, v9
	v_add_u32_e32 v1, 0xc0, v177
	v_lshl_add_u64 v[6:7], v[8:9], 0, v[12:13]
	v_ashrrev_i32_e32 v16, 3, v1
	v_lshl_add_u64 v[14:15], v[6:7], 0, v[128:129]
	v_mad_u64_u32 v[6:7], s[12:13], v16, s16, v[0:1]
	v_ashrrev_i32_e32 v17, 31, v16
	ds_read_b128 v[6:9], v6
	s_waitcnt lgkmcnt(1)
	global_store_dwordx4 v[14:15], v[2:5], off
	v_add_u32_e32 v1, 0x100, v177
	v_readlane_b32 s42, v253, 45
	v_lshl_add_u64 v[2:3], v[158:159], 0, v[16:17]
	v_mad_u64_u32 v[4:5], s[12:13], v2, s17, v[10:11]
	v_mad_i32_i24 v5, v3, s17, v5
	v_lshl_add_u64 v[2:3], v[4:5], 0, v[12:13]
	v_lshl_add_u64 v[2:3], v[2:3], 0, v[128:129]
	s_waitcnt lgkmcnt(0)
	global_store_dwordx4 v[2:3], v[6:9], off
	v_readlane_b32 s43, v253, 46
	v_readlane_b32 s44, v253, 47
	v_ashrrev_i32_e32 v6, 3, v1
	v_mad_u64_u32 v[2:3], s[12:13], v6, s16, v[0:1]
	v_ashrrev_i32_e32 v7, 31, v6
	ds_read_b128 v[2:5], v2
	v_lshl_add_u64 v[6:7], v[158:159], 0, v[6:7]
	v_mad_u64_u32 v[8:9], s[12:13], v6, s17, v[10:11]
	v_mad_i32_i24 v9, v7, s17, v9
	v_add_u32_e32 v1, 0x140, v177
	v_lshl_add_u64 v[6:7], v[8:9], 0, v[12:13]
	v_ashrrev_i32_e32 v16, 3, v1
	v_lshl_add_u64 v[14:15], v[6:7], 0, v[128:129]
	v_mad_u64_u32 v[6:7], s[12:13], v16, s16, v[0:1]
	v_ashrrev_i32_e32 v17, 31, v16
	ds_read_b128 v[6:9], v6
	s_waitcnt lgkmcnt(1)
	global_store_dwordx4 v[14:15], v[2:5], off
	v_add_u32_e32 v1, 0x180, v177
	v_readlane_b32 s45, v253, 48
	v_lshl_add_u64 v[2:3], v[158:159], 0, v[16:17]
	v_mad_u64_u32 v[4:5], s[12:13], v2, s17, v[10:11]
	v_mad_i32_i24 v5, v3, s17, v5
	v_lshl_add_u64 v[2:3], v[4:5], 0, v[12:13]
	v_lshl_add_u64 v[2:3], v[2:3], 0, v[128:129]
	s_waitcnt lgkmcnt(0)
	global_store_dwordx4 v[2:3], v[6:9], off
	v_readlane_b32 s46, v253, 49
	v_readlane_b32 s47, v253, 50
	v_ashrrev_i32_e32 v6, 3, v1
	v_mad_u64_u32 v[2:3], s[12:13], v6, s16, v[0:1]
	v_ashrrev_i32_e32 v7, 31, v6
	ds_read_b128 v[2:5], v2
	v_lshl_add_u64 v[6:7], v[158:159], 0, v[6:7]
	v_mad_u64_u32 v[8:9], s[12:13], v6, s17, v[10:11]
	v_mad_i32_i24 v9, v7, s17, v9
	v_add_u32_e32 v1, 0x1c0, v177
	v_lshl_add_u64 v[6:7], v[8:9], 0, v[12:13]
	v_ashrrev_i32_e32 v16, 3, v1
	v_lshl_add_u64 v[14:15], v[6:7], 0, v[128:129]
	v_mad_u64_u32 v[6:7], s[12:13], v16, s16, v[0:1]
	v_ashrrev_i32_e32 v17, 31, v16
	ds_read_b128 v[6:9], v6
	s_waitcnt lgkmcnt(1)
	global_store_dwordx4 v[14:15], v[2:5], off
	v_add_u32_e32 v1, 0x200, v177
	v_readlane_b32 s48, v253, 51
	v_lshl_add_u64 v[2:3], v[158:159], 0, v[16:17]
	v_mad_u64_u32 v[4:5], s[12:13], v2, s17, v[10:11]
	v_mad_i32_i24 v5, v3, s17, v5
	v_lshl_add_u64 v[2:3], v[4:5], 0, v[12:13]
	v_lshl_add_u64 v[2:3], v[2:3], 0, v[128:129]
	s_waitcnt lgkmcnt(0)
; template <int EPI, int PN>
; __device__ void gemm_phase(const Params& p, const u16* __restrict__ A, const u16* __restrict__ Bt, int nNt, char* smem) {
;     ...
;       for (int it = 0; it < 16; ++it) {
;         const int c = it * 64 + laneE, row = c >> 3, seg = c & 7;
;         const uint4 v = *(const uint4*)(et + row * 144 + seg * 16);
;         if (EPI == 0) *(uint4*)(p.proj + (row0 + row) * NPROJ + col0 + seg * 8) = v;
	global_store_dwordx4 v[2:3], v[6:9], off
	v_readlane_b32 s49, v253, 52
	v_readlane_b32 s50, v253, 53
	v_ashrrev_i32_e32 v6, 3, v1
	v_mad_u64_u32 v[2:3], s[12:13], v6, s16, v[0:1]
	v_ashrrev_i32_e32 v7, 31, v6
	ds_read_b128 v[2:5], v2
	v_lshl_add_u64 v[6:7], v[158:159], 0, v[6:7]
	v_mad_u64_u32 v[8:9], s[12:13], v6, s17, v[10:11]
	v_mad_i32_i24 v9, v7, s17, v9
	v_add_u32_e32 v1, 0x240, v177
	v_lshl_add_u64 v[6:7], v[8:9], 0, v[12:13]
	v_ashrrev_i32_e32 v16, 3, v1
	v_lshl_add_u64 v[14:15], v[6:7], 0, v[128:129]
	v_mad_u64_u32 v[6:7], s[12:13], v16, s16, v[0:1]
	v_ashrrev_i32_e32 v17, 31, v16
	ds_read_b128 v[6:9], v6
	s_waitcnt lgkmcnt(1)
	global_store_dwordx4 v[14:15], v[2:5], off
	v_add_u32_e32 v1, 0x280, v177
	v_readlane_b32 s51, v253, 54
	v_lshl_add_u64 v[2:3], v[158:159], 0, v[16:17]
	v_mad_u64_u32 v[4:5], s[12:13], v2, s17, v[10:11]
	v_mad_i32_i24 v5, v3, s17, v5
	v_lshl_add_u64 v[2:3], v[4:5], 0, v[12:13]
	v_lshl_add_u64 v[2:3], v[2:3], 0, v[128:129]
	s_waitcnt lgkmcnt(0)
	global_store_dwordx4 v[2:3], v[6:9], off
	s_nop 1
	v_ashrrev_i32_e32 v6, 3, v1
	v_mad_u64_u32 v[2:3], s[12:13], v6, s16, v[0:1]
	v_ashrrev_i32_e32 v7, 31, v6
	ds_read_b128 v[2:5], v2
	v_lshl_add_u64 v[6:7], v[158:159], 0, v[6:7]
	v_mad_u64_u32 v[8:9], s[12:13], v6, s17, v[10:11]
	v_mad_i32_i24 v9, v7, s17, v9
	v_add_u32_e32 v1, 0x2c0, v177
	v_lshl_add_u64 v[6:7], v[8:9], 0, v[12:13]
	v_ashrrev_i32_e32 v16, 3, v1
	v_lshl_add_u64 v[14:15], v[6:7], 0, v[128:129]
	v_mad_u64_u32 v[6:7], s[12:13], v16, s16, v[0:1]
	v_ashrrev_i32_e32 v17, 31, v16
	ds_read_b128 v[6:9], v6
	s_waitcnt lgkmcnt(1)
	global_store_dwordx4 v[14:15], v[2:5], off
	v_add_u32_e32 v1, 0x300, v177
	s_nop 0
	v_lshl_add_u64 v[2:3], v[158:159], 0, v[16:17]
	v_mad_u64_u32 v[4:5], s[12:13], v2, s17, v[10:11]
	v_mad_i32_i24 v5, v3, s17, v5
	v_lshl_add_u64 v[2:3], v[4:5], 0, v[12:13]
	v_lshl_add_u64 v[2:3], v[2:3], 0, v[128:129]
	s_waitcnt lgkmcnt(0)
	global_store_dwordx4 v[2:3], v[6:9], off
	s_nop 1
	v_ashrrev_i32_e32 v6, 3, v1
	v_mad_u64_u32 v[2:3], s[12:13], v6, s16, v[0:1]
	v_ashrrev_i32_e32 v7, 31, v6
	ds_read_b128 v[2:5], v2
	v_lshl_add_u64 v[6:7], v[158:159], 0, v[6:7]
	v_mad_u64_u32 v[8:9], s[12:13], v6, s17, v[10:11]
	v_mad_i32_i24 v9, v7, s17, v9
	v_add_u32_e32 v1, 0x340, v177
	v_lshl_add_u64 v[6:7], v[8:9], 0, v[12:13]
	v_ashrrev_i32_e32 v16, 3, v1
	v_lshl_add_u64 v[14:15], v[6:7], 0, v[128:129]
	v_mad_u64_u32 v[6:7], s[12:13], v16, s16, v[0:1]
	v_ashrrev_i32_e32 v17, 31, v16
	ds_read_b128 v[6:9], v6
	s_waitcnt lgkmcnt(1)
	global_store_dwordx4 v[14:15], v[2:5], off
	v_add_u32_e32 v1, 0x380, v177
	s_nop 0
	v_lshl_add_u64 v[2:3], v[158:159], 0, v[16:17]
	v_mad_u64_u32 v[4:5], s[12:13], v2, s17, v[10:11]
	v_mad_i32_i24 v5, v3, s17, v5
	v_lshl_add_u64 v[2:3], v[4:5], 0, v[12:13]
	v_lshl_add_u64 v[2:3], v[2:3], 0, v[128:129]
	s_waitcnt lgkmcnt(0)
	global_store_dwordx4 v[2:3], v[6:9], off
	s_nop 1
	v_ashrrev_i32_e32 v6, 3, v1
	v_mad_u64_u32 v[2:3], s[12:13], v6, s16, v[0:1]
	v_ashrrev_i32_e32 v7, 31, v6
	ds_read_b128 v[2:5], v2
	v_lshl_add_u64 v[6:7], v[158:159], 0, v[6:7]
	v_mad_u64_u32 v[8:9], s[12:13], v6, s17, v[10:11]
	v_add_u32_e32 v1, 0x3c0, v177
	v_mad_i32_i24 v9, v7, s17, v9
	v_ashrrev_i32_e32 v16, 3, v1
	v_lshl_add_u64 v[6:7], v[8:9], 0, v[12:13]
	v_mad_u64_u32 v[0:1], s[12:13], v16, s16, v[0:1]
	v_ashrrev_i32_e32 v17, 31, v16
	v_lshl_add_u64 v[14:15], v[6:7], 0, v[128:129]
	ds_read_b128 v[6:9], v0
	v_lshl_add_u64 v[0:1], v[158:159], 0, v[16:17]
	s_waitcnt lgkmcnt(1)
	global_store_dwordx4 v[14:15], v[2:5], off
	s_nop 1
	v_mad_u64_u32 v[2:3], s[12:13], v0, s17, v[10:11]
	v_mad_i32_i24 v3, v1, s17, v3
	v_lshl_add_u64 v[0:1], v[2:3], 0, v[12:13]
	v_lshl_add_u64 v[0:1], v[0:1], 0, v[128:129]
	s_waitcnt lgkmcnt(0)
	global_store_dwordx4 v[0:1], v[6:9], off

; template <int EPI, int PN>
; __device__ void gemm_phase(const Params& p, const u16* __restrict__ A, const u16* __restrict__ Bt, int nNt, char* smem) {
;     ...
;     const int pl = q / (4 * PN), w = q % (4 * PN);
;     const int gp = pl * 8 + xcd;
;     if (gp >= npatch) break;
;     const int mt = (gp / npn) * 4 + (w & 3), nt = (gp % npn) * PN + (w >> 2);
;     const int gch = sch ^ ((srow >> 1) & 7);
;     const u16* Ag0 = A + (size_t)(mt * 256 + srow) * LDK + gch * 8;
;     const u16* Bg0 = Bt + (size_t)(nt * 256 + srow) * LDK + gch * 8;
;     f32x16 acc[4][2];
; #pragma unroll
;     for (int i = 0; i < 4; ++i)
; #pragma unroll
;       for (int j = 0; j < 2; ++j) acc[i][j] = zero16();
;     asm volatile("s_waitcnt vmcnt(0)" ::: "memory");
; #pragma unroll
;     for (int i = 0; i < 4; ++i) {
;       glds16(Ag0 + (size_t)i * 64 * LDK, ring + (srow + 64 * i) * 64 + sch * 8);
;       glds16(Bg0 + (size_t)i * 64 * LDK, ring + 16384 + (srow + 64 * i) * 64 + sch * 8);
;     }
;     for (int kt = 0; kt < 32; ++kt) {
;       asm volatile("s_waitcnt vmcnt(0)" ::: "memory");
;       __builtin_amdgcn_s_barrier();
;       const u16* Ab = ring + (kt & 1) * STG;
;       const u16* Bb = Ab + 16384;
;       u16* st = ring + ((kt + 1) & 1) * STG;
;       const bool pre = (kt + 1 < 32);
;       s16x8 af[2][4], bf[2][2];
;       auto ldfrag = [&](int ks, int slot) {
; #pragma unroll
;         for (int i = 0; i < 4; ++i) {
;           const int row = wr * 128 + i * 32 + lr;
;           af[slot][i] = *(const s16x8*)(Ab + row * 64 + (((ks * 2 + lh) ^ ((row >> 1) & 7)) * 8));
;         }
; #pragma unroll
;         for (int j = 0; j < 2; ++j) {
;           const int rowb = nh * 128 + wc * 64 + j * 32 + lr;
;           bf[slot][j] = *(const s16x8*)(Bb + rowb * 64 + (((ks * 2 + lh) ^ ((rowb >> 1) & 7)) * 8));
;         }
;       };
;       ldfrag(0, 0);
;       ldfrag(1, 1);
.LBB0_665:
	s_ashr_i32 s12, s16, 31
	s_lshr_b32 s12, s12, 27
	s_add_i32 s12, s16, s12
	s_andn2_b32 s12, s12, 31
	s_sub_i32 s13, s16, s12
	s_lshl_b32 s12, s17, 2
	s_and_b32 s20, s13, 3
	s_or_b32 s12, s20, s12
	s_ashr_i32 s13, s13, 2
	v_lshl_add_u32 v0, s12, 8, v141
	v_lshl_add_u32 v6, s13, 8, v141
	v_mad_i64_i32 v[0:1], s[18:19], v0, s2, v[130:131]
	v_mad_i64_i32 v[2:3], s[18:19], v6, s2, v[132:133]
	s_waitcnt vmcnt(0)
	v_readfirstlane_b32 s18, v136
	s_mov_b32 s19, m0
	s_mov_b32 m0, s18
	s_nop 0
	global_load_lds_dwordx4 v[0:1], off
	s_mov_b32 m0, s19
	v_readfirstlane_b32 s18, v138
	s_mov_b32 s19, m0
	s_mov_b32 m0, s18
	s_nop 0
	global_load_lds_dwordx4 v[2:3], off
	s_mov_b32 m0, s19
	v_lshl_add_u64 v[4:5], v[0:1], 0, s[4:5]
	v_readfirstlane_b32 s18, v140
	s_mov_b32 s19, m0
	s_mov_b32 m0, s18
	s_nop 0
	global_load_lds_dwordx4 v[4:5], off
	s_mov_b32 m0, s19
	v_lshl_add_u64 v[4:5], v[2:3], 0, s[4:5]
	v_readfirstlane_b32 s18, v142
	s_mov_b32 s19, m0
	s_mov_b32 m0, s18
	s_nop 0
	global_load_lds_dwordx4 v[4:5], off
	s_mov_b32 m0, s19
	v_lshl_add_u64 v[4:5], v[0:1], 0, s[6:7]
	v_readfirstlane_b32 s18, v144
	s_mov_b32 s19, m0
	s_mov_b32 m0, s18
	s_nop 0
	global_load_lds_dwordx4 v[4:5], off
	s_mov_b32 m0, s19
	v_lshl_add_u64 v[4:5], v[2:3], 0, s[6:7]
	v_readfirstlane_b32 s18, v146
	s_mov_b32 s19, m0
	s_mov_b32 m0, s18
	s_nop 0
	global_load_lds_dwordx4 v[4:5], off
	s_mov_b32 m0, s19
	v_add_u32_e32 v4, 0x6000, v136
	v_lshl_add_u64 v[0:1], v[0:1], 0, s[8:9]
	v_readfirstlane_b32 s18, v4
	s_mov_b32 s19, m0
	s_mov_b32 m0, s18
	s_nop 0
	global_load_lds_dwordx4 v[0:1], off
	s_mov_b32 m0, s19
	v_readfirstlane_b32 s18, v150
	v_lshl_add_u64 v[0:1], v[2:3], 0, s[8:9]
	s_mov_b32 s19, m0
	s_mov_b32 m0, s18
	s_nop 0
	global_load_lds_dwordx4 v[0:1], off
	s_mov_b32 m0, s19
	s_lshl_b32 s17, s17, 10
	s_lshl_b32 s18, s20, 8
	s_or_b32 s17, s18, s17
	v_add_u32_e32 v0, s17, v141
	v_mad_i64_i32 v[158:159], s[18:19], v0, s2, v[152:153]
	v_mad_i64_i32 v[160:161], s[18:19], v6, s2, v[154:155]
	s_mov_b32 s17, 0x8000
	v_mov_b32_e32 v0, 0
	v_mov_b32_e32 v1, v129
	v_mov_b32_e32 v2, v129
	v_mov_b32_e32 v3, v129
	v_mov_b32_e32 v4, v129
	v_mov_b32_e32 v5, v129
	v_mov_b32_e32 v6, v129
	v_mov_b32_e32 v7, v129
	v_mov_b32_e32 v8, v129
	v_mov_b32_e32 v9, v129
	v_mov_b32_e32 v10, v129
	v_mov_b32_e32 v11, v129
	v_mov_b32_e32 v12, v129
	v_mov_b32_e32 v13, v129
	v_mov_b32_e32 v14, v129
	v_mov_b32_e32 v15, v129
	v_mov_b32_e32 v64, 0
	v_mov_b32_e32 v65, v129
	v_mov_b32_e32 v66, v129
	v_mov_b32_e32 v67, v129
	v_mov_b32_e32 v68, v129
	v_mov_b32_e32 v69, v129
	v_mov_b32_e32 v70, v129
	v_mov_b32_e32 v71, v129
	v_mov_b32_e32 v72, v129
	v_mov_b32_e32 v73, v129
	v_mov_b32_e32 v74, v129
	v_mov_b32_e32 v75, v129
	v_mov_b32_e32 v76, v129
	v_mov_b32_e32 v77, v129
	v_mov_b32_e32 v78, v129
	v_mov_b32_e32 v79, v129
	v_mov_b32_e32 v16, 0
	v_mov_b32_e32 v17, v129
	v_mov_b32_e32 v18, v129
	v_mov_b32_e32 v19, v129
	v_mov_b32_e32 v20, v129
	v_mov_b32_e32 v21, v129
	v_mov_b32_e32 v22, v129
	v_mov_b32_e32 v23, v129
	v_mov_b32_e32 v24, v129
	v_mov_b32_e32 v25, v129
	v_mov_b32_e32 v26, v129
	v_mov_b32_e32 v27, v129
	v_mov_b32_e32 v28, v129
	v_mov_b32_e32 v29, v129
	v_mov_b32_e32 v30, v129
	v_mov_b32_e32 v31, v129
	v_mov_b32_e32 v80, 0
	v_mov_b32_e32 v81, v129
	v_mov_b32_e32 v82, v129
	v_mov_b32_e32 v83, v129
	v_mov_b32_e32 v84, v129
	v_mov_b32_e32 v85, v129
	v_mov_b32_e32 v86, v129
	v_mov_b32_e32 v87, v129
	v_mov_b32_e32 v88, v129
	v_mov_b32_e32 v89, v129
	v_mov_b32_e32 v90, v129
	v_mov_b32_e32 v91, v129
	v_mov_b32_e32 v92, v129
	v_mov_b32_e32 v93, v129
	v_mov_b32_e32 v94, v129
	v_mov_b32_e32 v95, v129
	v_mov_b32_e32 v32, 0
	v_mov_b32_e32 v33, v129
	v_mov_b32_e32 v34, v129
	v_mov_b32_e32 v35, v129
	v_mov_b32_e32 v36, v129
	v_mov_b32_e32 v37, v129
	v_mov_b32_e32 v38, v129
	v_mov_b32_e32 v39, v129
	v_mov_b32_e32 v40, v129
	v_mov_b32_e32 v41, v129
	v_mov_b32_e32 v42, v129
	v_mov_b32_e32 v43, v129
	v_mov_b32_e32 v44, v129
	v_mov_b32_e32 v45, v129
	v_mov_b32_e32 v46, v129
	v_mov_b32_e32 v47, v129
	v_mov_b32_e32 v96, 0
	v_mov_b32_e32 v97, v129
	v_mov_b32_e32 v98, v129
	v_mov_b32_e32 v99, v129
	v_mov_b32_e32 v100, v129
	v_mov_b32_e32 v101, v129
	v_mov_b32_e32 v102, v129
	v_mov_b32_e32 v103, v129
	v_mov_b32_e32 v104, v129
	v_mov_b32_e32 v105, v129
	v_mov_b32_e32 v106, v129
	v_mov_b32_e32 v107, v129
	v_mov_b32_e32 v108, v129
	v_mov_b32_e32 v109, v129
	v_mov_b32_e32 v110, v129
	v_mov_b32_e32 v111, v129
	v_mov_b32_e32 v48, 0
	v_mov_b32_e32 v49, v129
	v_mov_b32_e32 v50, v129
	v_mov_b32_e32 v51, v129
	v_mov_b32_e32 v52, v129
	v_mov_b32_e32 v53, v129
	v_mov_b32_e32 v54, v129
	v_mov_b32_e32 v55, v129
	v_mov_b32_e32 v56, v129
	v_mov_b32_e32 v57, v129
	v_mov_b32_e32 v58, v129
	v_mov_b32_e32 v59, v129
	v_mov_b32_e32 v60, v129
	v_mov_b32_e32 v61, v129
	v_mov_b32_e32 v62, v129
	v_mov_b32_e32 v63, v129
	v_mov_b32_e32 v112, 0
	v_mov_b32_e32 v113, v129
	v_mov_b32_e32 v114, v129
	v_mov_b32_e32 v115, v129
	v_mov_b32_e32 v116, v129
	v_mov_b32_e32 v117, v129
	v_mov_b32_e32 v118, v129
	v_mov_b32_e32 v119, v129
	v_mov_b32_e32 v120, v129
	v_mov_b32_e32 v121, v129
	v_mov_b32_e32 v122, v129
	v_mov_b32_e32 v123, v129
	v_mov_b32_e32 v124, v129
	v_mov_b32_e32 v125, v129
	v_mov_b32_e32 v126, v129
	v_mov_b32_e32 v127, v129
	v_readfirstlane_b32 s99, v136
	s_add_i32 s99, s99, 0x10000
	s_mov_b32 s19, m0
	s_mov_b32 m0, s99
	s_nop 0
	global_load_lds_dwordx4 v[158:159], off
	v_lshl_add_u64 v[188:189], v[158:159], 0, s[4:5]
	s_add_i32 m0, s99, 0x2000
	s_nop 0
	global_load_lds_dwordx4 v[188:189], off
	v_lshl_add_u64 v[190:191], v[158:159], 0, s[6:7]
	s_add_i32 m0, s99, 0x4000
	s_nop 0
	global_load_lds_dwordx4 v[190:191], off
	v_lshl_add_u64 v[188:189], v[158:159], 0, s[8:9]
	s_add_i32 m0, s99, 0x6000
	s_nop 0
	global_load_lds_dwordx4 v[188:189], off
	s_mov_b32 m0, s19
	v_lshl_add_u64 v[158:159], v[158:159], 0, s[10:11]
	s_waitcnt vmcnt(0)
	s_barrier
	v_lshlrev_b32_e32 v212, 1, v143
	v_lshlrev_b32_e32 v213, 1, v147
	v_add_u32_e32 v149, v212, v234
	v_add_u32_e32 v148, v213, v234
	ds_read_b128 v[162:165], v149
	ds_read_b128 v[168:171], v149 offset:4096
	ds_read_b128 v[172:175], v149 offset:8192
	ds_read_b128 v[176:179], v149 offset:12288
	ds_read_b128 v[180:183], v148 offset:32768
	ds_read_b128 v[184:187], v148 offset:36864
	v_add_u32_e32 v149, v212, v235
	v_add_u32_e32 v148, v213, v235
	ds_read_b128 v[188:191], v149
	ds_read_b128 v[192:195], v149 offset:4096
	ds_read_b128 v[196:199], v149 offset:8192
	ds_read_b128 v[200:203], v149 offset:12288
	ds_read_b128 v[204:207], v148 offset:32768
	ds_read_b128 v[208:211], v148 offset:36864
; template <int EPI, int PN>
; __device__ void gemm_phase(const Params& p, const u16* __restrict__ A, const u16* __restrict__ Bt, int nNt, char* smem) {
;     ...
;     for (int kt = 0; kt < 32; ++kt) {
;       asm volatile("s_waitcnt vmcnt(0)" ::: "memory");
;       __builtin_amdgcn_s_barrier();
;       const u16* Ab = ring + (kt & 1) * STG;
;       const u16* Bb = Ab + 16384;
;       u16* st = ring + ((kt + 1) & 1) * STG;
;       const bool pre = (kt + 1 < 32);
;       s16x8 af[2][4], bf[2][2];
;       auto ldfrag = [&](int ks, int slot) {
; #pragma unroll
;         for (int i = 0; i < 4; ++i) {
;           const int row = wr * 128 + i * 32 + lr;
;           af[slot][i] = *(const s16x8*)(Ab + row * 64 + (((ks * 2 + lh) ^ ((row >> 1) & 7)) * 8));
;         }
; #pragma unroll
;         for (int j = 0; j < 2; ++j) {
;           const int rowb = nh * 128 + wc * 64 + j * 32 + lr;
;           bf[slot][j] = *(const s16x8*)(Bb + rowb * 64 + (((ks * 2 + lh) ^ ((rowb >> 1) & 7)) * 8));
;         }
;       };
;       ldfrag(0, 0);
;       ldfrag(1, 1);
;       __builtin_amdgcn_sched_barrier(0);
; #pragma unroll
;       for (int ks = 0; ks < 4; ++ks) {
;         const int slot = ks & 1;
; #pragma unroll
;         for (int i = 0; i < 4; ++i) {
;           acc[i][0] = mfma32(af[slot][i], bf[slot][0], acc[i][0]);
;           acc[i][1] = mfma32(af[slot][i], bf[slot][1], acc[i][1]);
;           __builtin_amdgcn_sched_barrier(0);
;           if (pre && (i & 1) == 0) {
;             const int pi = ks * 2 + (i >> 1);
;             if (pi < 4) glds16(Ag0 + (size_t)pi * 64 * LDK + (kt + 1) * 64, st + (srow + 64 * pi) * 64 + sch * 8);
;             else glds16(Bg0 + (size_t)(pi - 4) * 64 * LDK + (kt + 1) * 64, st + 16384 + (srow + 64 * (pi - 4)) * 64 + sch * 8);
;             __builtin_amdgcn_sched_barrier(0);
;           }
;         }
;         if (ks + 2 < 4) { ldfrag(ks + 2, slot); __builtin_amdgcn_sched_barrier(0); }
;       }
.Lrot666_loop:
	s_add_i32 s18, s17, 0xffff8000
	s_and_b32 s18, s18, 0x8000
	s_lshl_b32 s18, s18, 1
	v_lshl_or_b32 v128, v143, 1, s18
	v_lshl_add_u32 v166, v147, 1, s18
	s_and_b32 s98, s17, 0x8000
	s_lshl_b32 s98, s98, 1
	s_waitcnt lgkmcnt(7)
	v_mfma_f32_32x32x16_bf16 v[112:127], v[162:165], v[180:183], v[112:127]
	v_add3_u32 v148, s98, v224, v156
	s_waitcnt lgkmcnt(6)
	v_mfma_f32_32x32x16_bf16 v[48:63], v[162:165], v[184:187], v[48:63]
	v_readfirstlane_b32 s100, v148
	s_mov_b32 s19, m0
	s_add_i32 m0, s100, 0x8000
	s_nop 0
	global_load_lds_dwordx4 v[160:161], off
	v_mfma_f32_32x32x16_bf16 v[96:111], v[168:171], v[180:183], v[96:111]
	v_mfma_f32_32x32x16_bf16 v[32:47], v[168:171], v[184:187], v[32:47]
	v_lshl_add_u64 v[162:163], v[160:161], 0, s[4:5]
	s_add_i32 m0, s100, 0xa000
	s_nop 0
	global_load_lds_dwordx4 v[162:163], off
	v_mfma_f32_32x32x16_bf16 v[80:95], v[172:175], v[180:183], v[80:95]
	v_mfma_f32_32x32x16_bf16 v[16:31], v[172:175], v[184:187], v[16:31]
	v_lshl_add_u64 v[164:165], v[160:161], 0, s[6:7]
	s_add_i32 m0, s100, 0xc000
	s_nop 0
	global_load_lds_dwordx4 v[164:165], off
	v_mfma_f32_32x32x16_bf16 v[64:79], v[176:179], v[180:183], v[64:79]
	v_mfma_f32_32x32x16_bf16 v[0:15], v[176:179], v[184:187], v[0:15]
	v_lshl_add_u64 v[162:163], v[160:161], 0, s[8:9]
	s_add_i32 m0, s100, 0xe000
	s_nop 0
	global_load_lds_dwordx4 v[162:163], off
	s_mov_b32 m0, s19
	v_lshl_add_u64 v[160:161], v[160:161], 0, s[10:11]
	v_add_u32_e32 v176, v128, v236
	ds_read_b128 v[162:165], v176
	ds_read_b128 v[168:171], v176 offset:4096
	ds_read_b128 v[172:175], v176 offset:8192
	ds_read_b128 v[176:179], v176 offset:12288
	v_add_u32_e32 v184, v166, v236
	ds_read_b128 v[180:183], v184 offset:32768
	ds_read_b128 v[184:187], v184 offset:36864
	s_waitcnt lgkmcnt(7)
	v_mfma_f32_32x32x16_bf16 v[112:127], v[188:191], v[204:207], v[112:127]
	s_waitcnt lgkmcnt(6)
	v_mfma_f32_32x32x16_bf16 v[48:63], v[188:191], v[208:211], v[48:63]
	v_mfma_f32_32x32x16_bf16 v[96:111], v[192:195], v[204:207], v[96:111]
	v_mfma_f32_32x32x16_bf16 v[32:47], v[192:195], v[208:211], v[32:47]
	v_mfma_f32_32x32x16_bf16 v[80:95], v[196:199], v[204:207], v[80:95]
	v_mfma_f32_32x32x16_bf16 v[16:31], v[196:199], v[208:211], v[16:31]
	v_mfma_f32_32x32x16_bf16 v[64:79], v[200:203], v[204:207], v[64:79]
	v_mfma_f32_32x32x16_bf16 v[0:15], v[200:203], v[208:211], v[0:15]
	v_add_u32_e32 v128, v128, v237
	ds_read_b128 v[188:191], v128
	ds_read_b128 v[192:195], v128 offset:4096
	ds_read_b128 v[196:199], v128 offset:8192
	ds_read_b128 v[200:203], v128 offset:12288
	v_add_u32_e32 v128, v166, v237
	ds_read_b128 v[204:207], v128 offset:32768
	ds_read_b128 v[208:211], v128 offset:36864
	s_waitcnt lgkmcnt(7)
	v_mfma_f32_32x32x16_bf16 v[112:127], v[162:165], v[180:183], v[112:127]
	s_waitcnt lgkmcnt(6)
	v_mfma_f32_32x32x16_bf16 v[48:63], v[162:165], v[184:187], v[48:63]
	v_mfma_f32_32x32x16_bf16 v[96:111], v[168:171], v[180:183], v[96:111]
	v_mfma_f32_32x32x16_bf16 v[32:47], v[168:171], v[184:187], v[32:47]
	v_mfma_f32_32x32x16_bf16 v[80:95], v[172:175], v[180:183], v[80:95]
	v_mfma_f32_32x32x16_bf16 v[16:31], v[172:175], v[184:187], v[16:31]
	v_mfma_f32_32x32x16_bf16 v[64:79], v[176:179], v[180:183], v[64:79]
	v_mfma_f32_32x32x16_bf16 v[0:15], v[176:179], v[184:187], v[0:15]
	s_waitcnt vmcnt(0) lgkmcnt(0)
	s_barrier
	v_lshl_or_b32 v212, v143, 1, s98
	v_lshl_add_u32 v213, v147, 1, s98
	v_add_u32_e32 v149, v212, v234
	v_add_u32_e32 v148, v213, v234
	ds_read_b128 v[162:165], v149
	ds_read_b128 v[168:171], v149 offset:4096
	ds_read_b128 v[172:175], v149 offset:8192
	ds_read_b128 v[176:179], v149 offset:12288
	ds_read_b128 v[180:183], v148 offset:32768
	ds_read_b128 v[184:187], v148 offset:36864
	v_add3_u32 v148, s18, v224, v156
	v_mfma_f32_32x32x16_bf16 v[112:127], v[188:191], v[204:207], v[112:127]
	v_readfirstlane_b32 s99, v148
	s_mov_b32 s19, m0
	s_mov_b32 m0, s99
	s_nop 0
	global_load_lds_dwordx4 v[158:159], off
	v_mfma_f32_32x32x16_bf16 v[48:63], v[188:191], v[208:211], v[48:63]
	v_mfma_f32_32x32x16_bf16 v[96:111], v[192:195], v[204:207], v[96:111]
	v_lshl_add_u64 v[188:189], v[158:159], 0, s[4:5]
	s_add_i32 m0, s99, 0x2000
	s_nop 0
	global_load_lds_dwordx4 v[188:189], off
	v_mfma_f32_32x32x16_bf16 v[32:47], v[192:195], v[208:211], v[32:47]
	v_mfma_f32_32x32x16_bf16 v[80:95], v[196:199], v[204:207], v[80:95]
	v_lshl_add_u64 v[190:191], v[158:159], 0, s[6:7]
	s_add_i32 m0, s99, 0x4000
	s_nop 0
	global_load_lds_dwordx4 v[190:191], off
	v_mfma_f32_32x32x16_bf16 v[16:31], v[196:199], v[208:211], v[16:31]
	v_mfma_f32_32x32x16_bf16 v[64:79], v[200:203], v[204:207], v[64:79]
	v_lshl_add_u64 v[188:189], v[158:159], 0, s[8:9]
	s_add_i32 m0, s99, 0x6000
	s_nop 0
	global_load_lds_dwordx4 v[188:189], off
	s_mov_b32 m0, s19
	v_mfma_f32_32x32x16_bf16 v[0:15], v[200:203], v[208:211], v[0:15]
	v_add_u32_e32 v149, v212, v235
	v_add_u32_e32 v148, v213, v235
	ds_read_b128 v[188:191], v149
	ds_read_b128 v[192:195], v149 offset:4096
	ds_read_b128 v[196:199], v149 offset:8192
	ds_read_b128 v[200:203], v149 offset:12288
	ds_read_b128 v[204:207], v148 offset:32768
	ds_read_b128 v[208:211], v148 offset:36864
	s_add_i32 s17, s17, 0x8000
	v_lshl_add_u64 v[158:159], v[158:159], 0, s[10:11]
	s_cmp_eq_u32 s17, 0xf8000
	s_cbranch_scc0 .Lrot666_loop
; template <int EPI, int PN>
; __device__ void gemm_phase(const Params& p, const u16* __restrict__ A, const u16* __restrict__ Bt, int nNt, char* smem) {
;     ...
;     for (int kt = 0; kt < 32; ++kt) {
;       asm volatile("s_waitcnt vmcnt(0)" ::: "memory");
;       __builtin_amdgcn_s_barrier();
;       const u16* Ab = ring + (kt & 1) * STG;
;       const u16* Bb = Ab + 16384;
;       u16* st = ring + ((kt + 1) & 1) * STG;
;       const bool pre = (kt + 1 < 32);
;       s16x8 af[2][4], bf[2][2];
;       auto ldfrag = [&](int ks, int slot) {
; #pragma unroll
;         for (int i = 0; i < 4; ++i) {
;           const int row = wr * 128 + i * 32 + lr;
;           af[slot][i] = *(const s16x8*)(Ab + row * 64 + (((ks * 2 + lh) ^ ((row >> 1) & 7)) * 8));
;         }
; #pragma unroll
;         for (int j = 0; j < 2; ++j) {
;           const int rowb = nh * 128 + wc * 64 + j * 32 + lr;
;           bf[slot][j] = *(const s16x8*)(Bb + rowb * 64 + (((ks * 2 + lh) ^ ((rowb >> 1) & 7)) * 8));
;         }
;       };
;       ldfrag(0, 0);
;       ldfrag(1, 1);
;       __builtin_amdgcn_sched_barrier(0);
; #pragma unroll
;       for (int ks = 0; ks < 4; ++ks) {
;         const int slot = ks & 1;
; #pragma unroll
;         for (int i = 0; i < 4; ++i) {
;           acc[i][0] = mfma32(af[slot][i], bf[slot][0], acc[i][0]);
;           acc[i][1] = mfma32(af[slot][i], bf[slot][1], acc[i][1]);
;           __builtin_amdgcn_sched_barrier(0);
;           if (pre && (i & 1) == 0) {
;             const int pi = ks * 2 + (i >> 1);
;             if (pi < 4) glds16(Ag0 + (size_t)pi * 64 * LDK + (kt + 1) * 64, st + (srow + 64 * pi) * 64 + sch * 8);
;             else glds16(Bg0 + (size_t)(pi - 4) * 64 * LDK + (kt + 1) * 64, st + 16384 + (srow + 64 * (pi - 4)) * 64 + sch * 8);
;             __builtin_amdgcn_sched_barrier(0);
;           }
;         }
;         if (ks + 2 < 4) { ldfrag(ks + 2, slot); __builtin_amdgcn_sched_barrier(0); }
;       }
	s_add_i32 s18, s17, 0xffff8000
	s_and_b32 s18, s18, 0x8000
	s_lshl_b32 s18, s18, 1
	v_lshl_or_b32 v128, v143, 1, s18
	v_lshl_add_u32 v166, v147, 1, s18
	s_and_b32 s98, s17, 0x8000
	s_lshl_b32 s98, s98, 1
	s_waitcnt lgkmcnt(7)
	v_mfma_f32_32x32x16_bf16 v[112:127], v[162:165], v[180:183], v[112:127]
	v_add3_u32 v148, s98, v224, v156
	s_waitcnt lgkmcnt(6)
	v_mfma_f32_32x32x16_bf16 v[48:63], v[162:165], v[184:187], v[48:63]
	v_readfirstlane_b32 s100, v148
	s_mov_b32 s19, m0
	s_add_i32 m0, s100, 0x8000
	s_nop 0
	global_load_lds_dwordx4 v[160:161], off
	v_mfma_f32_32x32x16_bf16 v[96:111], v[168:171], v[180:183], v[96:111]
	v_mfma_f32_32x32x16_bf16 v[32:47], v[168:171], v[184:187], v[32:47]
	v_lshl_add_u64 v[162:163], v[160:161], 0, s[4:5]
	s_add_i32 m0, s100, 0xa000
	s_nop 0
	global_load_lds_dwordx4 v[162:163], off
	v_mfma_f32_32x32x16_bf16 v[80:95], v[172:175], v[180:183], v[80:95]
	v_mfma_f32_32x32x16_bf16 v[16:31], v[172:175], v[184:187], v[16:31]
	v_lshl_add_u64 v[164:165], v[160:161], 0, s[6:7]
	s_add_i32 m0, s100, 0xc000
	s_nop 0
	global_load_lds_dwordx4 v[164:165], off
	v_mfma_f32_32x32x16_bf16 v[64:79], v[176:179], v[180:183], v[64:79]
	v_mfma_f32_32x32x16_bf16 v[0:15], v[176:179], v[184:187], v[0:15]
	v_lshl_add_u64 v[162:163], v[160:161], 0, s[8:9]
	s_add_i32 m0, s100, 0xe000
	s_nop 0
	global_load_lds_dwordx4 v[162:163], off
	s_mov_b32 m0, s19
	v_lshl_add_u64 v[160:161], v[160:161], 0, s[10:11]
	v_add_u32_e32 v176, v128, v236
	ds_read_b128 v[162:165], v176
	ds_read_b128 v[168:171], v176 offset:4096
	ds_read_b128 v[172:175], v176 offset:8192
	ds_read_b128 v[176:179], v176 offset:12288
	v_add_u32_e32 v184, v166, v236
	ds_read_b128 v[180:183], v184 offset:32768
	ds_read_b128 v[184:187], v184 offset:36864
	s_waitcnt lgkmcnt(7)
	v_mfma_f32_32x32x16_bf16 v[112:127], v[188:191], v[204:207], v[112:127]
	s_waitcnt lgkmcnt(6)
	v_mfma_f32_32x32x16_bf16 v[48:63], v[188:191], v[208:211], v[48:63]
	v_mfma_f32_32x32x16_bf16 v[96:111], v[192:195], v[204:207], v[96:111]
	v_mfma_f32_32x32x16_bf16 v[32:47], v[192:195], v[208:211], v[32:47]
	v_mfma_f32_32x32x16_bf16 v[80:95], v[196:199], v[204:207], v[80:95]
	v_mfma_f32_32x32x16_bf16 v[16:31], v[196:199], v[208:211], v[16:31]
	v_mfma_f32_32x32x16_bf16 v[64:79], v[200:203], v[204:207], v[64:79]
	v_mfma_f32_32x32x16_bf16 v[0:15], v[200:203], v[208:211], v[0:15]
	v_add_u32_e32 v128, v128, v237
	ds_read_b128 v[188:191], v128
	ds_read_b128 v[192:195], v128 offset:4096
	ds_read_b128 v[196:199], v128 offset:8192
	ds_read_b128 v[200:203], v128 offset:12288
	v_add_u32_e32 v128, v166, v237
	ds_read_b128 v[204:207], v128 offset:32768
	ds_read_b128 v[208:211], v128 offset:36864
	s_waitcnt lgkmcnt(7)
	v_mfma_f32_32x32x16_bf16 v[112:127], v[162:165], v[180:183], v[112:127]
	s_waitcnt lgkmcnt(6)
	v_mfma_f32_32x32x16_bf16 v[48:63], v[162:165], v[184:187], v[48:63]
	v_mfma_f32_32x32x16_bf16 v[96:111], v[168:171], v[180:183], v[96:111]
	v_mfma_f32_32x32x16_bf16 v[32:47], v[168:171], v[184:187], v[32:47]
	v_mfma_f32_32x32x16_bf16 v[80:95], v[172:175], v[180:183], v[80:95]
	v_mfma_f32_32x32x16_bf16 v[16:31], v[172:175], v[184:187], v[16:31]
	v_mfma_f32_32x32x16_bf16 v[64:79], v[176:179], v[180:183], v[64:79]
	v_mfma_f32_32x32x16_bf16 v[0:15], v[176:179], v[184:187], v[0:15]
	s_waitcnt lgkmcnt(1)
	v_mfma_f32_32x32x16_bf16 v[112:127], v[188:191], v[204:207], v[112:127]
	s_waitcnt lgkmcnt(0)
	v_mfma_f32_32x32x16_bf16 v[48:63], v[188:191], v[208:211], v[48:63]
	v_mfma_f32_32x32x16_bf16 v[96:111], v[192:195], v[204:207], v[96:111]
	v_mfma_f32_32x32x16_bf16 v[32:47], v[192:195], v[208:211], v[32:47]
	v_mfma_f32_32x32x16_bf16 v[80:95], v[196:199], v[204:207], v[80:95]
	v_mfma_f32_32x32x16_bf16 v[16:31], v[196:199], v[208:211], v[16:31]
	v_mfma_f32_32x32x16_bf16 v[64:79], v[200:203], v[204:207], v[64:79]
	v_mfma_f32_32x32x16_bf16 v[0:15], v[200:203], v[208:211], v[0:15]
	s_waitcnt vmcnt(0)
	s_barrier
	ds_read_b128 v[158:161], v226
	ds_read_b128 v[162:165], v226 offset:4096
	ds_read_b128 v[168:171], v226 offset:8192
	ds_read_b128 v[172:175], v226 offset:12288
	ds_read_b128 v[176:179], v227
	ds_read_b128 v[180:183], v227 offset:4096
	ds_read_b128 v[184:187], v228
	ds_read_b128 v[188:191], v228 offset:4096
	ds_read_b128 v[192:195], v228 offset:8192
	ds_read_b128 v[196:199], v228 offset:12288
	ds_read_b128 v[200:203], v229
	ds_read_b128 v[204:207], v229 offset:4096
	s_waitcnt lgkmcnt(7)
	v_mfma_f32_32x32x16_bf16 v[112:127], v[158:161], v[176:179], v[112:127]
	s_waitcnt lgkmcnt(6)
	v_mfma_f32_32x32x16_bf16 v[48:63], v[158:161], v[180:183], v[48:63]
	v_mfma_f32_32x32x16_bf16 v[96:111], v[162:165], v[176:179], v[96:111]
	v_mfma_f32_32x32x16_bf16 v[32:47], v[162:165], v[180:183], v[32:47]
	v_mfma_f32_32x32x16_bf16 v[80:95], v[168:171], v[176:179], v[80:95]
	v_mfma_f32_32x32x16_bf16 v[16:31], v[168:171], v[180:183], v[16:31]
	v_mfma_f32_32x32x16_bf16 v[64:79], v[172:175], v[176:179], v[64:79]
	v_mfma_f32_32x32x16_bf16 v[0:15], v[172:175], v[180:183], v[0:15]
	ds_read_b128 v[158:161], v230
	ds_read_b128 v[162:165], v230 offset:4096
	ds_read_b128 v[168:171], v230 offset:8192
	ds_read_b128 v[172:175], v230 offset:12288
	ds_read_b128 v[176:179], v231
	ds_read_b128 v[180:183], v231 offset:4096
	s_waitcnt lgkmcnt(7)
	v_mfma_f32_32x32x16_bf16 v[112:127], v[184:187], v[200:203], v[112:127]
	s_waitcnt lgkmcnt(6)
; __device__ __forceinline__ int accrow(int reg, int lh) { return (reg & 3) + 8 * (reg >> 2) + 4 * lh; }
; template <int EPI, int PN>
; __device__ void gemm_phase(const Params& p, const u16* __restrict__ A, const u16* __restrict__ Bt, int nNt, char* smem) {
;     ...
;     __syncthreads();
;     int mte = __builtin_amdgcn_readfirstlane(mt), nte = __builtin_amdgcn_readfirstlane(nt), lrE = lr, lhE = lh, laneE = lane;
;     asm volatile("" : "+s"(mte), "+s"(nte), "+v"(lrE), "+v"(lhE), "+v"(laneE));
;     unsigned char* et = (unsigned char*)smem + wv * 18432;
;     const int col0 = nte * 256 + nh * 128 + wc * 64;
;     const size_t row0 = (size_t)mte * 256 + wr * 128;
;     if (EPI == 1) {
; #pragma unroll
;       for (int j = 0; j < 2; ++j) {
; #pragma unroll
;         for (int i = 0; i < 4; ++i)
; #pragma unroll
;           for (int r = 0; r < 16; ++r) *(float*)(et + (i * 32 + accrow(r, lhE)) * 144 + lrE * 4) = acc[i][j][r];
; #pragma unroll
;         for (int it = 0; it < 16; ++it) {
;           const int c = it * 64 + laneE, row = c >> 3, seg = c & 7;
;           const float4 v = *(const float4*)(et + row * 144 + seg * 16);
;           const size_t g = (row0 + row) * DM + col0 + j * 32 + seg * 4;
;           const float4 xv = *(const float4*)(p.x + g);
	v_mfma_f32_32x32x16_bf16 v[48:63], v[184:187], v[204:207], v[48:63]
	v_mfma_f32_32x32x16_bf16 v[96:111], v[188:191], v[200:203], v[96:111]
	v_mfma_f32_32x32x16_bf16 v[32:47], v[188:191], v[204:207], v[32:47]
	v_mfma_f32_32x32x16_bf16 v[80:95], v[192:195], v[200:203], v[80:95]
	v_mfma_f32_32x32x16_bf16 v[16:31], v[192:195], v[204:207], v[16:31]
	v_mfma_f32_32x32x16_bf16 v[64:79], v[196:199], v[200:203], v[64:79]
	v_mfma_f32_32x32x16_bf16 v[0:15], v[196:199], v[204:207], v[0:15]
	ds_read_b128 v[184:187], v232
	ds_read_b128 v[188:191], v232 offset:4096
	ds_read_b128 v[192:195], v232 offset:8192
	ds_read_b128 v[196:199], v232 offset:12288
	ds_read_b128 v[200:203], v233
	ds_read_b128 v[204:207], v233 offset:4096
	s_waitcnt lgkmcnt(7)
	v_mfma_f32_32x32x16_bf16 v[112:127], v[158:161], v[176:179], v[112:127]
	s_waitcnt lgkmcnt(6)
	v_mfma_f32_32x32x16_bf16 v[48:63], v[158:161], v[180:183], v[48:63]
	v_mfma_f32_32x32x16_bf16 v[96:111], v[162:165], v[176:179], v[96:111]
	v_mfma_f32_32x32x16_bf16 v[32:47], v[162:165], v[180:183], v[32:47]
	v_mfma_f32_32x32x16_bf16 v[80:95], v[168:171], v[176:179], v[80:95]
	v_mfma_f32_32x32x16_bf16 v[16:31], v[168:171], v[180:183], v[16:31]
	v_mfma_f32_32x32x16_bf16 v[64:79], v[172:175], v[176:179], v[64:79]
	v_mfma_f32_32x32x16_bf16 v[0:15], v[172:175], v[180:183], v[0:15]
	s_waitcnt lgkmcnt(1)
	v_mfma_f32_32x32x16_bf16 v[112:127], v[184:187], v[200:203], v[112:127]
	s_waitcnt lgkmcnt(0)
	v_mfma_f32_32x32x16_bf16 v[48:63], v[184:187], v[204:207], v[48:63]
	v_mfma_f32_32x32x16_bf16 v[96:111], v[188:191], v[200:203], v[96:111]
	v_mfma_f32_32x32x16_bf16 v[32:47], v[188:191], v[204:207], v[32:47]
	v_mfma_f32_32x32x16_bf16 v[80:95], v[192:195], v[200:203], v[80:95]
	v_mfma_f32_32x32x16_bf16 v[16:31], v[192:195], v[204:207], v[16:31]
	v_mfma_f32_32x32x16_bf16 v[64:79], v[196:199], v[200:203], v[64:79]
	v_mfma_f32_32x32x16_bf16 v[0:15], v[196:199], v[204:207], v[0:15]
	v_mov_b32_e32 v128, v139
	v_mov_b32_e32 v148, v137
	v_mov_b32_e32 v218, v135
	s_barrier
	v_readlane_b32 s52, v253, 7
	v_lshl_add_u32 v172, s13, 8, v145
	s_ashr_i32 s13, s12, 31
	s_lshl_b64 s[12:13], s[12:13], 8
	v_ashrrev_i32_e32 v158, 3, v218
	v_mov_b32_e32 v163, s13
	v_or_b32_e32 v162, s12, v134
	v_ashrrev_i32_e32 v159, 31, v158
	v_and_b32_e32 v149, 7, v218
	v_ashrrev_i32_e32 v173, 31, v172
	v_lshl_add_u64 v[174:175], v[162:163], 0, v[158:159]
	v_lshl_or_b32 v164, v149, 2, v172
	v_mov_b32_e32 v165, v173
	v_lshlrev_b64 v[160:161], 11, v[174:175]
	v_lshl_add_u64 v[160:161], v[160:161], 0, v[164:165]
	v_lshlrev_b64 v[176:177], 2, v[160:161]
	v_readlane_b32 s53, v253, 8
	v_lshl_add_u32 v166, v149, 4, v225
	v_lshlrev_b32_e32 v148, 2, v148
	v_lshl_add_u64 v[160:161], s[52:53], 0, v[176:177]
	global_load_dwordx4 v[168:171], v[160:161], off
	v_mad_u64_u32 v[158:159], s[12:13], v158, s14, v[166:167]
	v_mul_lo_u32 v128, v128, s15
	v_add3_u32 v159, v225, v148, v128
	ds_write_b32 v159, v112
	ds_write_b32 v159, v113 offset:144
	ds_write_b32 v159, v114 offset:288
	ds_write_b32 v159, v115 offset:432
	ds_write_b32 v159, v116 offset:1152
	ds_write_b32 v159, v117 offset:1296
	ds_write_b32 v159, v118 offset:1440
	ds_write_b32 v159, v119 offset:1584
	ds_write_b32 v159, v120 offset:2304
	ds_write_b32 v159, v121 offset:2448
	ds_write_b32 v159, v122 offset:2592
	ds_write_b32 v159, v123 offset:2736
	ds_write_b32 v159, v124 offset:3456
	ds_write_b32 v159, v125 offset:3600
	ds_write_b32 v159, v126 offset:3744
	ds_write_b32 v159, v127 offset:3888
	ds_write_b32 v159, v96 offset:4608
	ds_write_b32 v159, v97 offset:4752
	ds_write_b32 v159, v98 offset:4896
	ds_write_b32 v159, v99 offset:5040
	ds_write_b32 v159, v100 offset:5760
	ds_write_b32 v159, v101 offset:5904
	ds_write_b32 v159, v102 offset:6048
	ds_write_b32 v159, v103 offset:6192
	ds_write_b32 v159, v104 offset:6912
	ds_write_b32 v159, v105 offset:7056
	ds_write_b32 v159, v106 offset:7200
	ds_write_b32 v159, v107 offset:7344
	ds_write_b32 v159, v108 offset:8064
	ds_write_b32 v159, v109 offset:8208
	ds_write_b32 v159, v110 offset:8352
	ds_write_b32 v159, v111 offset:8496
	ds_write_b32 v159, v80 offset:9216
	ds_write_b32 v159, v81 offset:9360
	ds_write_b32 v159, v82 offset:9504
	ds_write_b32 v159, v83 offset:9648
	ds_write_b32 v159, v84 offset:10368
	ds_write_b32 v159, v85 offset:10512
	ds_write_b32 v159, v86 offset:10656
	ds_write_b32 v159, v87 offset:10800
	ds_write_b32 v159, v88 offset:11520
	ds_write_b32 v159, v89 offset:11664
	ds_write_b32 v159, v90 offset:11808
	ds_write_b32 v159, v91 offset:11952
	ds_write_b32 v159, v92 offset:12672
	ds_write_b32 v159, v93 offset:12816
	ds_write_b32 v159, v94 offset:12960
	ds_write_b32 v159, v95 offset:13104
	ds_write_b32 v159, v64 offset:13824
	ds_write_b32 v159, v65 offset:13968
	ds_write_b32 v159, v66 offset:14112
	ds_write_b32 v159, v67 offset:14256
	ds_write_b32 v159, v68 offset:14976
	ds_write_b32 v159, v69 offset:15120
	ds_write_b32 v159, v70 offset:15264
	ds_write_b32 v159, v71 offset:15408
	ds_write_b32 v159, v72 offset:16128
	ds_write_b32 v159, v73 offset:16272
	ds_write_b32 v159, v74 offset:16416
	ds_write_b32 v159, v75 offset:16560
	ds_write_b32 v159, v76 offset:17280
	ds_write_b32 v159, v77 offset:17424
	ds_write_b32 v159, v78 offset:17568
	ds_write_b32 v159, v79 offset:17712
	ds_read_b128 v[66:69], v158
	v_readlane_b32 s36, v253, 23
	v_readlane_b32 s40, v253, 27
	v_readlane_b32 s41, v253, 28
	v_readlane_b32 s42, v253, 29
	v_readlane_b32 s43, v253, 30
	s_mov_b64 s[20:21], s[40:41]
	s_mov_b64 s[22:23], s[42:43]
	v_lshl_add_u64 v[64:65], s[20:21], 0, v[176:177]
	v_mov_b64_e32 v[102:103], s[22:23]
	v_lshlrev_b64 v[104:105], 1, v[172:173]
	v_lshlrev_b32_e32 v128, 3, v149
	v_readlane_b32 s54, v253, 9
	v_readlane_b32 s55, v253, 10
	v_readlane_b32 s56, v253, 11
	v_readlane_b32 s57, v253, 12
	v_readlane_b32 s58, v253, 13
	v_readlane_b32 s59, v253, 14
	v_readlane_b32 s60, v253, 15
	v_readlane_b32 s61, v253, 16
	v_readlane_b32 s62, v253, 17
	v_readlane_b32 s63, v253, 18
	v_readlane_b32 s64, v253, 19
	v_readlane_b32 s65, v253, 20
	v_readlane_b32 s66, v253, 21
	v_readlane_b32 s67, v253, 22
	v_readlane_b32 s37, v253, 24
	v_readlane_b32 s38, v253, 25
	v_readlane_b32 s39, v253, 26
	v_readlane_b32 s44, v253, 31
	v_readlane_b32 s45, v253, 32
	v_readlane_b32 s46, v253, 33
	v_readlane_b32 s47, v253, 34
	v_readlane_b32 s48, v253, 35
	v_readlane_b32 s49, v253, 36
	v_readlane_b32 s50, v253, 37
	v_readlane_b32 s51, v253, 38
	s_waitcnt vmcnt(0) lgkmcnt(0)
; template <int EPI, int PN>
; __device__ void gemm_phase(const Params& p, const u16* __restrict__ A, const u16* __restrict__ Bt, int nNt, char* smem) {
;     ...
;         for (int it = 0; it < 16; ++it) {
;           const int c = it * 64 + laneE, row = c >> 3, seg = c & 7;
;           const float4 v = *(const float4*)(et + row * 144 + seg * 16);
;           const size_t g = (row0 + row) * DM + col0 + j * 32 + seg * 4;
;           const float4 xv = *(const float4*)(p.x + g);
;           const float4 hv = make_float4(xv.x + v.x, xv.y + v.y, xv.z + v.z, xv.w + v.w);
;           *(float4*)(p.out + g) = hv;
;           uint2 hb; hb.x = pack2(hv.x, hv.y); hb.y = pack2(hv.z, hv.w);
;           *(uint2*)(p.xn + (row0 + row) * LDK + col0 + j * 32 + seg * 4) = hb;
	v_pk_add_f32 v[66:67], v[66:67], v[168:169]
	v_pk_add_f32 v[68:69], v[68:69], v[170:171]
	global_store_dwordx4 v[64:65], v[66:69], off
	v_cvt_pk_bf16_f32 v70, v66, v67
	v_cvt_pk_bf16_f32 v71, v68, v69
	v_mad_u64_u32 v[66:67], s[12:13], v174, s2, v[102:103]
	v_mad_i32_i24 v67, v175, s2, v67
	v_lshl_add_u64 v[66:67], v[66:67], 0, v[104:105]
	v_lshl_add_u64 v[66:67], v[66:67], 0, v[128:129]
	v_add_u32_e32 v68, 64, v218
	global_store_dwordx2 v[66:67], v[70:71], off
	v_ashrrev_i32_e32 v70, 3, v68
	v_ashrrev_i32_e32 v71, 31, v70
	v_lshl_add_u64 v[74:75], v[162:163], 0, v[70:71]
	v_lshlrev_b64 v[68:69], 11, v[74:75]
	v_lshl_add_u64 v[68:69], v[68:69], 0, v[164:165]
	v_lshlrev_b64 v[76:77], 2, v[68:69]
	v_lshl_add_u64 v[68:69], s[52:53], 0, v[76:77]
	global_load_dwordx4 v[78:81], v[68:69], off
	v_mad_u64_u32 v[72:73], s[12:13], v70, s14, v[166:167]
	v_add_u32_e32 v71, 0x80, v218
	ds_read_b128 v[82:85], v72
	v_ashrrev_i32_e32 v90, 3, v71
	v_ashrrev_i32_e32 v91, 31, v90
	v_lshl_add_u64 v[94:95], v[162:163], 0, v[90:91]
	v_mad_u64_u32 v[70:71], s[12:13], v74, s2, v[102:103]
	v_lshlrev_b64 v[86:87], 11, v[94:95]
	v_mad_i32_i24 v71, v75, s2, v71
	v_lshl_add_u64 v[74:75], v[86:87], 0, v[164:165]
	v_lshl_add_u64 v[70:71], v[70:71], 0, v[104:105]
	v_lshl_add_u64 v[76:77], s[20:21], 0, v[76:77]
	v_lshlrev_b64 v[96:97], 2, v[74:75]
	v_lshl_add_u64 v[74:75], v[70:71], 0, v[128:129]
	v_lshl_add_u64 v[70:71], s[52:53], 0, v[96:97]
	v_add_u32_e32 v73, 0xc0, v218
	v_ashrrev_i32_e32 v98, 3, v73
	v_ashrrev_i32_e32 v99, 31, v98
	v_lshl_add_u64 v[106:107], v[162:163], 0, v[98:99]
	v_add_u32_e32 v73, 0x100, v218
	v_ashrrev_i32_e32 v110, 3, v73
	v_ashrrev_i32_e32 v111, 31, v110
	v_lshl_add_u64 v[114:115], v[162:163], 0, v[110:111]
	v_add_u32_e32 v73, 0x140, v218
	v_ashrrev_i32_e32 v118, 3, v73
	v_ashrrev_i32_e32 v119, 31, v118
	v_lshl_add_u64 v[122:123], v[162:163], 0, v[118:119]
	v_add_u32_e32 v73, 0x180, v218
	v_ashrrev_i32_e32 v126, 3, v73
	v_ashrrev_i32_e32 v127, 31, v126
	v_lshl_add_u64 v[172:173], v[162:163], 0, v[126:127]
	v_add_u32_e32 v73, 0x1c0, v218
	v_ashrrev_i32_e32 v176, 3, v73
	v_ashrrev_i32_e32 v177, 31, v176
	v_add_u32_e32 v73, 0x200, v218
	v_ashrrev_i32_e32 v182, 3, v73
	v_ashrrev_i32_e32 v183, 31, v182
	v_lshl_add_u64 v[186:187], v[162:163], 0, v[182:183]
	v_add_u32_e32 v73, 0x240, v218
	v_ashrrev_i32_e32 v190, 3, v73
	v_ashrrev_i32_e32 v191, 31, v190
	v_lshl_add_u64 v[194:195], v[162:163], 0, v[190:191]
	v_add_u32_e32 v73, 0x280, v218
	v_ashrrev_i32_e32 v198, 3, v73
	v_ashrrev_i32_e32 v199, 31, v198
	v_lshl_add_u64 v[202:203], v[162:163], 0, v[198:199]
	v_add_u32_e32 v73, 0x2c0, v218
	v_ashrrev_i32_e32 v206, 3, v73
	v_ashrrev_i32_e32 v207, 31, v206
	v_lshl_add_u64 v[210:211], v[162:163], 0, v[206:207]
	v_add_u32_e32 v73, 0x300, v218
	v_ashrrev_i32_e32 v214, 3, v73
	v_ashrrev_i32_e32 v215, 31, v214
	v_lshl_add_u64 v[220:221], v[162:163], 0, v[214:215]
	v_add_u32_e32 v73, 0x340, v218
	v_ashrrev_i32_e32 v238, 3, v73
	v_ashrrev_i32_e32 v239, 31, v238
	v_lshl_add_u64 v[242:243], v[162:163], 0, v[238:239]
	v_add_u32_e32 v73, 0x380, v218
	v_ashrrev_i32_e32 v246, 3, v73
	v_ashrrev_i32_e32 v247, 31, v246
	v_lshl_add_u64 v[248:249], v[162:163], 0, v[246:247]
	v_add_u32_e32 v73, 0x3c0, v218
	v_mad_u64_u32 v[218:219], s[12:13], v246, s14, v[166:167]
	v_ashrrev_i32_e32 v148, 3, v73
	v_ashrrev_i32_e32 v149, 31, v148
	v_lshl_add_u64 v[246:247], v[162:163], 0, v[148:149]
	s_waitcnt vmcnt(0) lgkmcnt(0)
	v_pk_add_f32 v[78:79], v[82:83], v[78:79]
	v_pk_add_f32 v[80:81], v[84:85], v[80:81]
	global_store_dwordx4 v[76:77], v[78:81], off
	v_lshlrev_b64 v[82:83], 11, v[106:107]
	v_lshl_add_u64 v[82:83], v[82:83], 0, v[164:165]
	v_cvt_pk_bf16_f32 v78, v78, v79
	v_cvt_pk_bf16_f32 v79, v80, v81
	global_store_dwordx2 v[74:75], v[78:79], off
	global_load_dwordx4 v[86:89], v[70:71], off
	v_mad_u64_u32 v[80:81], s[12:13], v90, s14, v[166:167]
	ds_read_b128 v[90:93], v80
	v_mad_u64_u32 v[78:79], s[12:13], v94, s2, v[102:103]
	v_mad_i32_i24 v79, v95, s2, v79
	v_lshl_add_u64 v[78:79], v[78:79], 0, v[104:105]
	v_lshl_add_u64 v[84:85], s[20:21], 0, v[96:97]
	v_lshlrev_b64 v[108:109], 2, v[82:83]
	v_lshl_add_u64 v[82:83], v[78:79], 0, v[128:129]
	v_lshl_add_u64 v[78:79], s[52:53], 0, v[108:109]
	s_waitcnt vmcnt(0) lgkmcnt(0)
	v_pk_add_f32 v[86:87], v[90:91], v[86:87]
	v_pk_add_f32 v[88:89], v[92:93], v[88:89]
	global_store_dwordx4 v[84:85], v[86:89], off
	v_lshlrev_b64 v[90:91], 11, v[114:115]
	v_lshl_add_u64 v[90:91], v[90:91], 0, v[164:165]
	v_cvt_pk_bf16_f32 v86, v86, v87
	v_cvt_pk_bf16_f32 v87, v88, v89
	global_store_dwordx2 v[82:83], v[86:87], off
	global_load_dwordx4 v[94:97], v[78:79], off
	v_mad_u64_u32 v[88:89], s[12:13], v98, s14, v[166:167]
	ds_read_b128 v[98:101], v88
	v_mad_u64_u32 v[86:87], s[12:13], v106, s2, v[102:103]
	v_mad_i32_i24 v87, v107, s2, v87
	v_lshl_add_u64 v[86:87], v[86:87], 0, v[104:105]
	v_lshl_add_u64 v[92:93], s[20:21], 0, v[108:109]
	v_lshlrev_b64 v[116:117], 2, v[90:91]
	v_lshl_add_u64 v[90:91], v[86:87], 0, v[128:129]
	v_lshl_add_u64 v[86:87], s[52:53], 0, v[116:117]
	s_waitcnt vmcnt(0) lgkmcnt(0)
	v_pk_add_f32 v[94:95], v[98:99], v[94:95]
	v_pk_add_f32 v[96:97], v[100:101], v[96:97]
	global_store_dwordx4 v[92:93], v[94:97], off
	v_lshlrev_b64 v[98:99], 11, v[122:123]
	v_lshl_add_u64 v[98:99], v[98:99], 0, v[164:165]
	v_cvt_pk_bf16_f32 v94, v94, v95
	v_cvt_pk_bf16_f32 v95, v96, v97
	global_store_dwordx2 v[90:91], v[94:95], off
	global_load_dwordx4 v[106:109], v[86:87], off
	v_mad_u64_u32 v[96:97], s[12:13], v110, s14, v[166:167]
	ds_read_b128 v[110:113], v96
	v_mad_u64_u32 v[94:95], s[12:13], v114, s2, v[102:103]
	v_mad_i32_i24 v95, v115, s2, v95
	v_lshl_add_u64 v[94:95], v[94:95], 0, v[104:105]
	v_lshl_add_u64 v[100:101], s[20:21], 0, v[116:117]
	v_lshlrev_b64 v[124:125], 2, v[98:99]
	v_lshl_add_u64 v[98:99], v[94:95], 0, v[128:129]
	v_lshl_add_u64 v[94:95], s[52:53], 0, v[124:125]
	s_waitcnt vmcnt(0) lgkmcnt(0)
; template <int EPI, int PN>
; __device__ void gemm_phase(const Params& p, const u16* __restrict__ A, const u16* __restrict__ Bt, int nNt, char* smem) {
;     ...
;         for (int it = 0; it < 16; ++it) {
;           const int c = it * 64 + laneE, row = c >> 3, seg = c & 7;
;           const float4 v = *(const float4*)(et + row * 144 + seg * 16);
;           const size_t g = (row0 + row) * DM + col0 + j * 32 + seg * 4;
;           const float4 xv = *(const float4*)(p.x + g);
;           const float4 hv = make_float4(xv.x + v.x, xv.y + v.y, xv.z + v.z, xv.w + v.w);
;           *(float4*)(p.out + g) = hv;
;           uint2 hb; hb.x = pack2(hv.x, hv.y); hb.y = pack2(hv.z, hv.w);
;           *(uint2*)(p.xn + (row0 + row) * LDK + col0 + j * 32 + seg * 4) = hb;
	v_pk_add_f32 v[106:107], v[110:111], v[106:107]
	v_pk_add_f32 v[108:109], v[112:113], v[108:109]
	global_store_dwordx4 v[100:101], v[106:109], off
	v_lshlrev_b64 v[110:111], 11, v[172:173]
	v_lshl_add_u64 v[110:111], v[110:111], 0, v[164:165]
	v_cvt_pk_bf16_f32 v106, v106, v107
	v_cvt_pk_bf16_f32 v107, v108, v109
	global_store_dwordx2 v[98:99], v[106:107], off
	global_load_dwordx4 v[114:117], v[94:95], off
	v_mad_u64_u32 v[108:109], s[12:13], v118, s14, v[166:167]
	ds_read_b128 v[118:121], v108
	v_mad_u64_u32 v[106:107], s[12:13], v122, s2, v[102:103]
	v_mad_i32_i24 v107, v123, s2, v107
	v_lshl_add_u64 v[106:107], v[106:107], 0, v[104:105]
	v_lshl_add_u64 v[112:113], s[20:21], 0, v[124:125]
	v_lshlrev_b64 v[174:175], 2, v[110:111]
	v_lshl_add_u64 v[110:111], v[106:107], 0, v[128:129]
	v_lshl_add_u64 v[106:107], s[52:53], 0, v[174:175]
	s_waitcnt vmcnt(0) lgkmcnt(0)
	v_pk_add_f32 v[114:115], v[118:119], v[114:115]
	v_pk_add_f32 v[116:117], v[120:121], v[116:117]
	global_store_dwordx4 v[112:113], v[114:117], off
	v_lshl_add_u64 v[120:121], s[20:21], 0, v[174:175]
	s_nop 0
	v_cvt_pk_bf16_f32 v114, v114, v115
	v_cvt_pk_bf16_f32 v115, v116, v117
	global_store_dwordx2 v[110:111], v[114:115], off
	global_load_dwordx4 v[122:125], v[106:107], off
	v_mad_u64_u32 v[116:117], s[12:13], v126, s14, v[166:167]
	ds_read_b128 v[168:171], v116
	v_lshl_add_u64 v[126:127], v[162:163], 0, v[176:177]
	v_mad_u64_u32 v[114:115], s[12:13], v172, s2, v[102:103]
	v_lshlrev_b64 v[118:119], 11, v[126:127]
	v_mad_i32_i24 v115, v173, s2, v115
	v_lshl_add_u64 v[118:119], v[118:119], 0, v[164:165]
	v_lshl_add_u64 v[114:115], v[114:115], 0, v[104:105]
	v_lshlrev_b64 v[178:179], 2, v[118:119]
	v_lshl_add_u64 v[118:119], v[114:115], 0, v[128:129]
	v_lshl_add_u64 v[114:115], s[52:53], 0, v[178:179]
	v_mad_u64_u32 v[162:163], s[12:13], v248, s2, v[102:103]
	v_mad_i32_i24 v163, v249, s2, v163
	v_lshl_add_u64 v[162:163], v[162:163], 0, v[104:105]
	s_waitcnt vmcnt(0) lgkmcnt(0)
	v_pk_add_f32 v[122:123], v[168:169], v[122:123]
	v_pk_add_f32 v[124:125], v[170:171], v[124:125]
	global_store_dwordx4 v[120:121], v[122:125], off
	v_lshlrev_b64 v[168:169], 11, v[186:187]
	s_nop 0
	v_cvt_pk_bf16_f32 v122, v122, v123
	v_cvt_pk_bf16_f32 v123, v124, v125
	global_store_dwordx2 v[118:119], v[122:123], off
	global_load_dwordx4 v[170:173], v[114:115], off
	v_mad_u64_u32 v[124:125], s[12:13], v176, s14, v[166:167]
	ds_read_b128 v[174:177], v124
	v_mad_u64_u32 v[122:123], s[12:13], v126, s2, v[102:103]
	v_mad_i32_i24 v123, v127, s2, v123
	v_lshl_add_u64 v[126:127], v[168:169], 0, v[164:165]
	v_lshl_add_u64 v[122:123], v[122:123], 0, v[104:105]
	v_lshl_add_u64 v[168:169], s[20:21], 0, v[178:179]
	v_lshlrev_b64 v[188:189], 2, v[126:127]
	v_lshl_add_u64 v[126:127], v[122:123], 0, v[128:129]
	v_lshl_add_u64 v[122:123], s[52:53], 0, v[188:189]
	s_waitcnt vmcnt(0) lgkmcnt(0)
	v_pk_add_f32 v[170:171], v[174:175], v[170:171]
	v_pk_add_f32 v[172:173], v[176:177], v[172:173]
	global_store_dwordx4 v[168:169], v[170:173], off
	v_lshlrev_b64 v[174:175], 11, v[194:195]
	v_lshl_add_u64 v[174:175], v[174:175], 0, v[164:165]
	v_cvt_pk_bf16_f32 v170, v170, v171
	v_cvt_pk_bf16_f32 v171, v172, v173
	global_store_dwordx2 v[126:127], v[170:171], off
	global_load_dwordx4 v[178:181], v[122:123], off
	v_mad_u64_u32 v[172:173], s[12:13], v182, s14, v[166:167]
	ds_read_b128 v[182:185], v172
	v_mad_u64_u32 v[170:171], s[12:13], v186, s2, v[102:103]
	v_mad_i32_i24 v171, v187, s2, v171
	v_lshl_add_u64 v[170:171], v[170:171], 0, v[104:105]
	v_lshl_add_u64 v[176:177], s[20:21], 0, v[188:189]
	v_lshlrev_b64 v[196:197], 2, v[174:175]
	v_lshl_add_u64 v[174:175], v[170:171], 0, v[128:129]
	v_lshl_add_u64 v[170:171], s[52:53], 0, v[196:197]
	s_waitcnt vmcnt(0) lgkmcnt(0)
	v_pk_add_f32 v[178:179], v[182:183], v[178:179]
	v_pk_add_f32 v[180:181], v[184:185], v[180:181]
	global_store_dwordx4 v[176:177], v[178:181], off
	v_lshlrev_b64 v[182:183], 11, v[202:203]
	v_lshl_add_u64 v[182:183], v[182:183], 0, v[164:165]
	v_cvt_pk_bf16_f32 v178, v178, v179
	v_cvt_pk_bf16_f32 v179, v180, v181
	global_store_dwordx2 v[174:175], v[178:179], off
	global_load_dwordx4 v[186:189], v[170:171], off
	v_mad_u64_u32 v[180:181], s[12:13], v190, s14, v[166:167]
	ds_read_b128 v[190:193], v180
	v_mad_u64_u32 v[178:179], s[12:13], v194, s2, v[102:103]
	v_mad_i32_i24 v179, v195, s2, v179
	v_lshl_add_u64 v[178:179], v[178:179], 0, v[104:105]
	v_lshl_add_u64 v[184:185], s[20:21], 0, v[196:197]
	v_lshlrev_b64 v[204:205], 2, v[182:183]
	v_lshl_add_u64 v[182:183], v[178:179], 0, v[128:129]
	v_lshl_add_u64 v[178:179], s[52:53], 0, v[204:205]
	s_waitcnt vmcnt(0) lgkmcnt(0)
	v_pk_add_f32 v[186:187], v[190:191], v[186:187]
	v_pk_add_f32 v[188:189], v[192:193], v[188:189]
	global_store_dwordx4 v[184:185], v[186:189], off
	v_lshlrev_b64 v[190:191], 11, v[210:211]
	v_lshl_add_u64 v[190:191], v[190:191], 0, v[164:165]
	v_cvt_pk_bf16_f32 v186, v186, v187
	v_cvt_pk_bf16_f32 v187, v188, v189
	global_store_dwordx2 v[182:183], v[186:187], off
	global_load_dwordx4 v[194:197], v[178:179], off
	v_mad_u64_u32 v[188:189], s[12:13], v198, s14, v[166:167]
	ds_read_b128 v[198:201], v188
	v_mad_u64_u32 v[186:187], s[12:13], v202, s2, v[102:103]
	v_mad_i32_i24 v187, v203, s2, v187
	v_lshl_add_u64 v[186:187], v[186:187], 0, v[104:105]
	v_lshl_add_u64 v[192:193], s[20:21], 0, v[204:205]
	v_lshlrev_b64 v[212:213], 2, v[190:191]
	v_lshl_add_u64 v[190:191], v[186:187], 0, v[128:129]
	v_lshl_add_u64 v[186:187], s[52:53], 0, v[212:213]
	s_waitcnt vmcnt(0) lgkmcnt(0)
; template <int EPI, int PN>
; __device__ void gemm_phase(const Params& p, const u16* __restrict__ A, const u16* __restrict__ Bt, int nNt, char* smem) {
;     ...
;   for (int q = jb;; q += NJ) {
;     const int pl = q / (4 * PN), w = q % (4 * PN);
;     const int gp = pl * 8 + xcd;
;     if (gp >= npatch) break;
;     ...
;         for (int it = 0; it < 16; ++it) {
;           const int c = it * 64 + laneE, row = c >> 3, seg = c & 7;
;           const float4 v = *(const float4*)(et + row * 144 + seg * 16);
;           const size_t g = (row0 + row) * DM + col0 + j * 32 + seg * 4;
;           const float4 xv = *(const float4*)(p.x + g);
;           const float4 hv = make_float4(xv.x + v.x, xv.y + v.y, xv.z + v.z, xv.w + v.w);
;           *(float4*)(p.out + g) = hv;
;           uint2 hb; hb.x = pack2(hv.x, hv.y); hb.y = pack2(hv.z, hv.w);
;           *(uint2*)(p.xn + (row0 + row) * LDK + col0 + j * 32 + seg * 4) = hb;
	v_pk_add_f32 v[194:195], v[198:199], v[194:195]
	v_pk_add_f32 v[196:197], v[200:201], v[196:197]
	global_store_dwordx4 v[192:193], v[194:197], off
	v_lshlrev_b64 v[198:199], 11, v[220:221]
	v_lshl_add_u64 v[198:199], v[198:199], 0, v[164:165]
	v_cvt_pk_bf16_f32 v194, v194, v195
	v_cvt_pk_bf16_f32 v195, v196, v197
	global_store_dwordx2 v[190:191], v[194:195], off
	global_load_dwordx4 v[202:205], v[186:187], off
	v_mad_u64_u32 v[196:197], s[12:13], v206, s14, v[166:167]
	ds_read_b128 v[206:209], v196
	v_mad_u64_u32 v[194:195], s[12:13], v210, s2, v[102:103]
	v_mad_i32_i24 v195, v211, s2, v195
	v_lshl_add_u64 v[194:195], v[194:195], 0, v[104:105]
	v_lshl_add_u64 v[200:201], s[20:21], 0, v[212:213]
	v_lshlrev_b64 v[222:223], 2, v[198:199]
	v_lshl_add_u64 v[198:199], v[194:195], 0, v[128:129]
	v_lshl_add_u64 v[194:195], s[52:53], 0, v[222:223]
	s_waitcnt vmcnt(0) lgkmcnt(0)
	v_pk_add_f32 v[202:203], v[206:207], v[202:203]
	v_pk_add_f32 v[204:205], v[208:209], v[204:205]
	global_store_dwordx4 v[200:201], v[202:205], off
	v_lshlrev_b64 v[206:207], 11, v[242:243]
	v_lshl_add_u64 v[206:207], v[206:207], 0, v[164:165]
	v_cvt_pk_bf16_f32 v202, v202, v203
	v_cvt_pk_bf16_f32 v203, v204, v205
	global_store_dwordx2 v[198:199], v[202:203], off
	global_load_dwordx4 v[210:213], v[194:195], off
	v_mad_u64_u32 v[204:205], s[12:13], v214, s14, v[166:167]
	ds_read_b128 v[214:217], v204
	v_mad_u64_u32 v[202:203], s[12:13], v220, s2, v[102:103]
	v_mad_i32_i24 v203, v221, s2, v203
	v_lshl_add_u64 v[202:203], v[202:203], 0, v[104:105]
	v_lshl_add_u64 v[208:209], s[20:21], 0, v[222:223]
	v_lshlrev_b64 v[244:245], 2, v[206:207]
	v_lshl_add_u64 v[206:207], v[202:203], 0, v[128:129]
	v_lshl_add_u64 v[202:203], s[52:53], 0, v[244:245]
	s_waitcnt vmcnt(0) lgkmcnt(0)
	v_pk_add_f32 v[210:211], v[214:215], v[210:211]
	v_pk_add_f32 v[212:213], v[216:217], v[212:213]
	global_store_dwordx4 v[208:209], v[210:213], off
	v_lshlrev_b64 v[214:215], 11, v[248:249]
	v_lshl_add_u64 v[214:215], v[214:215], 0, v[164:165]
	v_cvt_pk_bf16_f32 v210, v210, v211
	v_cvt_pk_bf16_f32 v211, v212, v213
	global_store_dwordx2 v[206:207], v[210:211], off
	global_load_dwordx4 v[220:223], v[202:203], off
	v_mad_u64_u32 v[212:213], s[12:13], v238, s14, v[166:167]
	ds_read_b128 v[238:241], v212
	v_mad_u64_u32 v[210:211], s[12:13], v242, s2, v[102:103]
	v_mad_i32_i24 v211, v243, s2, v211
	v_lshl_add_u64 v[210:211], v[210:211], 0, v[104:105]
	v_lshl_add_u64 v[216:217], s[20:21], 0, v[244:245]
	ds_read_b128 v[242:245], v218
	v_lshlrev_b64 v[250:251], 2, v[214:215]
	v_lshl_add_u64 v[214:215], v[210:211], 0, v[128:129]
	v_lshl_add_u64 v[210:211], s[52:53], 0, v[250:251]
	v_mad_u64_u32 v[102:103], s[12:13], v246, s2, v[102:103]
	v_mad_i32_i24 v103, v247, s2, v103
	v_lshl_add_u64 v[102:103], v[102:103], 0, v[104:105]
	v_lshl_add_u64 v[102:103], v[102:103], 0, v[128:129]
	s_waitcnt vmcnt(0) lgkmcnt(1)
	v_pk_add_f32 v[220:221], v[238:239], v[220:221]
	v_pk_add_f32 v[222:223], v[240:241], v[222:223]
	global_store_dwordx4 v[216:217], v[220:223], off
	s_nop 1
	v_cvt_pk_bf16_f32 v220, v220, v221
	v_cvt_pk_bf16_f32 v221, v222, v223
	global_store_dwordx2 v[214:215], v[220:221], off
	global_load_dwordx4 v[238:241], v[210:211], off
	v_lshlrev_b64 v[220:221], 11, v[246:247]
	v_lshl_add_u64 v[164:165], v[220:221], 0, v[164:165]
	v_lshlrev_b64 v[248:249], 2, v[164:165]
	v_lshl_add_u64 v[222:223], s[20:21], 0, v[250:251]
	v_lshl_add_u64 v[220:221], v[162:163], 0, v[128:129]
	v_lshl_add_u64 v[164:165], s[52:53], 0, v[248:249]
	v_lshl_add_u64 v[104:105], s[20:21], 0, v[248:249]
	s_waitcnt vmcnt(0) lgkmcnt(0)
	v_pk_add_f32 v[238:239], v[242:243], v[238:239]
	v_pk_add_f32 v[240:241], v[244:245], v[240:241]
	v_cvt_pk_bf16_f32 v162, v238, v239
	v_cvt_pk_bf16_f32 v163, v240, v241
	global_store_dwordx4 v[222:223], v[238:241], off
	global_store_dwordx2 v[220:221], v[162:163], off
	global_load_dwordx4 v[238:241], v[164:165], off
	v_mad_u64_u32 v[162:163], s[12:13], v148, s14, v[166:167]
	ds_read_b128 v[242:245], v162
	v_readlane_b32 s12, v254, 28
	s_add_i32 s16, s16, s12
	s_ashr_i32 s12, s16, 31
	s_lshr_b32 s12, s12, 27
	s_add_i32 s12, s16, s12
	s_ashr_i32 s12, s12, 5
	s_lshl_b32 s12, s12, 3
	v_readlane_b32 s13, v254, 24
	s_or_b32 s17, s12, s13
	s_cmp_gt_i32 s17, 31
	s_waitcnt vmcnt(0) lgkmcnt(0)
; __device__ __forceinline__ int accrow(int reg, int lh) { return (reg & 3) + 8 * (reg >> 2) + 4 * lh; }
; template <int EPI, int PN>
; __device__ void gemm_phase(const Params& p, const u16* __restrict__ A, const u16* __restrict__ Bt, int nNt, char* smem) {
;     ...
;       for (int j = 0; j < 2; ++j) {
; #pragma unroll
;         for (int i = 0; i < 4; ++i)
; #pragma unroll
;           for (int r = 0; r < 16; ++r) *(float*)(et + (i * 32 + accrow(r, lhE)) * 144 + lrE * 4) = acc[i][j][r];
; #pragma unroll
;         for (int it = 0; it < 16; ++it) {
;           const int c = it * 64 + laneE, row = c >> 3, seg = c & 7;
;           const float4 v = *(const float4*)(et + row * 144 + seg * 16);
;           const size_t g = (row0 + row) * DM + col0 + j * 32 + seg * 4;
;           const float4 xv = *(const float4*)(p.x + g);
;           const float4 hv = make_float4(xv.x + v.x, xv.y + v.y, xv.z + v.z, xv.w + v.w);
;           *(float4*)(p.out + g) = hv;
;           uint2 hb; hb.x = pack2(hv.x, hv.y); hb.y = pack2(hv.z, hv.w);
;           *(uint2*)(p.xn + (row0 + row) * LDK + col0 + j * 32 + seg * 4) = hb;
	v_pk_add_f32 v[238:239], v[242:243], v[238:239]
	v_pk_add_f32 v[240:241], v[244:245], v[240:241]
	v_cvt_pk_bf16_f32 v148, v238, v239
	v_cvt_pk_bf16_f32 v149, v240, v241
	global_store_dwordx4 v[104:105], v[238:241], off
	global_store_dwordx2 v[102:103], v[148:149], off
	global_load_dwordx4 v[238:241], v[160:161], off offset:128
	ds_write_b32 v159, v48
	ds_write_b32 v159, v49 offset:144
	ds_write_b32 v159, v50 offset:288
	ds_write_b32 v159, v51 offset:432
	ds_write_b32 v159, v52 offset:1152
	ds_write_b32 v159, v53 offset:1296
	ds_write_b32 v159, v54 offset:1440
	ds_write_b32 v159, v55 offset:1584
	ds_write_b32 v159, v56 offset:2304
	ds_write_b32 v159, v57 offset:2448
	ds_write_b32 v159, v58 offset:2592
	ds_write_b32 v159, v59 offset:2736
	ds_write_b32 v159, v60 offset:3456
	ds_write_b32 v159, v61 offset:3600
	ds_write_b32 v159, v62 offset:3744
	ds_write_b32 v159, v63 offset:3888
	ds_write_b32 v159, v32 offset:4608
	ds_write_b32 v159, v33 offset:4752
	ds_write_b32 v159, v34 offset:4896
	ds_write_b32 v159, v35 offset:5040
	ds_write_b32 v159, v36 offset:5760
	ds_write_b32 v159, v37 offset:5904
	ds_write_b32 v159, v38 offset:6048
	ds_write_b32 v159, v39 offset:6192
	ds_write_b32 v159, v40 offset:6912
	ds_write_b32 v159, v41 offset:7056
	ds_write_b32 v159, v42 offset:7200
	ds_write_b32 v159, v43 offset:7344
	ds_write_b32 v159, v44 offset:8064
	ds_write_b32 v159, v45 offset:8208
	ds_write_b32 v159, v46 offset:8352
	ds_write_b32 v159, v47 offset:8496
	ds_write_b32 v159, v16 offset:9216
	ds_write_b32 v159, v17 offset:9360
	ds_write_b32 v159, v18 offset:9504
	ds_write_b32 v159, v19 offset:9648
	ds_write_b32 v159, v20 offset:10368
	ds_write_b32 v159, v21 offset:10512
	ds_write_b32 v159, v22 offset:10656
	ds_write_b32 v159, v23 offset:10800
	ds_write_b32 v159, v24 offset:11520
	ds_write_b32 v159, v25 offset:11664
	ds_write_b32 v159, v26 offset:11808
	ds_write_b32 v159, v27 offset:11952
	ds_write_b32 v159, v28 offset:12672
	ds_write_b32 v159, v29 offset:12816
	ds_write_b32 v159, v30 offset:12960
	ds_write_b32 v159, v31 offset:13104
	ds_write_b32 v159, v0 offset:13824
	ds_write_b32 v159, v1 offset:13968
	ds_write_b32 v159, v2 offset:14112
	ds_write_b32 v159, v3 offset:14256
	ds_write_b32 v159, v4 offset:14976
	ds_write_b32 v159, v5 offset:15120
	ds_write_b32 v159, v6 offset:15264
	ds_write_b32 v159, v7 offset:15408
	ds_write_b32 v159, v8 offset:16128
	ds_write_b32 v159, v9 offset:16272
	ds_write_b32 v159, v10 offset:16416
	ds_write_b32 v159, v11 offset:16560
	ds_write_b32 v159, v12 offset:17280
	ds_write_b32 v159, v13 offset:17424
	ds_write_b32 v159, v14 offset:17568
	ds_write_b32 v159, v15 offset:17712
	ds_read_b128 v[0:3], v158
	ds_read_b128 v[4:7], v72
	s_waitcnt vmcnt(0) lgkmcnt(1)
	v_pk_add_f32 v[0:1], v[0:1], v[238:239]
	v_pk_add_f32 v[2:3], v[2:3], v[240:241]
	global_store_dwordx4 v[64:65], v[0:3], off offset:128
	s_nop 1
	v_cvt_pk_bf16_f32 v0, v0, v1
	v_cvt_pk_bf16_f32 v1, v2, v3
	global_store_dwordx2 v[66:67], v[0:1], off offset:64
	global_load_dwordx4 v[0:3], v[68:69], off offset:128
	s_waitcnt vmcnt(0) lgkmcnt(0)
	v_pk_add_f32 v[0:1], v[4:5], v[0:1]
	v_pk_add_f32 v[2:3], v[6:7], v[2:3]
	global_store_dwordx4 v[76:77], v[0:3], off offset:128
	ds_read_b128 v[4:7], v80
	s_nop 0
	v_cvt_pk_bf16_f32 v0, v0, v1
	v_cvt_pk_bf16_f32 v1, v2, v3
	global_store_dwordx2 v[74:75], v[0:1], off offset:64
	global_load_dwordx4 v[0:3], v[70:71], off offset:128
	s_waitcnt vmcnt(0) lgkmcnt(0)
	v_pk_add_f32 v[0:1], v[4:5], v[0:1]
	v_pk_add_f32 v[2:3], v[6:7], v[2:3]
	global_store_dwordx4 v[84:85], v[0:3], off offset:128
	ds_read_b128 v[4:7], v88
	s_nop 0
	v_cvt_pk_bf16_f32 v0, v0, v1
	v_cvt_pk_bf16_f32 v1, v2, v3
	global_store_dwordx2 v[82:83], v[0:1], off offset:64
	global_load_dwordx4 v[0:3], v[78:79], off offset:128
	s_waitcnt vmcnt(0) lgkmcnt(0)
	v_pk_add_f32 v[0:1], v[4:5], v[0:1]
	v_pk_add_f32 v[2:3], v[6:7], v[2:3]
	global_store_dwordx4 v[92:93], v[0:3], off offset:128
	ds_read_b128 v[4:7], v96
	s_nop 0
	v_cvt_pk_bf16_f32 v0, v0, v1
	v_cvt_pk_bf16_f32 v1, v2, v3
	global_store_dwordx2 v[90:91], v[0:1], off offset:64
	global_load_dwordx4 v[0:3], v[86:87], off offset:128
	s_waitcnt vmcnt(0) lgkmcnt(0)
; template <int EPI, int PN>
; __device__ void gemm_phase(const Params& p, const u16* __restrict__ A, const u16* __restrict__ Bt, int nNt, char* smem) {
;     ...
;         for (int it = 0; it < 16; ++it) {
;           const int c = it * 64 + laneE, row = c >> 3, seg = c & 7;
;           const float4 v = *(const float4*)(et + row * 144 + seg * 16);
;           const size_t g = (row0 + row) * DM + col0 + j * 32 + seg * 4;
;           const float4 xv = *(const float4*)(p.x + g);
;           const float4 hv = make_float4(xv.x + v.x, xv.y + v.y, xv.z + v.z, xv.w + v.w);
;           *(float4*)(p.out + g) = hv;
;           uint2 hb; hb.x = pack2(hv.x, hv.y); hb.y = pack2(hv.z, hv.w);
;           *(uint2*)(p.xn + (row0 + row) * LDK + col0 + j * 32 + seg * 4) = hb;
;     ...
;     __syncthreads();
	v_pk_add_f32 v[0:1], v[4:5], v[0:1]
	v_pk_add_f32 v[2:3], v[6:7], v[2:3]
	global_store_dwordx4 v[100:101], v[0:3], off offset:128
	ds_read_b128 v[4:7], v108
	s_nop 0
	v_cvt_pk_bf16_f32 v0, v0, v1
	v_cvt_pk_bf16_f32 v1, v2, v3
	global_store_dwordx2 v[98:99], v[0:1], off offset:64
	global_load_dwordx4 v[0:3], v[94:95], off offset:128
	s_waitcnt vmcnt(0) lgkmcnt(0)
	v_pk_add_f32 v[0:1], v[4:5], v[0:1]
	v_pk_add_f32 v[2:3], v[6:7], v[2:3]
	global_store_dwordx4 v[112:113], v[0:3], off offset:128
	ds_read_b128 v[4:7], v116
	s_nop 0
	v_cvt_pk_bf16_f32 v0, v0, v1
	v_cvt_pk_bf16_f32 v1, v2, v3
	global_store_dwordx2 v[110:111], v[0:1], off offset:64
	global_load_dwordx4 v[0:3], v[106:107], off offset:128
	s_waitcnt vmcnt(0) lgkmcnt(0)
	v_pk_add_f32 v[0:1], v[4:5], v[0:1]
	v_pk_add_f32 v[2:3], v[6:7], v[2:3]
	global_store_dwordx4 v[120:121], v[0:3], off offset:128
	ds_read_b128 v[4:7], v124
	s_nop 0
	v_cvt_pk_bf16_f32 v0, v0, v1
	v_cvt_pk_bf16_f32 v1, v2, v3
	global_store_dwordx2 v[118:119], v[0:1], off offset:64
	global_load_dwordx4 v[0:3], v[114:115], off offset:128
	s_waitcnt vmcnt(0) lgkmcnt(0)
	v_pk_add_f32 v[0:1], v[4:5], v[0:1]
	v_pk_add_f32 v[2:3], v[6:7], v[2:3]
	global_store_dwordx4 v[168:169], v[0:3], off offset:128
	ds_read_b128 v[4:7], v172
	s_nop 0
	v_cvt_pk_bf16_f32 v0, v0, v1
	v_cvt_pk_bf16_f32 v1, v2, v3
	global_store_dwordx2 v[126:127], v[0:1], off offset:64
	global_load_dwordx4 v[0:3], v[122:123], off offset:128
	s_waitcnt vmcnt(0) lgkmcnt(0)
	v_pk_add_f32 v[0:1], v[4:5], v[0:1]
	v_pk_add_f32 v[2:3], v[6:7], v[2:3]
	global_store_dwordx4 v[176:177], v[0:3], off offset:128
	ds_read_b128 v[4:7], v180
	s_nop 0
	v_cvt_pk_bf16_f32 v0, v0, v1
	v_cvt_pk_bf16_f32 v1, v2, v3
	global_store_dwordx2 v[174:175], v[0:1], off offset:64
	global_load_dwordx4 v[0:3], v[170:171], off offset:128
	s_waitcnt vmcnt(0) lgkmcnt(0)
	v_pk_add_f32 v[0:1], v[4:5], v[0:1]
	v_pk_add_f32 v[2:3], v[6:7], v[2:3]
	global_store_dwordx4 v[184:185], v[0:3], off offset:128
	ds_read_b128 v[4:7], v188
	s_nop 0
	v_cvt_pk_bf16_f32 v0, v0, v1
	v_cvt_pk_bf16_f32 v1, v2, v3
	global_store_dwordx2 v[182:183], v[0:1], off offset:64
	global_load_dwordx4 v[0:3], v[178:179], off offset:128
	s_waitcnt vmcnt(0) lgkmcnt(0)
	v_pk_add_f32 v[0:1], v[4:5], v[0:1]
	v_pk_add_f32 v[2:3], v[6:7], v[2:3]
	global_store_dwordx4 v[192:193], v[0:3], off offset:128
	ds_read_b128 v[4:7], v196
	s_nop 0
	v_cvt_pk_bf16_f32 v0, v0, v1
	v_cvt_pk_bf16_f32 v1, v2, v3
	global_store_dwordx2 v[190:191], v[0:1], off offset:64
	global_load_dwordx4 v[0:3], v[186:187], off offset:128
	s_waitcnt vmcnt(0) lgkmcnt(0)
	v_pk_add_f32 v[0:1], v[4:5], v[0:1]
	v_pk_add_f32 v[2:3], v[6:7], v[2:3]
	global_store_dwordx4 v[200:201], v[0:3], off offset:128
	ds_read_b128 v[4:7], v204
	s_nop 0
	v_cvt_pk_bf16_f32 v0, v0, v1
	v_cvt_pk_bf16_f32 v1, v2, v3
	global_store_dwordx2 v[198:199], v[0:1], off offset:64
	global_load_dwordx4 v[0:3], v[194:195], off offset:128
	s_waitcnt vmcnt(0) lgkmcnt(0)
	v_pk_add_f32 v[0:1], v[4:5], v[0:1]
	v_pk_add_f32 v[2:3], v[6:7], v[2:3]
	global_store_dwordx4 v[208:209], v[0:3], off offset:128
	ds_read_b128 v[4:7], v212
	s_nop 0
	v_cvt_pk_bf16_f32 v0, v0, v1
	v_cvt_pk_bf16_f32 v1, v2, v3
	global_store_dwordx2 v[206:207], v[0:1], off offset:64
	global_load_dwordx4 v[0:3], v[202:203], off offset:128
	s_waitcnt vmcnt(0) lgkmcnt(0)
	v_pk_add_f32 v[0:1], v[4:5], v[0:1]
	v_pk_add_f32 v[2:3], v[6:7], v[2:3]
	global_store_dwordx4 v[216:217], v[0:3], off offset:128
	ds_read_b128 v[4:7], v218
	s_nop 0
	v_cvt_pk_bf16_f32 v0, v0, v1
	v_cvt_pk_bf16_f32 v1, v2, v3
	global_store_dwordx2 v[214:215], v[0:1], off offset:64
	global_load_dwordx4 v[0:3], v[210:211], off offset:128
	s_waitcnt vmcnt(0) lgkmcnt(0)
	v_pk_add_f32 v[0:1], v[4:5], v[0:1]
	v_pk_add_f32 v[2:3], v[6:7], v[2:3]
	global_store_dwordx4 v[222:223], v[0:3], off offset:128
	ds_read_b128 v[4:7], v162
	s_nop 0
	v_cvt_pk_bf16_f32 v0, v0, v1
	v_cvt_pk_bf16_f32 v1, v2, v3
	global_store_dwordx2 v[220:221], v[0:1], off offset:64
	global_load_dwordx4 v[0:3], v[164:165], off offset:128
	s_waitcnt vmcnt(0) lgkmcnt(0)
	v_pk_add_f32 v[0:1], v[4:5], v[0:1]
	v_pk_add_f32 v[2:3], v[6:7], v[2:3]
	global_store_dwordx4 v[104:105], v[0:3], off offset:128
	s_nop 1
	v_cvt_pk_bf16_f32 v0, v0, v1
	v_cvt_pk_bf16_f32 v1, v2, v3
	global_store_dwordx2 v[102:103], v[0:1], off offset:64
	s_barrier
	s_cbranch_scc0 .LBB0_665

; template <int EPI, int PN>
; __device__ void gemm_phase(const Params& p, const u16* __restrict__ A, const u16* __restrict__ Bt, int nNt, char* smem) {
;     ...
;     const int pl = q / (4 * PN), w = q % (4 * PN);
;     const int gp = pl * 8 + xcd;
;     if (gp >= npatch) break;
;     const int mt = (gp / npn) * 4 + (w & 3), nt = (gp % npn) * PN + (w >> 2);
;     const int gch = sch ^ ((srow >> 1) & 7);
;     const u16* Ag0 = A + (size_t)(mt * 256 + srow) * LDK + gch * 8;
;     const u16* Bg0 = Bt + (size_t)(nt * 256 + srow) * LDK + gch * 8;
;     f32x16 acc[4][2];
; #pragma unroll
;     for (int i = 0; i < 4; ++i)
; #pragma unroll
;       for (int j = 0; j < 2; ++j) acc[i][j] = zero16();
;     asm volatile("s_waitcnt vmcnt(0)" ::: "memory");
; #pragma unroll
;     for (int i = 0; i < 4; ++i) {
;       glds16(Ag0 + (size_t)i * 64 * LDK, ring + (srow + 64 * i) * 64 + sch * 8);
;       glds16(Bg0 + (size_t)i * 64 * LDK, ring + 16384 + (srow + 64 * i) * 64 + sch * 8);
;     }
;     for (int kt = 0; kt < 32; ++kt) {
;       asm volatile("s_waitcnt vmcnt(0)" ::: "memory");
;       __builtin_amdgcn_s_barrier();
;       const u16* Ab = ring + (kt & 1) * STG;
;       const u16* Bb = Ab + 16384;
;       u16* st = ring + ((kt + 1) & 1) * STG;
;       const bool pre = (kt + 1 < 32);
;       s16x8 af[2][4], bf[2][2];
;       auto ldfrag = [&](int ks, int slot) {
; #pragma unroll
;         for (int i = 0; i < 4; ++i) {
;           const int row = wr * 128 + i * 32 + lr;
;           af[slot][i] = *(const s16x8*)(Ab + row * 64 + (((ks * 2 + lh) ^ ((row >> 1) & 7)) * 8));
;         }
; #pragma unroll
;         for (int j = 0; j < 2; ++j) {
;           const int rowb = nh * 128 + wc * 64 + j * 32 + lr;
;           bf[slot][j] = *(const s16x8*)(Bb + rowb * 64 + (((ks * 2 + lh) ^ ((rowb >> 1) & 7)) * 8));
;         }
;       };
;       ldfrag(0, 0);
;       ldfrag(1, 1);
.LBB0_722:
	s_ashr_i32 s10, s34, 31
	s_lshr_b32 s10, s10, 27
	s_add_i32 s10, s34, s10
	s_andn2_b32 s10, s10, 31
	s_sub_i32 s14, s34, s10
	s_lshl_b32 s10, s11, 2
	s_and_b32 s15, s14, 3
	s_or_b32 s10, s15, s10
	s_ashr_i32 s14, s14, 2
	v_lshl_add_u32 v0, s10, 8, v141
	v_lshl_add_u32 v6, s14, 8, v141
	v_mad_i64_i32 v[0:1], s[16:17], v0, s0, v[130:131]
	v_mad_i64_i32 v[2:3], s[16:17], v6, s0, v[132:133]
	s_waitcnt vmcnt(0)
	v_readfirstlane_b32 s16, v136
	s_mov_b32 s17, m0
	s_mov_b32 m0, s16
	s_nop 0
	global_load_lds_dwordx4 v[0:1], off
	s_mov_b32 m0, s17
	v_readfirstlane_b32 s16, v138
	s_mov_b32 s17, m0
	s_mov_b32 m0, s16
	s_nop 0
	global_load_lds_dwordx4 v[2:3], off
	s_mov_b32 m0, s17
	v_lshl_add_u64 v[4:5], v[0:1], 0, s[2:3]
	v_readfirstlane_b32 s16, v140
	s_mov_b32 s17, m0
	s_mov_b32 m0, s16
	s_nop 0
	global_load_lds_dwordx4 v[4:5], off
	s_mov_b32 m0, s17
	v_lshl_add_u64 v[4:5], v[2:3], 0, s[2:3]
	v_readfirstlane_b32 s16, v142
	s_mov_b32 s17, m0
	s_mov_b32 m0, s16
	s_nop 0
	global_load_lds_dwordx4 v[4:5], off
	s_mov_b32 m0, s17
	v_lshl_add_u64 v[4:5], v[0:1], 0, s[4:5]
	v_readfirstlane_b32 s16, v144
	s_mov_b32 s17, m0
	s_mov_b32 m0, s16
	s_nop 0
	global_load_lds_dwordx4 v[4:5], off
	s_mov_b32 m0, s17
	v_lshl_add_u64 v[4:5], v[2:3], 0, s[4:5]
	v_readfirstlane_b32 s16, v146
	s_mov_b32 s17, m0
	s_mov_b32 m0, s16
	s_nop 0
	global_load_lds_dwordx4 v[4:5], off
	s_mov_b32 m0, s17
	v_lshl_add_u64 v[0:1], v[0:1], 0, s[6:7]
	v_readfirstlane_b32 s16, v148
	s_mov_b32 s17, m0
	s_mov_b32 m0, s16
	s_nop 0
	global_load_lds_dwordx4 v[0:1], off
	s_mov_b32 m0, s17
	s_lshl_b32 s11, s11, 10
	s_lshl_b32 s15, s15, 8
	v_lshl_add_u64 v[0:1], v[2:3], 0, s[6:7]
	v_readfirstlane_b32 s16, v150
	s_mov_b32 s17, m0
	s_mov_b32 m0, s16
	s_nop 0
	global_load_lds_dwordx4 v[0:1], off
	s_mov_b32 m0, s17
	s_or_b32 s11, s15, s11
	v_add_u32_e32 v0, s11, v141
	v_mad_i64_i32 v[158:159], s[16:17], v0, s0, v[152:153]
	v_mad_i64_i32 v[160:161], s[16:17], v6, s0, v[154:155]
	s_mov_b32 s11, 0x8000
	v_mov_b32_e32 v0, 0
	v_mov_b32_e32 v1, v129
	v_mov_b32_e32 v2, v129
	v_mov_b32_e32 v3, v129
	v_mov_b32_e32 v4, v129
	v_mov_b32_e32 v5, v129
	v_mov_b32_e32 v6, v129
	v_mov_b32_e32 v7, v129
	v_mov_b32_e32 v8, v129
	v_mov_b32_e32 v9, v129
	v_mov_b32_e32 v10, v129
	v_mov_b32_e32 v11, v129
	v_mov_b32_e32 v12, v129
	v_mov_b32_e32 v13, v129
	v_mov_b32_e32 v14, v129
	v_mov_b32_e32 v15, v129
	v_mov_b32_e32 v16, 0
	v_mov_b32_e32 v17, v129
	v_mov_b32_e32 v18, v129
	v_mov_b32_e32 v19, v129
	v_mov_b32_e32 v20, v129
	v_mov_b32_e32 v21, v129
	v_mov_b32_e32 v22, v129
	v_mov_b32_e32 v23, v129
	v_mov_b32_e32 v24, v129
	v_mov_b32_e32 v25, v129
	v_mov_b32_e32 v26, v129
	v_mov_b32_e32 v27, v129
	v_mov_b32_e32 v28, v129
	v_mov_b32_e32 v29, v129
	v_mov_b32_e32 v30, v129
	v_mov_b32_e32 v31, v129
	v_mov_b32_e32 v32, 0
	v_mov_b32_e32 v33, v129
	v_mov_b32_e32 v34, v129
	v_mov_b32_e32 v35, v129
	v_mov_b32_e32 v36, v129
	v_mov_b32_e32 v37, v129
	v_mov_b32_e32 v38, v129
	v_mov_b32_e32 v39, v129
	v_mov_b32_e32 v40, v129
	v_mov_b32_e32 v41, v129
	v_mov_b32_e32 v42, v129
	v_mov_b32_e32 v43, v129
	v_mov_b32_e32 v44, v129
	v_mov_b32_e32 v45, v129
	v_mov_b32_e32 v46, v129
	v_mov_b32_e32 v47, v129
	v_mov_b32_e32 v48, 0
	v_mov_b32_e32 v49, v129
	v_mov_b32_e32 v50, v129
	v_mov_b32_e32 v51, v129
	v_mov_b32_e32 v52, v129
	v_mov_b32_e32 v53, v129
	v_mov_b32_e32 v54, v129
	v_mov_b32_e32 v55, v129
	v_mov_b32_e32 v56, v129
	v_mov_b32_e32 v57, v129
	v_mov_b32_e32 v58, v129
	v_mov_b32_e32 v59, v129
	v_mov_b32_e32 v60, v129
	v_mov_b32_e32 v61, v129
	v_mov_b32_e32 v62, v129
	v_mov_b32_e32 v63, v129
	v_mov_b32_e32 v64, 0
	v_mov_b32_e32 v65, v129
	v_mov_b32_e32 v66, v129
	v_mov_b32_e32 v67, v129
	v_mov_b32_e32 v68, v129
	v_mov_b32_e32 v69, v129
	v_mov_b32_e32 v70, v129
	v_mov_b32_e32 v71, v129
	v_mov_b32_e32 v72, v129
	v_mov_b32_e32 v73, v129
	v_mov_b32_e32 v74, v129
	v_mov_b32_e32 v75, v129
	v_mov_b32_e32 v76, v129
	v_mov_b32_e32 v77, v129
	v_mov_b32_e32 v78, v129
	v_mov_b32_e32 v79, v129
	v_mov_b32_e32 v80, 0
	v_mov_b32_e32 v81, v129
	v_mov_b32_e32 v82, v129
	v_mov_b32_e32 v83, v129
	v_mov_b32_e32 v84, v129
	v_mov_b32_e32 v85, v129
	v_mov_b32_e32 v86, v129
	v_mov_b32_e32 v87, v129
	v_mov_b32_e32 v88, v129
	v_mov_b32_e32 v89, v129
	v_mov_b32_e32 v90, v129
	v_mov_b32_e32 v91, v129
	v_mov_b32_e32 v92, v129
	v_mov_b32_e32 v93, v129
	v_mov_b32_e32 v94, v129
	v_mov_b32_e32 v95, v129
	v_mov_b32_e32 v96, 0
	v_mov_b32_e32 v97, v129
	v_mov_b32_e32 v98, v129
	v_mov_b32_e32 v99, v129
	v_mov_b32_e32 v100, v129
	v_mov_b32_e32 v101, v129
	v_mov_b32_e32 v102, v129
	v_mov_b32_e32 v103, v129
	v_mov_b32_e32 v104, v129
	v_mov_b32_e32 v105, v129
	v_mov_b32_e32 v106, v129
	v_mov_b32_e32 v107, v129
	v_mov_b32_e32 v108, v129
	v_mov_b32_e32 v109, v129
	v_mov_b32_e32 v110, v129
	v_mov_b32_e32 v111, v129
	v_mov_b32_e32 v112, 0
	v_mov_b32_e32 v113, v129
	v_mov_b32_e32 v114, v129
	v_mov_b32_e32 v115, v129
	v_mov_b32_e32 v116, v129
	v_mov_b32_e32 v117, v129
	v_mov_b32_e32 v118, v129
	v_mov_b32_e32 v119, v129
	v_mov_b32_e32 v120, v129
	v_mov_b32_e32 v121, v129
	v_mov_b32_e32 v122, v129
	v_mov_b32_e32 v123, v129
	v_mov_b32_e32 v124, v129
	v_mov_b32_e32 v125, v129
	v_mov_b32_e32 v126, v129
	v_mov_b32_e32 v127, v129
	v_readfirstlane_b32 s99, v136
	s_add_i32 s99, s99, 0x10000
	s_mov_b32 s16, m0
	s_mov_b32 m0, s99
	s_nop 0
	global_load_lds_dwordx4 v[158:159], off
	v_lshl_add_u64 v[232:233], v[158:159], 0, s[2:3]
	s_add_i32 m0, s99, 0x2000
	s_nop 0
	global_load_lds_dwordx4 v[232:233], off
	v_lshl_add_u64 v[234:235], v[158:159], 0, s[4:5]
	s_add_i32 m0, s99, 0x4000
	s_nop 0
	global_load_lds_dwordx4 v[234:235], off
	v_lshl_add_u64 v[232:233], v[158:159], 0, s[6:7]
	s_add_i32 m0, s99, 0x6000
	s_nop 0
	global_load_lds_dwordx4 v[232:233], off
	s_mov_b32 m0, s16
	v_lshl_add_u64 v[158:159], v[158:159], 0, s[8:9]
	s_waitcnt vmcnt(0)
	s_barrier
	v_lshlrev_b32_e32 v227, 1, v143
	v_lshlrev_b32_e32 v229, 1, v147
	v_add_u32_e32 v228, v227, v173
	v_add_u32_e32 v230, v229, v173
	ds_read_b128 v[178:181], v228
	ds_read_b128 v[182:185], v228 offset:4096
	ds_read_b128 v[186:189], v228 offset:8192
	ds_read_b128 v[190:193], v228 offset:12288
	ds_read_b128 v[194:197], v230 offset:32768
	ds_read_b128 v[198:201], v230 offset:36864
	v_add_u32_e32 v228, v227, v174
	v_add_u32_e32 v230, v229, v174
	ds_read_b128 v[202:205], v228
	ds_read_b128 v[206:209], v228 offset:4096
	ds_read_b128 v[210:213], v228 offset:8192
	ds_read_b128 v[214:217], v228 offset:12288
	ds_read_b128 v[218:221], v230 offset:32768
	ds_read_b128 v[222:225], v230 offset:36864
; template <int EPI, int PN>
; __device__ void gemm_phase(const Params& p, const u16* __restrict__ A, const u16* __restrict__ Bt, int nNt, char* smem) {
;     ...
;     for (int kt = 0; kt < 32; ++kt) {
;       asm volatile("s_waitcnt vmcnt(0)" ::: "memory");
;       __builtin_amdgcn_s_barrier();
;       const u16* Ab = ring + (kt & 1) * STG;
;       const u16* Bb = Ab + 16384;
;       u16* st = ring + ((kt + 1) & 1) * STG;
;       const bool pre = (kt + 1 < 32);
;       s16x8 af[2][4], bf[2][2];
;       auto ldfrag = [&](int ks, int slot) {
; #pragma unroll
;         for (int i = 0; i < 4; ++i) {
;           const int row = wr * 128 + i * 32 + lr;
;           af[slot][i] = *(const s16x8*)(Ab + row * 64 + (((ks * 2 + lh) ^ ((row >> 1) & 7)) * 8));
;         }
; #pragma unroll
;         for (int j = 0; j < 2; ++j) {
;           const int rowb = nh * 128 + wc * 64 + j * 32 + lr;
;           bf[slot][j] = *(const s16x8*)(Bb + rowb * 64 + (((ks * 2 + lh) ^ ((rowb >> 1) & 7)) * 8));
;         }
;       };
;       ldfrag(0, 0);
;       ldfrag(1, 1);
;       __builtin_amdgcn_sched_barrier(0);
; #pragma unroll
;       for (int ks = 0; ks < 4; ++ks) {
;         const int slot = ks & 1;
; #pragma unroll
;         for (int i = 0; i < 4; ++i) {
;           acc[i][0] = mfma32(af[slot][i], bf[slot][0], acc[i][0]);
;           acc[i][1] = mfma32(af[slot][i], bf[slot][1], acc[i][1]);
;           __builtin_amdgcn_sched_barrier(0);
;           if (pre && (i & 1) == 0) {
;             const int pi = ks * 2 + (i >> 1);
;             if (pi < 4) glds16(Ag0 + (size_t)pi * 64 * LDK + (kt + 1) * 64, st + (srow + 64 * pi) * 64 + sch * 8);
;             else glds16(Bg0 + (size_t)(pi - 4) * 64 * LDK + (kt + 1) * 64, st + 16384 + (srow + 64 * (pi - 4)) * 64 + sch * 8);
;             __builtin_amdgcn_sched_barrier(0);
;           }
;         }
;         if (ks + 2 < 4) { ldfrag(ks + 2, slot); __builtin_amdgcn_sched_barrier(0); }
;       }
.Lrot723_loop:
	s_add_i32 s15, s11, 0xffff8000
	s_and_b32 s15, s15, 0x8000
	s_lshl_b32 s15, s15, 1
	v_lshl_or_b32 v128, v143, 1, s15
	v_lshl_add_u32 v149, v147, 1, s15
	s_and_b32 s98, s11, 0x8000
	s_lshl_b32 s98, s98, 1
	s_waitcnt lgkmcnt(7)
	v_mfma_f32_32x32x16_bf16 v[112:127], v[178:181], v[194:197], v[112:127]
	v_add3_u32 v226, s98, v162, v156
	s_waitcnt lgkmcnt(6)
	v_mfma_f32_32x32x16_bf16 v[96:111], v[178:181], v[198:201], v[96:111]
	v_readfirstlane_b32 s100, v226
	s_mov_b32 s16, m0
	s_add_i32 m0, s100, 0x8000
	s_nop 0
	global_load_lds_dwordx4 v[160:161], off
	v_mfma_f32_32x32x16_bf16 v[80:95], v[182:185], v[194:197], v[80:95]
	v_mfma_f32_32x32x16_bf16 v[64:79], v[182:185], v[198:201], v[64:79]
	v_lshl_add_u64 v[178:179], v[160:161], 0, s[2:3]
	s_add_i32 m0, s100, 0xa000
	s_nop 0
	global_load_lds_dwordx4 v[178:179], off
	v_mfma_f32_32x32x16_bf16 v[48:63], v[186:189], v[194:197], v[48:63]
	v_mfma_f32_32x32x16_bf16 v[32:47], v[186:189], v[198:201], v[32:47]
	v_lshl_add_u64 v[180:181], v[160:161], 0, s[4:5]
	s_add_i32 m0, s100, 0xc000
	s_nop 0
	global_load_lds_dwordx4 v[180:181], off
	v_mfma_f32_32x32x16_bf16 v[16:31], v[190:193], v[194:197], v[16:31]
	v_mfma_f32_32x32x16_bf16 v[0:15], v[190:193], v[198:201], v[0:15]
	v_lshl_add_u64 v[178:179], v[160:161], 0, s[6:7]
	s_add_i32 m0, s100, 0xe000
	s_nop 0
	global_load_lds_dwordx4 v[178:179], off
	s_mov_b32 m0, s16
	v_lshl_add_u64 v[160:161], v[160:161], 0, s[8:9]
	v_add_u32_e32 v177, v128, v175
	ds_read_b128 v[178:181], v177
	ds_read_b128 v[182:185], v177 offset:4096
	ds_read_b128 v[186:189], v177 offset:8192
	ds_read_b128 v[190:193], v177 offset:12288
	v_add_u32_e32 v177, v149, v175
	ds_read_b128 v[194:197], v177 offset:32768
	ds_read_b128 v[198:201], v177 offset:36864
	s_waitcnt lgkmcnt(7)
	v_mfma_f32_32x32x16_bf16 v[112:127], v[202:205], v[218:221], v[112:127]
	s_waitcnt lgkmcnt(6)
	v_mfma_f32_32x32x16_bf16 v[96:111], v[202:205], v[222:225], v[96:111]
	v_mfma_f32_32x32x16_bf16 v[80:95], v[206:209], v[218:221], v[80:95]
	v_mfma_f32_32x32x16_bf16 v[64:79], v[206:209], v[222:225], v[64:79]
	v_mfma_f32_32x32x16_bf16 v[48:63], v[210:213], v[218:221], v[48:63]
	v_mfma_f32_32x32x16_bf16 v[32:47], v[210:213], v[222:225], v[32:47]
	v_mfma_f32_32x32x16_bf16 v[16:31], v[214:217], v[218:221], v[16:31]
	v_mfma_f32_32x32x16_bf16 v[0:15], v[214:217], v[222:225], v[0:15]
	v_add_u32_e32 v128, v128, v176
	ds_read_b128 v[202:205], v128
	ds_read_b128 v[206:209], v128 offset:4096
	ds_read_b128 v[210:213], v128 offset:8192
	ds_read_b128 v[214:217], v128 offset:12288
	v_add_u32_e32 v128, v149, v176
	ds_read_b128 v[218:221], v128 offset:32768
	ds_read_b128 v[222:225], v128 offset:36864
	s_waitcnt lgkmcnt(7)
	v_mfma_f32_32x32x16_bf16 v[112:127], v[178:181], v[194:197], v[112:127]
	s_waitcnt lgkmcnt(6)
	v_mfma_f32_32x32x16_bf16 v[96:111], v[178:181], v[198:201], v[96:111]
	v_mfma_f32_32x32x16_bf16 v[80:95], v[182:185], v[194:197], v[80:95]
	v_mfma_f32_32x32x16_bf16 v[64:79], v[182:185], v[198:201], v[64:79]
	v_mfma_f32_32x32x16_bf16 v[48:63], v[186:189], v[194:197], v[48:63]
	v_mfma_f32_32x32x16_bf16 v[32:47], v[186:189], v[198:201], v[32:47]
	v_mfma_f32_32x32x16_bf16 v[16:31], v[190:193], v[194:197], v[16:31]
	v_mfma_f32_32x32x16_bf16 v[0:15], v[190:193], v[198:201], v[0:15]
	s_waitcnt vmcnt(0) lgkmcnt(0)
	s_barrier
	v_lshl_or_b32 v227, v143, 1, s98
	v_lshl_add_u32 v229, v147, 1, s98
	v_add_u32_e32 v228, v227, v173
	v_add_u32_e32 v230, v229, v173
	ds_read_b128 v[178:181], v228
	ds_read_b128 v[182:185], v228 offset:4096
	ds_read_b128 v[186:189], v228 offset:8192
	ds_read_b128 v[190:193], v228 offset:12288
	ds_read_b128 v[194:197], v230 offset:32768
	ds_read_b128 v[198:201], v230 offset:36864
	v_add3_u32 v226, s15, v162, v156
	v_mfma_f32_32x32x16_bf16 v[112:127], v[202:205], v[218:221], v[112:127]
	v_readfirstlane_b32 s99, v226
	s_mov_b32 s16, m0
	s_mov_b32 m0, s99
	s_nop 0
	global_load_lds_dwordx4 v[158:159], off
	v_mfma_f32_32x32x16_bf16 v[96:111], v[202:205], v[222:225], v[96:111]
	v_mfma_f32_32x32x16_bf16 v[80:95], v[206:209], v[218:221], v[80:95]
	v_lshl_add_u64 v[232:233], v[158:159], 0, s[2:3]
	s_add_i32 m0, s99, 0x2000
	s_nop 0
	global_load_lds_dwordx4 v[232:233], off
	v_mfma_f32_32x32x16_bf16 v[64:79], v[206:209], v[222:225], v[64:79]
	v_mfma_f32_32x32x16_bf16 v[48:63], v[210:213], v[218:221], v[48:63]
	v_lshl_add_u64 v[234:235], v[158:159], 0, s[4:5]
	s_add_i32 m0, s99, 0x4000
	s_nop 0
	global_load_lds_dwordx4 v[234:235], off
	v_mfma_f32_32x32x16_bf16 v[32:47], v[210:213], v[222:225], v[32:47]
	v_mfma_f32_32x32x16_bf16 v[16:31], v[214:217], v[218:221], v[16:31]
	v_lshl_add_u64 v[232:233], v[158:159], 0, s[6:7]
	s_add_i32 m0, s99, 0x6000
	s_nop 0
	global_load_lds_dwordx4 v[232:233], off
	s_mov_b32 m0, s16
	v_mfma_f32_32x32x16_bf16 v[0:15], v[214:217], v[222:225], v[0:15]
	v_add_u32_e32 v228, v227, v174
	v_add_u32_e32 v230, v229, v174
	ds_read_b128 v[202:205], v228
	ds_read_b128 v[206:209], v228 offset:4096
	ds_read_b128 v[210:213], v228 offset:8192
	ds_read_b128 v[214:217], v228 offset:12288
	ds_read_b128 v[218:221], v230 offset:32768
	ds_read_b128 v[222:225], v230 offset:36864
	s_add_i32 s11, s11, 0x8000
	v_lshl_add_u64 v[158:159], v[158:159], 0, s[8:9]
	s_cmp_eq_u32 s11, 0xf8000
	s_cbranch_scc0 .Lrot723_loop
; template <int EPI, int PN>
; __device__ void gemm_phase(const Params& p, const u16* __restrict__ A, const u16* __restrict__ Bt, int nNt, char* smem) {
;     ...
;     for (int kt = 0; kt < 32; ++kt) {
;       asm volatile("s_waitcnt vmcnt(0)" ::: "memory");
;       __builtin_amdgcn_s_barrier();
;       const u16* Ab = ring + (kt & 1) * STG;
;       const u16* Bb = Ab + 16384;
;       u16* st = ring + ((kt + 1) & 1) * STG;
;       const bool pre = (kt + 1 < 32);
;       s16x8 af[2][4], bf[2][2];
;       auto ldfrag = [&](int ks, int slot) {
; #pragma unroll
;         for (int i = 0; i < 4; ++i) {
;           const int row = wr * 128 + i * 32 + lr;
;           af[slot][i] = *(const s16x8*)(Ab + row * 64 + (((ks * 2 + lh) ^ ((row >> 1) & 7)) * 8));
;         }
; #pragma unroll
;         for (int j = 0; j < 2; ++j) {
;           const int rowb = nh * 128 + wc * 64 + j * 32 + lr;
;           bf[slot][j] = *(const s16x8*)(Bb + rowb * 64 + (((ks * 2 + lh) ^ ((rowb >> 1) & 7)) * 8));
;         }
;       };
;       ldfrag(0, 0);
;       ldfrag(1, 1);
;       __builtin_amdgcn_sched_barrier(0);
; #pragma unroll
;       for (int ks = 0; ks < 4; ++ks) {
;         const int slot = ks & 1;
; #pragma unroll
;         for (int i = 0; i < 4; ++i) {
;           acc[i][0] = mfma32(af[slot][i], bf[slot][0], acc[i][0]);
;           acc[i][1] = mfma32(af[slot][i], bf[slot][1], acc[i][1]);
;           __builtin_amdgcn_sched_barrier(0);
;           if (pre && (i & 1) == 0) {
;             const int pi = ks * 2 + (i >> 1);
;             if (pi < 4) glds16(Ag0 + (size_t)pi * 64 * LDK + (kt + 1) * 64, st + (srow + 64 * pi) * 64 + sch * 8);
;             else glds16(Bg0 + (size_t)(pi - 4) * 64 * LDK + (kt + 1) * 64, st + 16384 + (srow + 64 * (pi - 4)) * 64 + sch * 8);
;             __builtin_amdgcn_sched_barrier(0);
;           }
;         }
;         if (ks + 2 < 4) { ldfrag(ks + 2, slot); __builtin_amdgcn_sched_barrier(0); }
;       }
	s_add_i32 s15, s11, 0xffff8000
	s_and_b32 s15, s15, 0x8000
	s_lshl_b32 s15, s15, 1
	v_lshl_or_b32 v128, v143, 1, s15
	v_lshl_add_u32 v149, v147, 1, s15
	s_and_b32 s98, s11, 0x8000
	s_lshl_b32 s98, s98, 1
	s_waitcnt lgkmcnt(7)
	v_mfma_f32_32x32x16_bf16 v[112:127], v[178:181], v[194:197], v[112:127]
	v_add3_u32 v226, s98, v162, v156
	s_waitcnt lgkmcnt(6)
	v_mfma_f32_32x32x16_bf16 v[96:111], v[178:181], v[198:201], v[96:111]
	v_readfirstlane_b32 s100, v226
	s_mov_b32 s16, m0
	s_add_i32 m0, s100, 0x8000
	s_nop 0
	global_load_lds_dwordx4 v[160:161], off
	v_mfma_f32_32x32x16_bf16 v[80:95], v[182:185], v[194:197], v[80:95]
	v_mfma_f32_32x32x16_bf16 v[64:79], v[182:185], v[198:201], v[64:79]
	v_lshl_add_u64 v[178:179], v[160:161], 0, s[2:3]
	s_add_i32 m0, s100, 0xa000
	s_nop 0
	global_load_lds_dwordx4 v[178:179], off
	v_mfma_f32_32x32x16_bf16 v[48:63], v[186:189], v[194:197], v[48:63]
	v_mfma_f32_32x32x16_bf16 v[32:47], v[186:189], v[198:201], v[32:47]
	v_lshl_add_u64 v[180:181], v[160:161], 0, s[4:5]
	s_add_i32 m0, s100, 0xc000
	s_nop 0
	global_load_lds_dwordx4 v[180:181], off
	v_mfma_f32_32x32x16_bf16 v[16:31], v[190:193], v[194:197], v[16:31]
	v_mfma_f32_32x32x16_bf16 v[0:15], v[190:193], v[198:201], v[0:15]
	v_lshl_add_u64 v[178:179], v[160:161], 0, s[6:7]
	s_add_i32 m0, s100, 0xe000
	s_nop 0
	global_load_lds_dwordx4 v[178:179], off
	s_mov_b32 m0, s16
	v_lshl_add_u64 v[160:161], v[160:161], 0, s[8:9]
	v_add_u32_e32 v177, v128, v175
	ds_read_b128 v[178:181], v177
	ds_read_b128 v[182:185], v177 offset:4096
	ds_read_b128 v[186:189], v177 offset:8192
	ds_read_b128 v[190:193], v177 offset:12288
	v_add_u32_e32 v177, v149, v175
	ds_read_b128 v[194:197], v177 offset:32768
	ds_read_b128 v[198:201], v177 offset:36864
	s_waitcnt lgkmcnt(7)
	v_mfma_f32_32x32x16_bf16 v[112:127], v[202:205], v[218:221], v[112:127]
	s_waitcnt lgkmcnt(6)
	v_mfma_f32_32x32x16_bf16 v[96:111], v[202:205], v[222:225], v[96:111]
	v_mfma_f32_32x32x16_bf16 v[80:95], v[206:209], v[218:221], v[80:95]
	v_mfma_f32_32x32x16_bf16 v[64:79], v[206:209], v[222:225], v[64:79]
	v_mfma_f32_32x32x16_bf16 v[48:63], v[210:213], v[218:221], v[48:63]
	v_mfma_f32_32x32x16_bf16 v[32:47], v[210:213], v[222:225], v[32:47]
	v_mfma_f32_32x32x16_bf16 v[16:31], v[214:217], v[218:221], v[16:31]
	v_mfma_f32_32x32x16_bf16 v[0:15], v[214:217], v[222:225], v[0:15]
	v_add_u32_e32 v128, v128, v176
	ds_read_b128 v[202:205], v128
	ds_read_b128 v[206:209], v128 offset:4096
	ds_read_b128 v[210:213], v128 offset:8192
	ds_read_b128 v[214:217], v128 offset:12288
	v_add_u32_e32 v128, v149, v176
	ds_read_b128 v[218:221], v128 offset:32768
	ds_read_b128 v[222:225], v128 offset:36864
	s_waitcnt lgkmcnt(7)
	v_mfma_f32_32x32x16_bf16 v[112:127], v[178:181], v[194:197], v[112:127]
	s_waitcnt lgkmcnt(6)
	v_mfma_f32_32x32x16_bf16 v[96:111], v[178:181], v[198:201], v[96:111]
	v_mfma_f32_32x32x16_bf16 v[80:95], v[182:185], v[194:197], v[80:95]
	v_mfma_f32_32x32x16_bf16 v[64:79], v[182:185], v[198:201], v[64:79]
	v_mfma_f32_32x32x16_bf16 v[48:63], v[186:189], v[194:197], v[48:63]
	v_mfma_f32_32x32x16_bf16 v[32:47], v[186:189], v[198:201], v[32:47]
	v_mfma_f32_32x32x16_bf16 v[16:31], v[190:193], v[194:197], v[16:31]
	v_mfma_f32_32x32x16_bf16 v[0:15], v[190:193], v[198:201], v[0:15]
	s_waitcnt lgkmcnt(1)
	v_mfma_f32_32x32x16_bf16 v[112:127], v[202:205], v[218:221], v[112:127]
	s_waitcnt lgkmcnt(0)
	v_mfma_f32_32x32x16_bf16 v[96:111], v[202:205], v[222:225], v[96:111]
	v_mfma_f32_32x32x16_bf16 v[80:95], v[206:209], v[218:221], v[80:95]
	v_mfma_f32_32x32x16_bf16 v[64:79], v[206:209], v[222:225], v[64:79]
	v_mfma_f32_32x32x16_bf16 v[48:63], v[210:213], v[218:221], v[48:63]
	v_mfma_f32_32x32x16_bf16 v[32:47], v[210:213], v[222:225], v[32:47]
	v_mfma_f32_32x32x16_bf16 v[16:31], v[214:217], v[218:221], v[16:31]
	v_mfma_f32_32x32x16_bf16 v[0:15], v[214:217], v[222:225], v[0:15]
	s_waitcnt vmcnt(0)
	s_barrier
	ds_read_b128 v[158:161], v164
	ds_read_b128 v[178:181], v164 offset:4096
	ds_read_b128 v[182:185], v164 offset:8192
	ds_read_b128 v[186:189], v164 offset:12288
	ds_read_b128 v[190:193], v165
	ds_read_b128 v[194:197], v165 offset:4096
	ds_read_b128 v[198:201], v166
	ds_read_b128 v[202:205], v166 offset:4096
	ds_read_b128 v[206:209], v166 offset:8192
	ds_read_b128 v[210:213], v166 offset:12288
	ds_read_b128 v[214:217], v168
	ds_read_b128 v[218:221], v168 offset:4096
	s_waitcnt lgkmcnt(7)
	v_mfma_f32_32x32x16_bf16 v[112:127], v[158:161], v[190:193], v[112:127]
	s_waitcnt lgkmcnt(6)
	v_mfma_f32_32x32x16_bf16 v[96:111], v[158:161], v[194:197], v[96:111]
	v_mfma_f32_32x32x16_bf16 v[80:95], v[178:181], v[190:193], v[80:95]
	v_mfma_f32_32x32x16_bf16 v[64:79], v[178:181], v[194:197], v[64:79]
	v_mfma_f32_32x32x16_bf16 v[48:63], v[182:185], v[190:193], v[48:63]
	v_mfma_f32_32x32x16_bf16 v[32:47], v[182:185], v[194:197], v[32:47]
	v_mfma_f32_32x32x16_bf16 v[16:31], v[186:189], v[190:193], v[16:31]
	v_mfma_f32_32x32x16_bf16 v[0:15], v[186:189], v[194:197], v[0:15]
	ds_read_b128 v[158:161], v169
	ds_read_b128 v[178:181], v169 offset:4096
	ds_read_b128 v[182:185], v169 offset:8192
	ds_read_b128 v[186:189], v169 offset:12288
	ds_read_b128 v[190:193], v170
	ds_read_b128 v[194:197], v170 offset:4096
	s_waitcnt lgkmcnt(7)
	v_mfma_f32_32x32x16_bf16 v[112:127], v[198:201], v[214:217], v[112:127]
	s_waitcnt lgkmcnt(6)
; __device__ __forceinline__ int accrow(int reg, int lh) { return (reg & 3) + 8 * (reg >> 2) + 4 * lh; }
; template <int EPI, int PN>
; __device__ void gemm_phase(const Params& p, const u16* __restrict__ A, const u16* __restrict__ Bt, int nNt, char* smem) {
;     ...
;         for (int i = 0; i < 4; ++i) {
;           acc[i][0] = mfma32(af[slot][i], bf[slot][0], acc[i][0]);
;           acc[i][1] = mfma32(af[slot][i], bf[slot][1], acc[i][1]);
;     ...
;     } else {
; #pragma unroll
;       for (int i = 0; i < 4; ++i)
; #pragma unroll
;         for (int j = 0; j < 2; ++j)
; #pragma unroll
;           for (int r = 0; r < 16; ++r) *(u16*)(et + (i * 32 + accrow(r, lhE)) * 144 + (j * 32 + lrE) * 2) = f2bf(acc[i][j][r]);
	v_mfma_f32_32x32x16_bf16 v[96:111], v[198:201], v[218:221], v[96:111]
	v_mfma_f32_32x32x16_bf16 v[80:95], v[202:205], v[214:217], v[80:95]
	v_mfma_f32_32x32x16_bf16 v[64:79], v[202:205], v[218:221], v[64:79]
	v_mfma_f32_32x32x16_bf16 v[48:63], v[206:209], v[214:217], v[48:63]
	v_mfma_f32_32x32x16_bf16 v[32:47], v[206:209], v[218:221], v[32:47]
	v_mfma_f32_32x32x16_bf16 v[16:31], v[210:213], v[214:217], v[16:31]
	v_mfma_f32_32x32x16_bf16 v[0:15], v[210:213], v[218:221], v[0:15]
	ds_read_b128 v[198:201], v171
	ds_read_b128 v[202:205], v171 offset:4096
	ds_read_b128 v[206:209], v171 offset:8192
	ds_read_b128 v[210:213], v171 offset:12288
	ds_read_b128 v[214:217], v172
	ds_read_b128 v[218:221], v172 offset:4096
	s_waitcnt lgkmcnt(7)
	v_mfma_f32_32x32x16_bf16 v[112:127], v[158:161], v[190:193], v[112:127]
	s_waitcnt lgkmcnt(6)
	v_mfma_f32_32x32x16_bf16 v[96:111], v[158:161], v[194:197], v[96:111]
	v_mfma_f32_32x32x16_bf16 v[80:95], v[178:181], v[190:193], v[80:95]
	v_mfma_f32_32x32x16_bf16 v[64:79], v[178:181], v[194:197], v[64:79]
	v_mfma_f32_32x32x16_bf16 v[48:63], v[182:185], v[190:193], v[48:63]
	v_mfma_f32_32x32x16_bf16 v[32:47], v[182:185], v[194:197], v[32:47]
	v_mfma_f32_32x32x16_bf16 v[16:31], v[186:189], v[190:193], v[16:31]
	v_mfma_f32_32x32x16_bf16 v[0:15], v[186:189], v[194:197], v[0:15]
	s_waitcnt lgkmcnt(1)
	v_mfma_f32_32x32x16_bf16 v[112:127], v[198:201], v[214:217], v[112:127]
	s_waitcnt lgkmcnt(0)
	v_mfma_f32_32x32x16_bf16 v[96:111], v[198:201], v[218:221], v[96:111]
	v_mfma_f32_32x32x16_bf16 v[80:95], v[202:205], v[214:217], v[80:95]
	v_mfma_f32_32x32x16_bf16 v[64:79], v[202:205], v[218:221], v[64:79]
	v_mfma_f32_32x32x16_bf16 v[48:63], v[206:209], v[214:217], v[48:63]
	v_mfma_f32_32x32x16_bf16 v[32:47], v[206:209], v[218:221], v[32:47]
	v_mfma_f32_32x32x16_bf16 v[16:31], v[210:213], v[214:217], v[16:31]
	v_mfma_f32_32x32x16_bf16 v[0:15], v[210:213], v[218:221], v[0:15]
	v_mov_b32_e32 v149, v135
	v_mov_b32_e32 v128, v139
	v_mov_b32_e32 v158, v137
	s_barrier
	s_nop 7
	v_cvt_pk_bf16_f32 v0, v0, s0
	v_lshlrev_b32_e32 v158, 1, v158
	v_mul_lo_u32 v128, v128, s12
	v_add3_u32 v128, v163, v158, v128
	v_cvt_pk_bf16_f32 v112, v112, s0
	v_cvt_pk_bf16_f32 v96, v96, s0
	v_cvt_pk_bf16_f32 v80, v80, s0
	v_cvt_pk_bf16_f32 v64, v64, s0
	v_cvt_pk_bf16_f32 v48, v48, s0
	v_cvt_pk_bf16_f32 v32, v32, s0
	v_cvt_pk_bf16_f32 v16, v16, s0
	ds_write_b16 v128, v0 offset:13888
	v_cvt_pk_bf16_f32 v0, v1, s0
	ds_write_b16 v128, v112
	v_cvt_pk_bf16_f32 v112, v113, s0
	ds_write_b16 v128, v96 offset:64
	v_cvt_pk_bf16_f32 v96, v97, s0
	ds_write_b16 v128, v80 offset:4608
	v_cvt_pk_bf16_f32 v80, v81, s0
	ds_write_b16 v128, v64 offset:4672
	v_cvt_pk_bf16_f32 v64, v65, s0
	ds_write_b16 v128, v48 offset:9216
	v_cvt_pk_bf16_f32 v48, v49, s0
	ds_write_b16 v128, v32 offset:9280
	v_cvt_pk_bf16_f32 v32, v33, s0
	ds_write_b16 v128, v16 offset:13824
	v_cvt_pk_bf16_f32 v16, v17, s0
	ds_write_b16 v128, v0 offset:14032
	v_cvt_pk_bf16_f32 v0, v2, s0
	ds_write_b16 v128, v112 offset:144
	v_cvt_pk_bf16_f32 v112, v114, s0
	ds_write_b16 v128, v96 offset:208
	v_cvt_pk_bf16_f32 v96, v98, s0
	ds_write_b16 v128, v80 offset:4752
	v_cvt_pk_bf16_f32 v80, v82, s0
	ds_write_b16 v128, v64 offset:4816
	v_cvt_pk_bf16_f32 v64, v66, s0
	ds_write_b16 v128, v48 offset:9360
	v_cvt_pk_bf16_f32 v48, v50, s0
	ds_write_b16 v128, v32 offset:9424
	v_cvt_pk_bf16_f32 v32, v34, s0
	ds_write_b16 v128, v16 offset:13968
	v_cvt_pk_bf16_f32 v16, v18, s0
	ds_write_b16 v128, v0 offset:14176
	v_cvt_pk_bf16_f32 v0, v3, s0
	ds_write_b16 v128, v112 offset:288
	v_cvt_pk_bf16_f32 v112, v115, s0
	ds_write_b16 v128, v96 offset:352
	v_cvt_pk_bf16_f32 v96, v99, s0
	ds_write_b16 v128, v80 offset:4896
	v_cvt_pk_bf16_f32 v80, v83, s0
	ds_write_b16 v128, v64 offset:4960
	v_cvt_pk_bf16_f32 v64, v67, s0
	ds_write_b16 v128, v48 offset:9504
	v_cvt_pk_bf16_f32 v48, v51, s0
	ds_write_b16 v128, v32 offset:9568
	v_cvt_pk_bf16_f32 v32, v35, s0
	ds_write_b16 v128, v16 offset:14112
	v_cvt_pk_bf16_f32 v16, v19, s0
	ds_write_b16 v128, v0 offset:14320
	v_cvt_pk_bf16_f32 v0, v4, s0
	ds_write_b16 v128, v112 offset:432
	v_cvt_pk_bf16_f32 v112, v116, s0
	ds_write_b16 v128, v96 offset:496
	v_cvt_pk_bf16_f32 v96, v100, s0
	ds_write_b16 v128, v80 offset:5040
	v_cvt_pk_bf16_f32 v80, v84, s0
	ds_write_b16 v128, v64 offset:5104
	v_cvt_pk_bf16_f32 v64, v68, s0
	ds_write_b16 v128, v48 offset:9648
	v_cvt_pk_bf16_f32 v48, v52, s0
	ds_write_b16 v128, v32 offset:9712
	v_cvt_pk_bf16_f32 v32, v36, s0
	ds_write_b16 v128, v16 offset:14256
	v_cvt_pk_bf16_f32 v16, v20, s0
	ds_write_b16 v128, v0 offset:15040
	v_cvt_pk_bf16_f32 v0, v5, s0
	ds_write_b16 v128, v112 offset:1152
	v_cvt_pk_bf16_f32 v112, v117, s0
	ds_write_b16 v128, v96 offset:1216
	v_cvt_pk_bf16_f32 v96, v101, s0
	ds_write_b16 v128, v80 offset:5760
	v_cvt_pk_bf16_f32 v80, v85, s0
	ds_write_b16 v128, v64 offset:5824
	v_cvt_pk_bf16_f32 v64, v69, s0
	ds_write_b16 v128, v48 offset:10368
	v_cvt_pk_bf16_f32 v48, v53, s0
	ds_write_b16 v128, v32 offset:10432
	v_cvt_pk_bf16_f32 v32, v37, s0
	ds_write_b16 v128, v16 offset:14976
	v_cvt_pk_bf16_f32 v16, v21, s0
	ds_write_b16 v128, v0 offset:15184
	v_cvt_pk_bf16_f32 v0, v6, s0
	ds_write_b16 v128, v112 offset:1296
	v_cvt_pk_bf16_f32 v112, v118, s0
	ds_write_b16 v128, v96 offset:1360
	v_cvt_pk_bf16_f32 v96, v102, s0
	ds_write_b16 v128, v80 offset:5904
	v_cvt_pk_bf16_f32 v80, v86, s0
	ds_write_b16 v128, v64 offset:5968
	v_cvt_pk_bf16_f32 v64, v70, s0
	ds_write_b16 v128, v48 offset:10512
	v_cvt_pk_bf16_f32 v48, v54, s0
	ds_write_b16 v128, v32 offset:10576
	v_cvt_pk_bf16_f32 v32, v38, s0
	ds_write_b16 v128, v16 offset:15120
	v_cvt_pk_bf16_f32 v16, v22, s0
; __device__ __forceinline__ int accrow(int reg, int lh) { return (reg & 3) + 8 * (reg >> 2) + 4 * lh; }
; template <int EPI, int PN>
; __device__ void gemm_phase(const Params& p, const u16* __restrict__ A, const u16* __restrict__ Bt, int nNt, char* smem) {
;     ...
;           for (int r = 0; r < 16; ++r) *(u16*)(et + (i * 32 + accrow(r, lhE)) * 144 + (j * 32 + lrE) * 2) = f2bf(acc[i][j][r]);
; #pragma unroll
;       for (int it = 0; it < 16; ++it) {
;         const int c = it * 64 + laneE, row = c >> 3, seg = c & 7;
;         const uint4 v = *(const uint4*)(et + row * 144 + seg * 16);
;         if (EPI == 0) *(uint4*)(p.proj + (row0 + row) * NPROJ + col0 + seg * 8) = v;
;         else *(uint4*)(p.qp + (row0 + row) * DM + col0 + seg * 8) = v;
	ds_write_b16 v128, v0 offset:15328
	v_cvt_pk_bf16_f32 v0, v7, s0
	ds_write_b16 v128, v112 offset:1440
	v_cvt_pk_bf16_f32 v112, v119, s0
	ds_write_b16 v128, v96 offset:1504
	v_cvt_pk_bf16_f32 v96, v103, s0
	ds_write_b16 v128, v80 offset:6048
	v_cvt_pk_bf16_f32 v80, v87, s0
	ds_write_b16 v128, v64 offset:6112
	v_cvt_pk_bf16_f32 v64, v71, s0
	ds_write_b16 v128, v48 offset:10656
	v_cvt_pk_bf16_f32 v48, v55, s0
	ds_write_b16 v128, v32 offset:10720
	v_cvt_pk_bf16_f32 v32, v39, s0
	ds_write_b16 v128, v16 offset:15264
	v_cvt_pk_bf16_f32 v16, v23, s0
	ds_write_b16 v128, v0 offset:15472
	v_cvt_pk_bf16_f32 v0, v8, s0
	ds_write_b16 v128, v112 offset:1584
	v_cvt_pk_bf16_f32 v112, v120, s0
	ds_write_b16 v128, v96 offset:1648
	v_cvt_pk_bf16_f32 v96, v104, s0
	ds_write_b16 v128, v80 offset:6192
	v_cvt_pk_bf16_f32 v80, v88, s0
	ds_write_b16 v128, v64 offset:6256
	v_cvt_pk_bf16_f32 v64, v72, s0
	ds_write_b16 v128, v48 offset:10800
	v_cvt_pk_bf16_f32 v48, v56, s0
	ds_write_b16 v128, v32 offset:10864
	v_cvt_pk_bf16_f32 v32, v40, s0
	ds_write_b16 v128, v16 offset:15408
	v_cvt_pk_bf16_f32 v16, v24, s0
	ds_write_b16 v128, v0 offset:16192
	v_cvt_pk_bf16_f32 v0, v9, s0
	ds_write_b16 v128, v112 offset:2304
	v_cvt_pk_bf16_f32 v112, v121, s0
	ds_write_b16 v128, v96 offset:2368
	v_cvt_pk_bf16_f32 v96, v105, s0
	ds_write_b16 v128, v80 offset:6912
	v_cvt_pk_bf16_f32 v80, v89, s0
	ds_write_b16 v128, v64 offset:6976
	v_cvt_pk_bf16_f32 v64, v73, s0
	ds_write_b16 v128, v48 offset:11520
	v_cvt_pk_bf16_f32 v48, v57, s0
	ds_write_b16 v128, v32 offset:11584
	v_cvt_pk_bf16_f32 v32, v41, s0
	ds_write_b16 v128, v16 offset:16128
	v_cvt_pk_bf16_f32 v16, v25, s0
	ds_write_b16 v128, v0 offset:16336
	v_cvt_pk_bf16_f32 v0, v10, s0
	ds_write_b16 v128, v112 offset:2448
	v_cvt_pk_bf16_f32 v112, v122, s0
	ds_write_b16 v128, v96 offset:2512
	v_cvt_pk_bf16_f32 v96, v106, s0
	ds_write_b16 v128, v80 offset:7056
	v_cvt_pk_bf16_f32 v80, v90, s0
	ds_write_b16 v128, v64 offset:7120
	v_cvt_pk_bf16_f32 v64, v74, s0
	ds_write_b16 v128, v48 offset:11664
	v_cvt_pk_bf16_f32 v48, v58, s0
	ds_write_b16 v128, v32 offset:11728
	v_cvt_pk_bf16_f32 v32, v42, s0
	ds_write_b16 v128, v16 offset:16272
	v_cvt_pk_bf16_f32 v16, v26, s0
	ds_write_b16 v128, v0 offset:16480
	v_cvt_pk_bf16_f32 v0, v11, s0
	ds_write_b16 v128, v112 offset:2592
	v_cvt_pk_bf16_f32 v112, v123, s0
	ds_write_b16 v128, v96 offset:2656
	v_cvt_pk_bf16_f32 v96, v107, s0
	ds_write_b16 v128, v80 offset:7200
	v_cvt_pk_bf16_f32 v80, v91, s0
	ds_write_b16 v128, v64 offset:7264
	v_cvt_pk_bf16_f32 v64, v75, s0
	ds_write_b16 v128, v48 offset:11808
	v_cvt_pk_bf16_f32 v48, v59, s0
	ds_write_b16 v128, v32 offset:11872
	v_cvt_pk_bf16_f32 v32, v43, s0
	ds_write_b16 v128, v16 offset:16416
	v_cvt_pk_bf16_f32 v16, v27, s0
	ds_write_b16 v128, v0 offset:16624
	v_cvt_pk_bf16_f32 v0, v12, s0
	ds_write_b16 v128, v112 offset:2736
	v_cvt_pk_bf16_f32 v112, v124, s0
	ds_write_b16 v128, v96 offset:2800
	v_cvt_pk_bf16_f32 v96, v108, s0
	ds_write_b16 v128, v80 offset:7344
	v_cvt_pk_bf16_f32 v80, v92, s0
	ds_write_b16 v128, v64 offset:7408
	v_cvt_pk_bf16_f32 v64, v76, s0
	ds_write_b16 v128, v48 offset:11952
	v_cvt_pk_bf16_f32 v48, v60, s0
	ds_write_b16 v128, v32 offset:12016
	v_cvt_pk_bf16_f32 v32, v44, s0
	ds_write_b16 v128, v16 offset:16560
	v_cvt_pk_bf16_f32 v16, v28, s0
	ds_write_b16 v128, v0 offset:17344
	v_cvt_pk_bf16_f32 v0, v13, s0
	ds_write_b16 v128, v112 offset:3456
	v_cvt_pk_bf16_f32 v112, v125, s0
	ds_write_b16 v128, v96 offset:3520
	v_cvt_pk_bf16_f32 v96, v109, s0
	ds_write_b16 v128, v80 offset:8064
	v_cvt_pk_bf16_f32 v80, v93, s0
	ds_write_b16 v128, v64 offset:8128
	v_cvt_pk_bf16_f32 v64, v77, s0
	ds_write_b16 v128, v48 offset:12672
	v_cvt_pk_bf16_f32 v48, v61, s0
	ds_write_b16 v128, v32 offset:12736
	v_cvt_pk_bf16_f32 v32, v45, s0
	ds_write_b16 v128, v16 offset:17280
	v_cvt_pk_bf16_f32 v16, v29, s0
	ds_write_b16 v128, v0 offset:17488
	v_cvt_pk_bf16_f32 v0, v14, s0
	ds_write_b16 v128, v112 offset:3600
	v_cvt_pk_bf16_f32 v112, v126, s0
	ds_write_b16 v128, v96 offset:3664
	v_cvt_pk_bf16_f32 v96, v110, s0
	ds_write_b16 v128, v80 offset:8208
	v_cvt_pk_bf16_f32 v80, v94, s0
	ds_write_b16 v128, v64 offset:8272
	v_cvt_pk_bf16_f32 v64, v78, s0
	ds_write_b16 v128, v48 offset:12816
	v_cvt_pk_bf16_f32 v48, v62, s0
	ds_write_b16 v128, v32 offset:12880
	v_cvt_pk_bf16_f32 v32, v46, s0
	ds_write_b16 v128, v16 offset:17424
	v_cvt_pk_bf16_f32 v16, v30, s0
	ds_write_b16 v128, v0 offset:17632
	v_cvt_pk_bf16_f32 v0, v15, s0
	s_ashr_i32 s11, s10, 31
	ds_write_b16 v128, v112 offset:3744
	v_cvt_pk_bf16_f32 v112, v127, s0
	ds_write_b16 v128, v96 offset:3808
	v_cvt_pk_bf16_f32 v96, v111, s0
	ds_write_b16 v128, v80 offset:8352
	v_cvt_pk_bf16_f32 v80, v95, s0
	ds_write_b16 v128, v64 offset:8416
	v_cvt_pk_bf16_f32 v64, v79, s0
	ds_write_b16 v128, v48 offset:12960
	v_cvt_pk_bf16_f32 v48, v63, s0
	ds_write_b16 v128, v32 offset:13024
	v_cvt_pk_bf16_f32 v32, v47, s0
	ds_write_b16 v128, v16 offset:17568
	v_cvt_pk_bf16_f32 v16, v31, s0
	ds_write_b16 v128, v0 offset:17776
	v_lshlrev_b32_e32 v0, 4, v149
	s_lshl_b64 s[10:11], s[10:11], 8
	ds_write_b16 v128, v112 offset:3888
	ds_write_b16 v128, v96 offset:3952
	ds_write_b16 v128, v80 offset:8496
	ds_write_b16 v128, v64 offset:8560
	ds_write_b16 v128, v48 offset:13104
	ds_write_b16 v128, v32 offset:13168
	ds_write_b16 v128, v16 offset:17712
	v_and_b32_e32 v128, 0x70, v0
	v_ashrrev_i32_e32 v6, 3, v149
	v_mov_b32_e32 v9, s11
	v_or_b32_e32 v8, s10, v134
	v_add_u32_e32 v10, v163, v128
	v_ashrrev_i32_e32 v7, 31, v6
	v_lshl_add_u32 v4, s14, 8, v145
	v_mad_u64_u32 v[0:1], s[10:11], v6, s13, v[10:11]
	v_lshl_add_u64 v[6:7], v[8:9], 0, v[6:7]
	v_readlane_b32 s16, v253, 39
	v_ashrrev_i32_e32 v5, 31, v4
	v_lshlrev_b64 v[6:7], 12, v[6:7]
	v_readlane_b32 s26, v253, 49
	v_readlane_b32 s27, v253, 50
	ds_read_b128 v[0:3], v0
	v_lshlrev_b64 v[12:13], 1, v[4:5]
	v_lshl_add_u64 v[6:7], s[26:27], 0, v[6:7]
	v_lshl_add_u64 v[4:5], v[6:7], 0, v[12:13]
	v_lshl_add_u64 v[14:15], v[4:5], 0, v[128:129]
	v_add_u32_e32 v4, 64, v149
	v_ashrrev_i32_e32 v16, 3, v4
	v_mad_u64_u32 v[4:5], s[10:11], v16, s13, v[10:11]
	v_ashrrev_i32_e32 v17, 31, v16
	ds_read_b128 v[4:7], v4
	s_waitcnt lgkmcnt(1)
; template <int EPI, int PN>
; __device__ void gemm_phase(const Params& p, const u16* __restrict__ A, const u16* __restrict__ Bt, int nNt, char* smem) {
;     ...
;       for (int it = 0; it < 16; ++it) {
;         const int c = it * 64 + laneE, row = c >> 3, seg = c & 7;
;         const uint4 v = *(const uint4*)(et + row * 144 + seg * 16);
;         if (EPI == 0) *(uint4*)(p.proj + (row0 + row) * NPROJ + col0 + seg * 8) = v;
;         else *(uint4*)(p.qp + (row0 + row) * DM + col0 + seg * 8) = v;
;       }
	global_store_dwordx4 v[14:15], v[0:3], off
	v_readlane_b32 s17, v253, 40
	v_readlane_b32 s18, v253, 41
	v_lshl_add_u64 v[0:1], v[8:9], 0, v[16:17]
	v_lshlrev_b64 v[0:1], 12, v[0:1]
	v_lshl_add_u64 v[0:1], s[26:27], 0, v[0:1]
	v_lshl_add_u64 v[0:1], v[0:1], 0, v[12:13]
	v_lshl_add_u64 v[0:1], v[0:1], 0, v[128:129]
	s_waitcnt lgkmcnt(0)
	global_store_dwordx4 v[0:1], v[4:7], off
	v_add_u32_e32 v0, 0x80, v149
	v_readlane_b32 s19, v253, 42
	v_ashrrev_i32_e32 v4, 3, v0
	v_ashrrev_i32_e32 v5, 31, v4
	v_mad_u64_u32 v[0:1], s[10:11], v4, s13, v[10:11]
	v_lshl_add_u64 v[4:5], v[8:9], 0, v[4:5]
	v_lshlrev_b64 v[4:5], 12, v[4:5]
	ds_read_b128 v[0:3], v0
	v_lshl_add_u64 v[4:5], s[26:27], 0, v[4:5]
	v_lshl_add_u64 v[4:5], v[4:5], 0, v[12:13]
	v_lshl_add_u64 v[14:15], v[4:5], 0, v[128:129]
	v_add_u32_e32 v4, 0xc0, v149
	v_ashrrev_i32_e32 v16, 3, v4
	v_mad_u64_u32 v[4:5], s[10:11], v16, s13, v[10:11]
	v_ashrrev_i32_e32 v17, 31, v16
	ds_read_b128 v[4:7], v4
	s_waitcnt lgkmcnt(1)
	global_store_dwordx4 v[14:15], v[0:3], off
	v_readlane_b32 s20, v253, 43
	v_readlane_b32 s21, v253, 44
	v_lshl_add_u64 v[0:1], v[8:9], 0, v[16:17]
	v_lshlrev_b64 v[0:1], 12, v[0:1]
	v_lshl_add_u64 v[0:1], s[26:27], 0, v[0:1]
	v_lshl_add_u64 v[0:1], v[0:1], 0, v[12:13]
	v_lshl_add_u64 v[0:1], v[0:1], 0, v[128:129]
	s_waitcnt lgkmcnt(0)
	global_store_dwordx4 v[0:1], v[4:7], off
	v_add_u32_e32 v0, 0x100, v149
	v_readlane_b32 s22, v253, 45
	v_ashrrev_i32_e32 v4, 3, v0
	v_ashrrev_i32_e32 v5, 31, v4
	v_mad_u64_u32 v[0:1], s[10:11], v4, s13, v[10:11]
	v_lshl_add_u64 v[4:5], v[8:9], 0, v[4:5]
	v_lshlrev_b64 v[4:5], 12, v[4:5]
	ds_read_b128 v[0:3], v0
	v_lshl_add_u64 v[4:5], s[26:27], 0, v[4:5]
	v_lshl_add_u64 v[4:5], v[4:5], 0, v[12:13]
	v_lshl_add_u64 v[14:15], v[4:5], 0, v[128:129]
	v_add_u32_e32 v4, 0x140, v149
	v_ashrrev_i32_e32 v16, 3, v4
	v_mad_u64_u32 v[4:5], s[10:11], v16, s13, v[10:11]
	v_ashrrev_i32_e32 v17, 31, v16
	ds_read_b128 v[4:7], v4
	s_waitcnt lgkmcnt(1)
	global_store_dwordx4 v[14:15], v[0:3], off
	v_readlane_b32 s23, v253, 46
	v_readlane_b32 s24, v253, 47
	v_lshl_add_u64 v[0:1], v[8:9], 0, v[16:17]
	v_lshlrev_b64 v[0:1], 12, v[0:1]
	v_lshl_add_u64 v[0:1], s[26:27], 0, v[0:1]
	v_lshl_add_u64 v[0:1], v[0:1], 0, v[12:13]
	v_lshl_add_u64 v[0:1], v[0:1], 0, v[128:129]
	s_waitcnt lgkmcnt(0)
	global_store_dwordx4 v[0:1], v[4:7], off
	v_add_u32_e32 v0, 0x180, v149
	v_readlane_b32 s25, v253, 48
	v_ashrrev_i32_e32 v4, 3, v0
	v_ashrrev_i32_e32 v5, 31, v4
	v_mad_u64_u32 v[0:1], s[10:11], v4, s13, v[10:11]
	v_lshl_add_u64 v[4:5], v[8:9], 0, v[4:5]
	v_lshlrev_b64 v[4:5], 12, v[4:5]
	ds_read_b128 v[0:3], v0
	v_lshl_add_u64 v[4:5], s[26:27], 0, v[4:5]
	v_lshl_add_u64 v[4:5], v[4:5], 0, v[12:13]
	v_lshl_add_u64 v[14:15], v[4:5], 0, v[128:129]
	v_add_u32_e32 v4, 0x1c0, v149
	v_ashrrev_i32_e32 v16, 3, v4
	v_mad_u64_u32 v[4:5], s[10:11], v16, s13, v[10:11]
	v_ashrrev_i32_e32 v17, 31, v16
	ds_read_b128 v[4:7], v4
	s_waitcnt lgkmcnt(1)
	global_store_dwordx4 v[14:15], v[0:3], off
	v_readlane_b32 s28, v253, 51
	v_readlane_b32 s29, v253, 52
	v_lshl_add_u64 v[0:1], v[8:9], 0, v[16:17]
	v_lshlrev_b64 v[0:1], 12, v[0:1]
	v_lshl_add_u64 v[0:1], s[26:27], 0, v[0:1]
	v_lshl_add_u64 v[0:1], v[0:1], 0, v[12:13]
	v_lshl_add_u64 v[0:1], v[0:1], 0, v[128:129]
	s_waitcnt lgkmcnt(0)
	global_store_dwordx4 v[0:1], v[4:7], off
	v_add_u32_e32 v0, 0x200, v149
	v_readlane_b32 s30, v253, 53
	v_ashrrev_i32_e32 v4, 3, v0
	v_ashrrev_i32_e32 v5, 31, v4
	v_mad_u64_u32 v[0:1], s[10:11], v4, s13, v[10:11]
	v_lshl_add_u64 v[4:5], v[8:9], 0, v[4:5]
	v_lshlrev_b64 v[4:5], 12, v[4:5]
	ds_read_b128 v[0:3], v0
	v_lshl_add_u64 v[4:5], s[26:27], 0, v[4:5]
	v_lshl_add_u64 v[4:5], v[4:5], 0, v[12:13]
	v_lshl_add_u64 v[14:15], v[4:5], 0, v[128:129]
	v_add_u32_e32 v4, 0x240, v149
	v_ashrrev_i32_e32 v16, 3, v4
	v_mad_u64_u32 v[4:5], s[10:11], v16, s13, v[10:11]
	v_ashrrev_i32_e32 v17, 31, v16
	ds_read_b128 v[4:7], v4
	s_waitcnt lgkmcnt(1)
; template <int EPI, int PN>
; __device__ void gemm_phase(const Params& p, const u16* __restrict__ A, const u16* __restrict__ Bt, int nNt, char* smem) {
;     ...
;   for (int q = jb;; q += NJ) {
;     const int pl = q / (4 * PN), w = q % (4 * PN);
;     const int gp = pl * 8 + xcd;
;     if (gp >= npatch) break;
;     ...
;       for (int it = 0; it < 16; ++it) {
;         const int c = it * 64 + laneE, row = c >> 3, seg = c & 7;
;         const uint4 v = *(const uint4*)(et + row * 144 + seg * 16);
;         if (EPI == 0) *(uint4*)(p.proj + (row0 + row) * NPROJ + col0 + seg * 8) = v;
;         else *(uint4*)(p.qp + (row0 + row) * DM + col0 + seg * 8) = v;
;       }
;     }
;     __syncthreads();
	global_store_dwordx4 v[14:15], v[0:3], off
	v_readlane_b32 s31, v253, 54
	s_nop 0
	v_lshl_add_u64 v[0:1], v[8:9], 0, v[16:17]
	v_lshlrev_b64 v[0:1], 12, v[0:1]
	v_lshl_add_u64 v[0:1], s[26:27], 0, v[0:1]
	v_lshl_add_u64 v[0:1], v[0:1], 0, v[12:13]
	v_lshl_add_u64 v[0:1], v[0:1], 0, v[128:129]
	s_waitcnt lgkmcnt(0)
	global_store_dwordx4 v[0:1], v[4:7], off
	v_add_u32_e32 v0, 0x280, v149
	s_nop 0
	v_ashrrev_i32_e32 v4, 3, v0
	v_ashrrev_i32_e32 v5, 31, v4
	v_mad_u64_u32 v[0:1], s[10:11], v4, s13, v[10:11]
	v_lshl_add_u64 v[4:5], v[8:9], 0, v[4:5]
	v_lshlrev_b64 v[4:5], 12, v[4:5]
	ds_read_b128 v[0:3], v0
	v_lshl_add_u64 v[4:5], s[26:27], 0, v[4:5]
	v_lshl_add_u64 v[4:5], v[4:5], 0, v[12:13]
	v_lshl_add_u64 v[14:15], v[4:5], 0, v[128:129]
	v_add_u32_e32 v4, 0x2c0, v149
	v_ashrrev_i32_e32 v16, 3, v4
	v_mad_u64_u32 v[4:5], s[10:11], v16, s13, v[10:11]
	v_ashrrev_i32_e32 v17, 31, v16
	ds_read_b128 v[4:7], v4
	s_waitcnt lgkmcnt(1)
	global_store_dwordx4 v[14:15], v[0:3], off
	s_nop 1
	v_lshl_add_u64 v[0:1], v[8:9], 0, v[16:17]
	v_lshlrev_b64 v[0:1], 12, v[0:1]
	v_lshl_add_u64 v[0:1], s[26:27], 0, v[0:1]
	v_lshl_add_u64 v[0:1], v[0:1], 0, v[12:13]
	v_lshl_add_u64 v[0:1], v[0:1], 0, v[128:129]
	s_waitcnt lgkmcnt(0)
	global_store_dwordx4 v[0:1], v[4:7], off
	v_add_u32_e32 v0, 0x300, v149
	s_nop 0
	v_ashrrev_i32_e32 v4, 3, v0
	v_ashrrev_i32_e32 v5, 31, v4
	v_mad_u64_u32 v[0:1], s[10:11], v4, s13, v[10:11]
	v_lshl_add_u64 v[4:5], v[8:9], 0, v[4:5]
	v_lshlrev_b64 v[4:5], 12, v[4:5]
	ds_read_b128 v[0:3], v0
	v_lshl_add_u64 v[4:5], s[26:27], 0, v[4:5]
	v_lshl_add_u64 v[4:5], v[4:5], 0, v[12:13]
	v_lshl_add_u64 v[14:15], v[4:5], 0, v[128:129]
	v_add_u32_e32 v4, 0x340, v149
	v_ashrrev_i32_e32 v16, 3, v4
	v_mad_u64_u32 v[4:5], s[10:11], v16, s13, v[10:11]
	v_ashrrev_i32_e32 v17, 31, v16
	ds_read_b128 v[4:7], v4
	s_waitcnt lgkmcnt(1)
	global_store_dwordx4 v[14:15], v[0:3], off
	s_nop 1
	v_lshl_add_u64 v[0:1], v[8:9], 0, v[16:17]
	v_lshlrev_b64 v[0:1], 12, v[0:1]
	v_lshl_add_u64 v[0:1], s[26:27], 0, v[0:1]
	v_lshl_add_u64 v[0:1], v[0:1], 0, v[12:13]
	v_lshl_add_u64 v[0:1], v[0:1], 0, v[128:129]
	s_waitcnt lgkmcnt(0)
	global_store_dwordx4 v[0:1], v[4:7], off
	v_add_u32_e32 v0, 0x380, v149
	s_nop 0
	v_ashrrev_i32_e32 v4, 3, v0
	v_ashrrev_i32_e32 v5, 31, v4
	v_mad_u64_u32 v[0:1], s[10:11], v4, s13, v[10:11]
	v_lshl_add_u64 v[4:5], v[8:9], 0, v[4:5]
	v_lshlrev_b64 v[4:5], 12, v[4:5]
	v_lshl_add_u64 v[4:5], s[26:27], 0, v[4:5]
	v_lshl_add_u64 v[4:5], v[4:5], 0, v[12:13]
	v_lshl_add_u64 v[14:15], v[4:5], 0, v[128:129]
	v_add_u32_e32 v4, 0x3c0, v149
	v_ashrrev_i32_e32 v16, 3, v4
	ds_read_b128 v[0:3], v0
	v_mad_u64_u32 v[4:5], s[10:11], v16, s13, v[10:11]
	v_readlane_b32 s10, v254, 28
	s_add_i32 s34, s34, s10
	s_ashr_i32 s10, s34, 31
	v_ashrrev_i32_e32 v17, 31, v16
	s_lshr_b32 s10, s10, 27
	ds_read_b128 v[4:7], v4
	s_waitcnt lgkmcnt(1)
	global_store_dwordx4 v[14:15], v[0:3], off
	s_add_i32 s10, s34, s10
	s_ashr_i32 s10, s10, 5
	v_lshl_add_u64 v[0:1], v[8:9], 0, v[16:17]
	v_lshlrev_b64 v[0:1], 12, v[0:1]
	v_lshl_add_u64 v[0:1], s[26:27], 0, v[0:1]
	s_lshl_b32 s10, s10, 3
	v_readlane_b32 s11, v254, 24
	v_lshl_add_u64 v[0:1], v[0:1], 0, v[12:13]
	s_or_b32 s11, s10, s11
	v_lshl_add_u64 v[0:1], v[0:1], 0, v[128:129]
	s_cmp_gt_i32 s11, 31
	s_waitcnt lgkmcnt(0)
	global_store_dwordx4 v[0:1], v[4:7], off
	s_waitcnt vmcnt(63) expcnt(7) lgkmcnt(15)
	s_barrier
	s_cbranch_scc0 .LBB0_722
